# GEMM main loops: removed the redundant s_setprio 0 / s_setprio 1 toggle in the middle of each 32-MFMA segment (priority window unchanged)
# baseline (speedup 1.0000x reference)
; #define PG8_STAGE(bufoff, gbase, voff) do { _Pragma("unroll") for (int _i = 0; _i < 2; ++_i) \
;         __builtin_amdgcn_global_load_lds((const unsigned*)((const char*)(gbase) + (voff)[_i]), (LAS unsigned*)(lds + (bufoff) + ldsw + _i * 8192), 16, 0, 0); } while (0)
; #define PG8_LDA(dst, b, h) do { _Pragma("unroll") for (int m = 0; m < 4; ++m) _Pragma("unroll") for (int k = 0; k < 2; ++k) dst[m][k] = *(const LAS bf16x8*)(lds + PG8_SA(b, h) + aoff + m * 2048 + k * 1024); } while (0)
; #define PG8_LDB(dst, b, h) do { _Pragma("unroll") for (int n = 0; n < 2; ++n) _Pragma("unroll") for (int k = 0; k < 2; ++k) dst[n][k] = *(const LAS bf16x8*)(lds + PG8_SB(b, h) + boff + n * 2048 + k * 1024); } while (0)
; #define PG8_MMA(ai, bj, At, Bt) do { __builtin_amdgcn_s_setprio(1); _Pragma("unroll") for (int m = 0; m < 4; ++m) _Pragma("unroll") for (int n = 0; n < 2; ++n) _Pragma("unroll") for (int k = 0; k < 2; ++k) \
;         acc[ai][bj][m][n] = __builtin_amdgcn_mfma_f32_16x16x32_bf16(Bt[n][k], At[m][k], acc[ai][bj][m][n], 0, 0, 0); __builtin_amdgcn_s_setprio(0); } while (0)
; #define PG8_WAIT_V(n) asm volatile("s_waitcnt vmcnt(" #n ")" ::: "memory")
; #define PG8_WAIT_L(n) asm volatile("s_waitcnt lgkmcnt(" #n ")" ::: "memory")
; #define PG8_BAR __builtin_amdgcn_s_barrier()
; #define PG8_SCHED __builtin_amdgcn_sched_barrier(0)
; template <class Epi>
; __device__ __forceinline__ void gemm_phase(LAS unsigned char* lds, const Gemm g, const StaticOrder& S, const Epi& E) {
;     ...
;             const bool last = (t == nt - 2);
;             const char* a1 = cA + (size_t)(t + 1) * kstep;
;             const char* a2 = last ? nA : cA + (size_t)(t + 2) * kstep; const char* b2 = last ? nB : cB + (size_t)(t + 2) * kstep;
;             const char* a3 = a2 + kstep; const char* b3 = b2 + kstep;
;             PG8_LDB(B0, 0, 0); PG8_LDB(B1, 0, 1); PG8_SCHED; PG8_LDA(At, 0, 0); PG8_STAGE(PG8_SA(1, 1), a1 + hstepA, voffA);
;             PG8_WAIT_V(8); PG8_WAIT_L(0); PG8_BAR; PG8_MMA(0, 0, At, B0); PG8_MMA(0, 1, At, B1); PG8_BAR; PG8_SCHED;
;             PG8_LDA(At, 0, 1); PG8_STAGE(PG8_SB(0, 0), b2, voffB); PG8_STAGE(PG8_SB(0, 1), b2 + hstepB, voffB); PG8_STAGE(PG8_SA(0, 0), a2, voffA);
;             PG8_WAIT_V(8); PG8_WAIT_L(0); PG8_BAR; PG8_MMA(1, 0, At, B0); PG8_MMA(1, 1, At, B1); PG8_BAR; PG8_SCHED;
.LBB0_268:
	ds_read_b128 v[72:75], v171
	ds_read_b128 v[76:79], v171 offset:1024
	ds_read_b128 v[80:83], v171 offset:2048
	ds_read_b128 v[84:87], v171 offset:3072
	ds_read_b128 v[172:175], v181
	ds_read_b128 v[182:185], v181 offset:1024
	ds_read_b128 v[186:189], v181 offset:2048
	ds_read_b128 v[198:201], v181 offset:3072
	s_add_u32 s20, s40, 0xfffc0080
	s_addc_u32 s21, s41, -1
	s_cmp_eq_u32 s79, 12
	s_cselect_b32 s55, s17, s21
	s_cselect_b32 s54, s35, s20
	s_cselect_b32 s53, s23, s78
	s_cselect_b32 s52, s46, s47
	v_lshl_add_u64 v[166:167], s[40:41], 0, v[156:157]
	s_add_i32 m0, s58, 0xc000
	ds_read_b128 v[202:205], v193
	ds_read_b128 v[206:209], v193 offset:1024
	ds_read_b128 v[210:213], v193 offset:2048
	ds_read_b128 v[214:217], v193 offset:3072
	ds_read_b128 v[218:221], v193 offset:4096
	ds_read_b128 v[222:225], v193 offset:5120
	ds_read_b128 v[226:229], v193 offset:6144
	ds_read_b128 v[230:233], v193 offset:7168
	global_load_lds_dwordx4 v[166:167], off
	v_lshl_add_u64 v[166:167], s[40:41], 0, v[158:159]
	s_add_i32 m0, s58, 0xe000
	s_nop 0
	global_load_lds_dwordx4 v[166:167], off
	s_waitcnt vmcnt(8)
	s_waitcnt lgkmcnt(0)
	s_barrier
	s_setprio 1
	s_waitcnt lgkmcnt(0)
	v_mfma_f32_16x16x32_bf16 v[140:143], v[72:75], v[202:205], v[140:143]
	v_mfma_f32_16x16x32_bf16 v[136:139], v[80:83], v[202:205], v[136:139]
	v_mfma_f32_16x16x32_bf16 v[124:127], v[72:75], v[210:213], v[124:127]
	v_mfma_f32_16x16x32_bf16 v[120:123], v[80:83], v[210:213], v[120:123]
	v_mfma_f32_16x16x32_bf16 v[108:111], v[72:75], v[218:221], v[108:111]
	v_mfma_f32_16x16x32_bf16 v[104:107], v[80:83], v[218:221], v[104:107]
	v_mfma_f32_16x16x32_bf16 v[92:95], v[72:75], v[226:229], v[92:95]
	v_mfma_f32_16x16x32_bf16 v[88:91], v[80:83], v[226:229], v[88:91]
	v_mfma_f32_16x16x32_bf16 v[140:143], v[76:79], v[206:209], v[140:143]
	v_mfma_f32_16x16x32_bf16 v[136:139], v[84:87], v[206:209], v[136:139]
	v_mfma_f32_16x16x32_bf16 v[124:127], v[76:79], v[214:217], v[124:127]
	v_mfma_f32_16x16x32_bf16 v[120:123], v[84:87], v[214:217], v[120:123]
	v_mfma_f32_16x16x32_bf16 v[108:111], v[76:79], v[222:225], v[108:111]
	v_mfma_f32_16x16x32_bf16 v[104:107], v[84:87], v[222:225], v[104:107]
	v_mfma_f32_16x16x32_bf16 v[92:95], v[76:79], v[230:233], v[92:95]
	v_mfma_f32_16x16x32_bf16 v[88:91], v[84:87], v[230:233], v[88:91]
	v_mfma_f32_16x16x32_bf16 v[132:135], v[172:175], v[202:205], v[132:135]
	v_mfma_f32_16x16x32_bf16 v[128:131], v[186:189], v[202:205], v[128:131]
	v_mfma_f32_16x16x32_bf16 v[116:119], v[172:175], v[210:213], v[116:119]
	v_mfma_f32_16x16x32_bf16 v[112:115], v[186:189], v[210:213], v[112:115]
	v_mfma_f32_16x16x32_bf16 v[100:103], v[172:175], v[218:221], v[100:103]
	v_mfma_f32_16x16x32_bf16 v[96:99], v[186:189], v[218:221], v[96:99]
	v_mfma_f32_16x16x32_bf16 v[68:71], v[172:175], v[226:229], v[68:71]
	v_mfma_f32_16x16x32_bf16 v[64:67], v[186:189], v[226:229], v[64:67]
	v_mfma_f32_16x16x32_bf16 v[132:135], v[182:185], v[206:209], v[132:135]
	v_mfma_f32_16x16x32_bf16 v[128:131], v[198:201], v[206:209], v[128:131]
	v_mfma_f32_16x16x32_bf16 v[116:119], v[182:185], v[214:217], v[116:119]
	v_mfma_f32_16x16x32_bf16 v[112:115], v[198:201], v[214:217], v[112:115]
	v_mfma_f32_16x16x32_bf16 v[100:103], v[182:185], v[222:225], v[100:103]
	v_mfma_f32_16x16x32_bf16 v[96:99], v[198:201], v[222:225], v[96:99]
	v_mfma_f32_16x16x32_bf16 v[68:71], v[182:185], v[230:233], v[68:71]
	v_mfma_f32_16x16x32_bf16 v[64:67], v[198:201], v[230:233], v[64:67]
	s_setprio 0
	s_barrier
	s_add_i32 s20, s72, s25
	v_lshl_add_u64 v[166:167], s[52:53], 0, v[148:149]
	s_mov_b32 m0, s20
	ds_read_b128 v[202:205], v193 offset:16384
	ds_read_b128 v[206:209], v193 offset:17408
	ds_read_b128 v[210:213], v193 offset:18432
	ds_read_b128 v[214:217], v193 offset:19456
	ds_read_b128 v[218:221], v193 offset:20480
	ds_read_b128 v[222:225], v193 offset:21504
	ds_read_b128 v[226:229], v193 offset:22528
	ds_read_b128 v[230:233], v193 offset:23552
	global_load_lds_dwordx4 v[166:167], off
	s_add_i32 m0, s20, 0x2000
	s_add_u32 s20, s52, 0x40000
	v_lshl_add_u64 v[190:191], s[52:53], 0, v[144:145]
	s_addc_u32 s21, s53, 0
	s_add_i32 s28, s73, s25
	global_load_lds_dwordx4 v[190:191], off
	v_lshl_add_u64 v[194:195], s[20:21], 0, v[148:149]
	s_mov_b32 m0, s28
	v_lshl_add_u64 v[234:235], s[54:55], 0, v[146:147]
	global_load_lds_dwordx4 v[194:195], off
	v_lshl_add_u64 v[194:195], s[20:21], 0, v[144:145]
	s_add_i32 m0, s28, 0x2000
	s_nop 0
	global_load_lds_dwordx4 v[194:195], off
	v_lshl_add_u64 v[194:195], s[54:55], 0, v[150:151]
	s_mov_b32 m0, s58
	s_nop 0
	global_load_lds_dwordx4 v[194:195], off
	s_mov_b32 m0, s59
	s_nop 0
	global_load_lds_dwordx4 v[234:235], off
	s_waitcnt vmcnt(8)
	s_waitcnt lgkmcnt(0)
	s_barrier
; #define PG8_STAGE(bufoff, gbase, voff) do { _Pragma("unroll") for (int _i = 0; _i < 2; ++_i) \
;         __builtin_amdgcn_global_load_lds((const unsigned*)((const char*)(gbase) + (voff)[_i]), (LAS unsigned*)(lds + (bufoff) + ldsw + _i * 8192), 16, 0, 0); } while (0)
; #define PG8_LDA(dst, b, h) do { _Pragma("unroll") for (int m = 0; m < 4; ++m) _Pragma("unroll") for (int k = 0; k < 2; ++k) dst[m][k] = *(const LAS bf16x8*)(lds + PG8_SA(b, h) + aoff + m * 2048 + k * 1024); } while (0)
; #define PG8_LDB(dst, b, h) do { _Pragma("unroll") for (int n = 0; n < 2; ++n) _Pragma("unroll") for (int k = 0; k < 2; ++k) dst[n][k] = *(const LAS bf16x8*)(lds + PG8_SB(b, h) + boff + n * 2048 + k * 1024); } while (0)
; #define PG8_MMA(ai, bj, At, Bt) do { __builtin_amdgcn_s_setprio(1); _Pragma("unroll") for (int m = 0; m < 4; ++m) _Pragma("unroll") for (int n = 0; n < 2; ++n) _Pragma("unroll") for (int k = 0; k < 2; ++k) \
;         acc[ai][bj][m][n] = __builtin_amdgcn_mfma_f32_16x16x32_bf16(Bt[n][k], At[m][k], acc[ai][bj][m][n], 0, 0, 0); __builtin_amdgcn_s_setprio(0); } while (0)
; #define PG8_WAIT_V(n) asm volatile("s_waitcnt vmcnt(" #n ")" ::: "memory")
; #define PG8_WAIT_L(n) asm volatile("s_waitcnt lgkmcnt(" #n ")" ::: "memory")
; #define PG8_BAR __builtin_amdgcn_s_barrier()
; #define PG8_SCHED __builtin_amdgcn_sched_barrier(0)
; template <class Epi>
; __device__ __forceinline__ void gemm_phase(LAS unsigned char* lds, const Gemm g, const StaticOrder& S, const Epi& E) {
;     ...
;             PG8_WAIT_V(8); PG8_WAIT_L(0); PG8_BAR; PG8_MMA(1, 0, At, B0); PG8_MMA(1, 1, At, B1); PG8_BAR; PG8_SCHED;
;             PG8_LDB(B0, 1, 0); PG8_LDB(B1, 1, 1); PG8_SCHED; PG8_LDA(At, 1, 0); PG8_STAGE(PG8_SA(0, 1), a2 + hstepA, voffA);
;             PG8_WAIT_V(8); PG8_WAIT_L(0); PG8_BAR; PG8_MMA(0, 0, At, B0); PG8_MMA(0, 1, At, B1); PG8_BAR; PG8_SCHED;
	s_setprio 1
	s_waitcnt lgkmcnt(0)
	v_mfma_f32_16x16x32_bf16 v[60:63], v[72:75], v[202:205], v[60:63]
	v_mfma_f32_16x16x32_bf16 v[56:59], v[80:83], v[202:205], v[56:59]
	v_mfma_f32_16x16x32_bf16 v[44:47], v[72:75], v[210:213], v[44:47]
	v_mfma_f32_16x16x32_bf16 v[40:43], v[80:83], v[210:213], v[40:43]
	v_mfma_f32_16x16x32_bf16 v[28:31], v[72:75], v[218:221], v[28:31]
	v_mfma_f32_16x16x32_bf16 v[24:27], v[80:83], v[218:221], v[24:27]
	v_mfma_f32_16x16x32_bf16 v[12:15], v[72:75], v[226:229], v[12:15]
	v_mfma_f32_16x16x32_bf16 v[8:11], v[80:83], v[226:229], v[8:11]
	v_mfma_f32_16x16x32_bf16 v[60:63], v[76:79], v[206:209], v[60:63]
	v_mfma_f32_16x16x32_bf16 v[56:59], v[84:87], v[206:209], v[56:59]
	v_mfma_f32_16x16x32_bf16 v[44:47], v[76:79], v[214:217], v[44:47]
	v_mfma_f32_16x16x32_bf16 v[40:43], v[84:87], v[214:217], v[40:43]
	v_mfma_f32_16x16x32_bf16 v[28:31], v[76:79], v[222:225], v[28:31]
	v_mfma_f32_16x16x32_bf16 v[24:27], v[84:87], v[222:225], v[24:27]
	v_mfma_f32_16x16x32_bf16 v[12:15], v[76:79], v[230:233], v[12:15]
	v_mfma_f32_16x16x32_bf16 v[8:11], v[84:87], v[230:233], v[8:11]
	v_mfma_f32_16x16x32_bf16 v[52:55], v[172:175], v[202:205], v[52:55]
	v_mfma_f32_16x16x32_bf16 v[48:51], v[186:189], v[202:205], v[48:51]
	v_mfma_f32_16x16x32_bf16 v[36:39], v[172:175], v[210:213], v[36:39]
	v_mfma_f32_16x16x32_bf16 v[32:35], v[186:189], v[210:213], v[32:35]
	v_mfma_f32_16x16x32_bf16 v[20:23], v[172:175], v[218:221], v[20:23]
	v_mfma_f32_16x16x32_bf16 v[16:19], v[186:189], v[218:221], v[16:19]
	v_mfma_f32_16x16x32_bf16 v[4:7], v[172:175], v[226:229], v[4:7]
	v_mfma_f32_16x16x32_bf16 v[0:3], v[186:189], v[226:229], v[0:3]
	v_mfma_f32_16x16x32_bf16 v[52:55], v[182:185], v[206:209], v[52:55]
	v_mfma_f32_16x16x32_bf16 v[48:51], v[198:201], v[206:209], v[48:51]
	v_mfma_f32_16x16x32_bf16 v[36:39], v[182:185], v[214:217], v[36:39]
	v_mfma_f32_16x16x32_bf16 v[32:35], v[198:201], v[214:217], v[32:35]
	v_mfma_f32_16x16x32_bf16 v[20:23], v[182:185], v[222:225], v[20:23]
	v_mfma_f32_16x16x32_bf16 v[16:19], v[198:201], v[222:225], v[16:19]
	v_mfma_f32_16x16x32_bf16 v[4:7], v[182:185], v[230:233], v[4:7]
	v_mfma_f32_16x16x32_bf16 v[0:3], v[198:201], v[230:233], v[0:3]
	s_setprio 0
	s_barrier
	s_add_i32 s28, 0, 0x18000
	s_add_i32 s29, 0, 0x1c000
	v_add_u32_e32 v84, s28, v169
	v_add_u32_e32 v152, s29, v169
	ds_read_b128 v[72:75], v84
	ds_read_b128 v[76:79], v84 offset:1024
	ds_read_b128 v[80:83], v84 offset:2048
	ds_read_b128 v[84:87], v84 offset:3072
	ds_read_b128 v[172:175], v152
	ds_read_b128 v[182:185], v152 offset:1024
	ds_read_b128 v[186:189], v152 offset:2048
	ds_read_b128 v[198:201], v152 offset:3072
	s_add_u32 s20, s54, 0x40000
	s_addc_u32 s21, s55, 0
	s_mov_b32 m0, s60
	v_lshl_add_u64 v[240:241], s[20:21], 0, v[150:151]
	ds_read_b128 v[202:205], v193 offset:32768
	ds_read_b128 v[206:209], v193 offset:33792
	ds_read_b128 v[210:213], v193 offset:34816
	ds_read_b128 v[214:217], v193 offset:35840
	ds_read_b128 v[218:221], v193 offset:36864
	ds_read_b128 v[222:225], v193 offset:37888
	ds_read_b128 v[226:229], v193 offset:38912
	ds_read_b128 v[230:233], v193 offset:39936
	global_load_lds_dwordx4 v[240:241], off
	v_lshl_add_u64 v[240:241], s[20:21], 0, v[146:147]
	s_mov_b32 m0, s61
	s_nop 0
	global_load_lds_dwordx4 v[240:241], off
	s_waitcnt vmcnt(8)
	s_waitcnt lgkmcnt(0)
	s_barrier
	s_setprio 1
	s_waitcnt lgkmcnt(0)
	v_mfma_f32_16x16x32_bf16 v[140:143], v[72:75], v[202:205], v[140:143]
	v_mfma_f32_16x16x32_bf16 v[136:139], v[80:83], v[202:205], v[136:139]
	v_mfma_f32_16x16x32_bf16 v[124:127], v[72:75], v[210:213], v[124:127]
	v_mfma_f32_16x16x32_bf16 v[120:123], v[80:83], v[210:213], v[120:123]
	v_mfma_f32_16x16x32_bf16 v[108:111], v[72:75], v[218:221], v[108:111]
	v_mfma_f32_16x16x32_bf16 v[104:107], v[80:83], v[218:221], v[104:107]
	v_mfma_f32_16x16x32_bf16 v[92:95], v[72:75], v[226:229], v[92:95]
	v_mfma_f32_16x16x32_bf16 v[88:91], v[80:83], v[226:229], v[88:91]
	v_mfma_f32_16x16x32_bf16 v[140:143], v[76:79], v[206:209], v[140:143]
	v_mfma_f32_16x16x32_bf16 v[136:139], v[84:87], v[206:209], v[136:139]
	v_mfma_f32_16x16x32_bf16 v[124:127], v[76:79], v[214:217], v[124:127]
	v_mfma_f32_16x16x32_bf16 v[120:123], v[84:87], v[214:217], v[120:123]
	v_mfma_f32_16x16x32_bf16 v[108:111], v[76:79], v[222:225], v[108:111]
	v_mfma_f32_16x16x32_bf16 v[104:107], v[84:87], v[222:225], v[104:107]
	v_mfma_f32_16x16x32_bf16 v[92:95], v[76:79], v[230:233], v[92:95]
	v_mfma_f32_16x16x32_bf16 v[88:91], v[84:87], v[230:233], v[88:91]
	v_mfma_f32_16x16x32_bf16 v[132:135], v[172:175], v[202:205], v[132:135]
	v_mfma_f32_16x16x32_bf16 v[128:131], v[186:189], v[202:205], v[128:131]
	v_mfma_f32_16x16x32_bf16 v[116:119], v[172:175], v[210:213], v[116:119]
	v_mfma_f32_16x16x32_bf16 v[112:115], v[186:189], v[210:213], v[112:115]
	v_mfma_f32_16x16x32_bf16 v[100:103], v[172:175], v[218:221], v[100:103]
	v_mfma_f32_16x16x32_bf16 v[96:99], v[186:189], v[218:221], v[96:99]
	v_mfma_f32_16x16x32_bf16 v[68:71], v[172:175], v[226:229], v[68:71]
	v_mfma_f32_16x16x32_bf16 v[64:67], v[186:189], v[226:229], v[64:67]
	v_mfma_f32_16x16x32_bf16 v[132:135], v[182:185], v[206:209], v[132:135]
	v_mfma_f32_16x16x32_bf16 v[128:131], v[198:201], v[206:209], v[128:131]
	v_mfma_f32_16x16x32_bf16 v[116:119], v[182:185], v[214:217], v[116:119]
	v_mfma_f32_16x16x32_bf16 v[112:115], v[198:201], v[214:217], v[112:115]
	v_mfma_f32_16x16x32_bf16 v[100:103], v[182:185], v[222:225], v[100:103]
	v_mfma_f32_16x16x32_bf16 v[96:99], v[198:201], v[222:225], v[96:99]
	v_mfma_f32_16x16x32_bf16 v[68:71], v[182:185], v[230:233], v[68:71]
	v_mfma_f32_16x16x32_bf16 v[64:67], v[198:201], v[230:233], v[64:67]
	s_setprio 0
	s_barrier
; #define PG8_STAGE(bufoff, gbase, voff) do { _Pragma("unroll") for (int _i = 0; _i < 2; ++_i) \
;         __builtin_amdgcn_global_load_lds((const unsigned*)((const char*)(gbase) + (voff)[_i]), (LAS unsigned*)(lds + (bufoff) + ldsw + _i * 8192), 16, 0, 0); } while (0)
; #define PG8_LDA(dst, b, h) do { _Pragma("unroll") for (int m = 0; m < 4; ++m) _Pragma("unroll") for (int k = 0; k < 2; ++k) dst[m][k] = *(const LAS bf16x8*)(lds + PG8_SA(b, h) + aoff + m * 2048 + k * 1024); } while (0)
; #define PG8_MMA(ai, bj, At, Bt) do { __builtin_amdgcn_s_setprio(1); _Pragma("unroll") for (int m = 0; m < 4; ++m) _Pragma("unroll") for (int n = 0; n < 2; ++n) _Pragma("unroll") for (int k = 0; k < 2; ++k) \
;         acc[ai][bj][m][n] = __builtin_amdgcn_mfma_f32_16x16x32_bf16(Bt[n][k], At[m][k], acc[ai][bj][m][n], 0, 0, 0); __builtin_amdgcn_s_setprio(0); } while (0)
; #define PG8_WAIT_V(n) asm volatile("s_waitcnt vmcnt(" #n ")" ::: "memory")
; #define PG8_WAIT_L(n) asm volatile("s_waitcnt lgkmcnt(" #n ")" ::: "memory")
; #define PG8_BAR __builtin_amdgcn_s_barrier()
; #define PG8_SCHED __builtin_amdgcn_sched_barrier(0)
; template <class Epi>
; __device__ __forceinline__ void gemm_phase(LAS unsigned char* lds, const Gemm g, const StaticOrder& S, const Epi& E) {
;     ...
;             PG8_LDA(At, 1, 1); PG8_STAGE(PG8_SB(1, 0), b3, voffB); PG8_STAGE(PG8_SB(1, 1), b3 + hstepB, voffB); PG8_STAGE(PG8_SA(1, 0), a3, voffA);
;             PG8_WAIT_V(8); PG8_WAIT_L(0); PG8_BAR; PG8_MMA(1, 0, At, B0); PG8_MMA(1, 1, At, B1); PG8_BAR; PG8_SCHED;
;         }
;         if (wr == 0) PG8_BAR;
	s_add_i32 s20, s28, s25
	v_lshl_add_u64 v[166:167], v[166:167], 0, s[10:11]
	s_mov_b32 m0, s20
	ds_read_b128 v[202:205], v193 offset:49152
	ds_read_b128 v[206:209], v193 offset:50176
	ds_read_b128 v[210:213], v193 offset:51200
	ds_read_b128 v[214:217], v193 offset:52224
	ds_read_b128 v[218:221], v193 offset:53248
	ds_read_b128 v[222:225], v193 offset:54272
	ds_read_b128 v[226:229], v193 offset:55296
	ds_read_b128 v[230:233], v193 offset:56320
	global_load_lds_dwordx4 v[166:167], off
	s_add_i32 m0, s20, 0x2000
	s_add_u32 s20, s52, 0x40080
	v_lshl_add_u64 v[166:167], v[190:191], 0, s[10:11]
	s_addc_u32 s21, s53, 0
	s_add_i32 s28, s29, s25
	global_load_lds_dwordx4 v[166:167], off
	v_lshl_add_u64 v[166:167], s[20:21], 0, v[148:149]
	s_mov_b32 m0, s28
	s_nop 0
	global_load_lds_dwordx4 v[166:167], off
	v_lshl_add_u64 v[166:167], s[20:21], 0, v[144:145]
	s_add_i32 m0, s28, 0x2000
	s_nop 0
	global_load_lds_dwordx4 v[166:167], off
	v_lshl_add_u64 v[166:167], v[194:195], 0, s[10:11]
	s_mov_b32 m0, s68
	s_nop 0
	global_load_lds_dwordx4 v[166:167], off
	v_lshl_add_u64 v[166:167], v[234:235], 0, s[10:11]
	s_mov_b32 m0, s69
	s_nop 0
	global_load_lds_dwordx4 v[166:167], off
	s_waitcnt vmcnt(8)
	s_waitcnt lgkmcnt(0)
	s_barrier
	s_setprio 1
	s_waitcnt lgkmcnt(0)
	v_mfma_f32_16x16x32_bf16 v[60:63], v[72:75], v[202:205], v[60:63]
	v_mfma_f32_16x16x32_bf16 v[56:59], v[80:83], v[202:205], v[56:59]
	v_mfma_f32_16x16x32_bf16 v[44:47], v[72:75], v[210:213], v[44:47]
	v_mfma_f32_16x16x32_bf16 v[40:43], v[80:83], v[210:213], v[40:43]
	v_mfma_f32_16x16x32_bf16 v[28:31], v[72:75], v[218:221], v[28:31]
	v_mfma_f32_16x16x32_bf16 v[24:27], v[80:83], v[218:221], v[24:27]
	v_mfma_f32_16x16x32_bf16 v[12:15], v[72:75], v[226:229], v[12:15]
	v_mfma_f32_16x16x32_bf16 v[8:11], v[80:83], v[226:229], v[8:11]
	v_mfma_f32_16x16x32_bf16 v[60:63], v[76:79], v[206:209], v[60:63]
	v_mfma_f32_16x16x32_bf16 v[56:59], v[84:87], v[206:209], v[56:59]
	v_mfma_f32_16x16x32_bf16 v[44:47], v[76:79], v[214:217], v[44:47]
	v_mfma_f32_16x16x32_bf16 v[40:43], v[84:87], v[214:217], v[40:43]
	v_mfma_f32_16x16x32_bf16 v[28:31], v[76:79], v[222:225], v[28:31]
	v_mfma_f32_16x16x32_bf16 v[24:27], v[84:87], v[222:225], v[24:27]
	v_mfma_f32_16x16x32_bf16 v[12:15], v[76:79], v[230:233], v[12:15]
	v_mfma_f32_16x16x32_bf16 v[8:11], v[84:87], v[230:233], v[8:11]
	v_mfma_f32_16x16x32_bf16 v[52:55], v[172:175], v[202:205], v[52:55]
	v_mfma_f32_16x16x32_bf16 v[48:51], v[186:189], v[202:205], v[48:51]
	v_mfma_f32_16x16x32_bf16 v[36:39], v[172:175], v[210:213], v[36:39]
	v_mfma_f32_16x16x32_bf16 v[32:35], v[186:189], v[210:213], v[32:35]
	v_mfma_f32_16x16x32_bf16 v[20:23], v[172:175], v[218:221], v[20:23]
	v_mfma_f32_16x16x32_bf16 v[16:19], v[186:189], v[218:221], v[16:19]
	v_mfma_f32_16x16x32_bf16 v[4:7], v[172:175], v[226:229], v[4:7]
	v_mfma_f32_16x16x32_bf16 v[0:3], v[186:189], v[226:229], v[0:3]
	v_mfma_f32_16x16x32_bf16 v[52:55], v[182:185], v[206:209], v[52:55]
	v_mfma_f32_16x16x32_bf16 v[48:51], v[198:201], v[206:209], v[48:51]
	v_mfma_f32_16x16x32_bf16 v[36:39], v[182:185], v[214:217], v[36:39]
	v_mfma_f32_16x16x32_bf16 v[32:35], v[198:201], v[214:217], v[32:35]
	v_mfma_f32_16x16x32_bf16 v[20:23], v[182:185], v[222:225], v[20:23]
	v_mfma_f32_16x16x32_bf16 v[16:19], v[198:201], v[222:225], v[16:19]
	v_mfma_f32_16x16x32_bf16 v[4:7], v[182:185], v[230:233], v[4:7]
	v_mfma_f32_16x16x32_bf16 v[0:3], v[198:201], v[230:233], v[0:3]
	s_setprio 0
	s_barrier
	s_add_i32 s79, s79, 2
	s_add_u32 s40, s40, 0x100
	s_addc_u32 s41, s41, 0
	s_add_u32 s47, s47, 0x100
	s_addc_u32 s78, s78, 0
	s_cmp_gt_u32 s79, 13
	s_cbranch_scc0 .LBB0_268
	s_and_b64 vcc, exec, s[12:13]
	s_cbranch_vccz .LBB0_271
	s_barrier

; #define PG8_STAGE(bufoff, gbase, voff) do { _Pragma("unroll") for (int _i = 0; _i < 2; ++_i) \
;         __builtin_amdgcn_global_load_lds((const unsigned*)((const char*)(gbase) + (voff)[_i]), (LAS unsigned*)(lds + (bufoff) + ldsw + _i * 8192), 16, 0, 0); } while (0)
; #define PG8_LDA(dst, b, h) do { _Pragma("unroll") for (int m = 0; m < 4; ++m) _Pragma("unroll") for (int k = 0; k < 2; ++k) dst[m][k] = *(const LAS bf16x8*)(lds + PG8_SA(b, h) + aoff + m * 2048 + k * 1024); } while (0)
; #define PG8_LDB(dst, b, h) do { _Pragma("unroll") for (int n = 0; n < 2; ++n) _Pragma("unroll") for (int k = 0; k < 2; ++k) dst[n][k] = *(const LAS bf16x8*)(lds + PG8_SB(b, h) + boff + n * 2048 + k * 1024); } while (0)
; #define PG8_MMA(ai, bj, At, Bt) do { __builtin_amdgcn_s_setprio(1); _Pragma("unroll") for (int m = 0; m < 4; ++m) _Pragma("unroll") for (int n = 0; n < 2; ++n) _Pragma("unroll") for (int k = 0; k < 2; ++k) \
;         acc[ai][bj][m][n] = __builtin_amdgcn_mfma_f32_16x16x32_bf16(Bt[n][k], At[m][k], acc[ai][bj][m][n], 0, 0, 0); __builtin_amdgcn_s_setprio(0); } while (0)
; #define PG8_WAIT_V(n) asm volatile("s_waitcnt vmcnt(" #n ")" ::: "memory")
; #define PG8_WAIT_L(n) asm volatile("s_waitcnt lgkmcnt(" #n ")" ::: "memory")
; #define PG8_BAR __builtin_amdgcn_s_barrier()
; #define PG8_SCHED __builtin_amdgcn_sched_barrier(0)
; template <class Epi>
; __device__ __forceinline__ void gemm_phase(LAS unsigned char* lds, const Gemm g, const StaticOrder& S, const Epi& E) {
;     ...
;             const bool last = (t == nt - 2);
;             const char* a1 = cA + (size_t)(t + 1) * kstep;
;             const char* a2 = last ? nA : cA + (size_t)(t + 2) * kstep; const char* b2 = last ? nB : cB + (size_t)(t + 2) * kstep;
;             const char* a3 = a2 + kstep; const char* b3 = b2 + kstep;
;             PG8_LDB(B0, 0, 0); PG8_LDB(B1, 0, 1); PG8_SCHED; PG8_LDA(At, 0, 0); PG8_STAGE(PG8_SA(1, 1), a1 + hstepA, voffA);
;             PG8_WAIT_V(8); PG8_WAIT_L(0); PG8_BAR; PG8_MMA(0, 0, At, B0); PG8_MMA(0, 1, At, B1); PG8_BAR; PG8_SCHED;
;             PG8_LDA(At, 0, 1); PG8_STAGE(PG8_SB(0, 0), b2, voffB); PG8_STAGE(PG8_SB(0, 1), b2 + hstepB, voffB); PG8_STAGE(PG8_SA(0, 0), a2, voffA);
;             PG8_WAIT_V(8); PG8_WAIT_L(0); PG8_BAR; PG8_MMA(1, 0, At, B0); PG8_MMA(1, 1, At, B1); PG8_BAR; PG8_SCHED;
.LBB0_360:
	ds_read_b128 v[60:63], v237
	ds_read_b128 v[64:67], v237 offset:1024
	ds_read_b128 v[68:71], v237 offset:2048
	ds_read_b128 v[72:75], v237 offset:3072
	ds_read_b128 v[76:79], v245
	ds_read_b128 v[80:83], v245 offset:1024
	ds_read_b128 v[88:91], v245 offset:2048
	ds_read_b128 v[92:95], v245 offset:3072
	s_add_u32 s60, s58, 0x100
	s_addc_u32 s61, s59, 0
	s_cmp_eq_u32 vcc_lo, 40
	s_cselect_b32 s71, s1, s61
	s_cselect_b32 s70, s0, s60
	s_cselect_b32 s69, s57, s47
	s_cselect_b32 s68, s56, s46
	v_lshl_add_u64 v[218:219], s[58:59], 0, v[172:173]
	s_add_i32 m0, s67, 0xc000
	ds_read_b128 v[186:189], v246
	ds_read_b128 v[190:193], v246 offset:1024
	ds_read_b128 v[194:197], v246 offset:2048
	ds_read_b128 v[198:201], v246 offset:3072
	ds_read_b128 v[202:205], v246 offset:4096
	ds_read_b128 v[206:209], v246 offset:5120
	ds_read_b128 v[210:213], v246 offset:6144
	ds_read_b128 v[214:217], v246 offset:7168
	global_load_lds_dwordx4 v[218:219], off
	v_lshl_add_u64 v[218:219], s[58:59], 0, v[174:175]
	s_add_i32 m0, s67, 0xe000
	s_nop 0
	global_load_lds_dwordx4 v[218:219], off
	s_waitcnt vmcnt(8)
	s_waitcnt lgkmcnt(0)
	s_barrier
	s_setprio 1
	s_waitcnt lgkmcnt(0)
	v_mfma_f32_16x16x32_bf16 v[156:159], v[60:63], v[186:189], v[156:159]
	v_mfma_f32_16x16x32_bf16 v[152:155], v[68:71], v[186:189], v[152:155]
	v_mfma_f32_16x16x32_bf16 v[140:143], v[60:63], v[194:197], v[140:143]
	v_mfma_f32_16x16x32_bf16 v[136:139], v[68:71], v[194:197], v[136:139]
	v_mfma_f32_16x16x32_bf16 v[124:127], v[60:63], v[202:205], v[124:127]
	v_mfma_f32_16x16x32_bf16 v[120:123], v[68:71], v[202:205], v[120:123]
	v_mfma_f32_16x16x32_bf16 v[108:111], v[60:63], v[210:213], v[108:111]
	v_mfma_f32_16x16x32_bf16 v[104:107], v[68:71], v[210:213], v[104:107]
	v_mfma_f32_16x16x32_bf16 v[156:159], v[64:67], v[190:193], v[156:159]
	v_mfma_f32_16x16x32_bf16 v[152:155], v[72:75], v[190:193], v[152:155]
	v_mfma_f32_16x16x32_bf16 v[140:143], v[64:67], v[198:201], v[140:143]
	v_mfma_f32_16x16x32_bf16 v[136:139], v[72:75], v[198:201], v[136:139]
	v_mfma_f32_16x16x32_bf16 v[124:127], v[64:67], v[206:209], v[124:127]
	v_mfma_f32_16x16x32_bf16 v[120:123], v[72:75], v[206:209], v[120:123]
	v_mfma_f32_16x16x32_bf16 v[108:111], v[64:67], v[214:217], v[108:111]
	v_mfma_f32_16x16x32_bf16 v[104:107], v[72:75], v[214:217], v[104:107]
	v_mfma_f32_16x16x32_bf16 v[148:151], v[76:79], v[186:189], v[148:151]
	v_mfma_f32_16x16x32_bf16 v[144:147], v[88:91], v[186:189], v[144:147]
	v_mfma_f32_16x16x32_bf16 v[132:135], v[76:79], v[194:197], v[132:135]
	v_mfma_f32_16x16x32_bf16 v[128:131], v[88:91], v[194:197], v[128:131]
	v_mfma_f32_16x16x32_bf16 v[116:119], v[76:79], v[202:205], v[116:119]
	v_mfma_f32_16x16x32_bf16 v[112:115], v[88:91], v[202:205], v[112:115]
	v_mfma_f32_16x16x32_bf16 v[100:103], v[76:79], v[210:213], v[100:103]
	v_mfma_f32_16x16x32_bf16 v[96:99], v[88:91], v[210:213], v[96:99]
	v_mfma_f32_16x16x32_bf16 v[148:151], v[80:83], v[190:193], v[148:151]
	v_mfma_f32_16x16x32_bf16 v[144:147], v[92:95], v[190:193], v[144:147]
	v_mfma_f32_16x16x32_bf16 v[132:135], v[80:83], v[198:201], v[132:135]
	v_mfma_f32_16x16x32_bf16 v[128:131], v[92:95], v[198:201], v[128:131]
	v_mfma_f32_16x16x32_bf16 v[116:119], v[80:83], v[206:209], v[116:119]
	v_mfma_f32_16x16x32_bf16 v[112:115], v[92:95], v[206:209], v[112:115]
	v_mfma_f32_16x16x32_bf16 v[100:103], v[80:83], v[214:217], v[100:103]
	v_mfma_f32_16x16x32_bf16 v[96:99], v[92:95], v[214:217], v[96:99]
	s_setprio 0
	s_barrier
	s_add_i32 s20, s83, s25
	v_lshl_add_u64 v[218:219], s[68:69], 0, v[162:163]
	s_mov_b32 m0, s20
	ds_read_b128 v[186:189], v246 offset:16384
	ds_read_b128 v[190:193], v246 offset:17408
	ds_read_b128 v[194:197], v246 offset:18432
	ds_read_b128 v[198:201], v246 offset:19456
	ds_read_b128 v[202:205], v246 offset:20480
	ds_read_b128 v[206:209], v246 offset:21504
	ds_read_b128 v[210:213], v246 offset:22528
	ds_read_b128 v[214:217], v246 offset:23552
	global_load_lds_dwordx4 v[218:219], off
	s_add_i32 m0, s20, 0x2000
	s_add_u32 s20, s68, 0xb0000
	v_lshl_add_u64 v[220:221], s[68:69], 0, v[164:165]
	s_addc_u32 s21, s69, 0
	s_add_i32 s28, s88, s25
	global_load_lds_dwordx4 v[220:221], off
	v_lshl_add_u64 v[222:223], s[20:21], 0, v[162:163]
	s_mov_b32 m0, s28
	v_lshl_add_u64 v[224:225], s[70:71], 0, v[164:165]
	global_load_lds_dwordx4 v[222:223], off
	v_lshl_add_u64 v[222:223], s[20:21], 0, v[164:165]
	s_add_i32 m0, s28, 0x2000
	s_nop 0
	global_load_lds_dwordx4 v[222:223], off
	v_lshl_add_u64 v[222:223], s[70:71], 0, v[162:163]
	s_mov_b32 m0, s67
	s_nop 0
	global_load_lds_dwordx4 v[222:223], off
	s_mov_b32 m0, s72
	s_nop 0
	global_load_lds_dwordx4 v[224:225], off
	s_waitcnt vmcnt(8)
	s_waitcnt lgkmcnt(0)
	s_barrier
; #define PG8_STAGE(bufoff, gbase, voff) do { _Pragma("unroll") for (int _i = 0; _i < 2; ++_i) \
;         __builtin_amdgcn_global_load_lds((const unsigned*)((const char*)(gbase) + (voff)[_i]), (LAS unsigned*)(lds + (bufoff) + ldsw + _i * 8192), 16, 0, 0); } while (0)
; #define PG8_LDA(dst, b, h) do { _Pragma("unroll") for (int m = 0; m < 4; ++m) _Pragma("unroll") for (int k = 0; k < 2; ++k) dst[m][k] = *(const LAS bf16x8*)(lds + PG8_SA(b, h) + aoff + m * 2048 + k * 1024); } while (0)
; #define PG8_LDB(dst, b, h) do { _Pragma("unroll") for (int n = 0; n < 2; ++n) _Pragma("unroll") for (int k = 0; k < 2; ++k) dst[n][k] = *(const LAS bf16x8*)(lds + PG8_SB(b, h) + boff + n * 2048 + k * 1024); } while (0)
; #define PG8_MMA(ai, bj, At, Bt) do { __builtin_amdgcn_s_setprio(1); _Pragma("unroll") for (int m = 0; m < 4; ++m) _Pragma("unroll") for (int n = 0; n < 2; ++n) _Pragma("unroll") for (int k = 0; k < 2; ++k) \
;         acc[ai][bj][m][n] = __builtin_amdgcn_mfma_f32_16x16x32_bf16(Bt[n][k], At[m][k], acc[ai][bj][m][n], 0, 0, 0); __builtin_amdgcn_s_setprio(0); } while (0)
; #define PG8_WAIT_V(n) asm volatile("s_waitcnt vmcnt(" #n ")" ::: "memory")
; #define PG8_WAIT_L(n) asm volatile("s_waitcnt lgkmcnt(" #n ")" ::: "memory")
; #define PG8_BAR __builtin_amdgcn_s_barrier()
; #define PG8_SCHED __builtin_amdgcn_sched_barrier(0)
; template <class Epi>
; __device__ __forceinline__ void gemm_phase(LAS unsigned char* lds, const Gemm g, const StaticOrder& S, const Epi& E) {
;     ...
;             PG8_WAIT_V(8); PG8_WAIT_L(0); PG8_BAR; PG8_MMA(1, 0, At, B0); PG8_MMA(1, 1, At, B1); PG8_BAR; PG8_SCHED;
;             PG8_LDB(B0, 1, 0); PG8_LDB(B1, 1, 1); PG8_SCHED; PG8_LDA(At, 1, 0); PG8_STAGE(PG8_SA(0, 1), a2 + hstepA, voffA);
;             PG8_WAIT_V(8); PG8_WAIT_L(0); PG8_BAR; PG8_MMA(0, 0, At, B0); PG8_MMA(0, 1, At, B1); PG8_BAR; PG8_SCHED;
	s_setprio 1
	s_waitcnt lgkmcnt(0)
	v_mfma_f32_16x16x32_bf16 v[84:87], v[60:63], v[186:189], v[84:87]
	v_mfma_f32_16x16x32_bf16 v[56:59], v[68:71], v[186:189], v[56:59]
	v_mfma_f32_16x16x32_bf16 v[44:47], v[60:63], v[194:197], v[44:47]
	v_mfma_f32_16x16x32_bf16 v[40:43], v[68:71], v[194:197], v[40:43]
	v_mfma_f32_16x16x32_bf16 v[28:31], v[60:63], v[202:205], v[28:31]
	v_mfma_f32_16x16x32_bf16 v[24:27], v[68:71], v[202:205], v[24:27]
	v_mfma_f32_16x16x32_bf16 v[12:15], v[60:63], v[210:213], v[12:15]
	v_mfma_f32_16x16x32_bf16 v[8:11], v[68:71], v[210:213], v[8:11]
	v_mfma_f32_16x16x32_bf16 v[84:87], v[64:67], v[190:193], v[84:87]
	v_mfma_f32_16x16x32_bf16 v[56:59], v[72:75], v[190:193], v[56:59]
	v_mfma_f32_16x16x32_bf16 v[44:47], v[64:67], v[198:201], v[44:47]
	v_mfma_f32_16x16x32_bf16 v[40:43], v[72:75], v[198:201], v[40:43]
	v_mfma_f32_16x16x32_bf16 v[28:31], v[64:67], v[206:209], v[28:31]
	v_mfma_f32_16x16x32_bf16 v[24:27], v[72:75], v[206:209], v[24:27]
	v_mfma_f32_16x16x32_bf16 v[12:15], v[64:67], v[214:217], v[12:15]
	v_mfma_f32_16x16x32_bf16 v[8:11], v[72:75], v[214:217], v[8:11]
	v_mfma_f32_16x16x32_bf16 v[52:55], v[76:79], v[186:189], v[52:55]
	v_mfma_f32_16x16x32_bf16 v[48:51], v[88:91], v[186:189], v[48:51]
	v_mfma_f32_16x16x32_bf16 v[36:39], v[76:79], v[194:197], v[36:39]
	v_mfma_f32_16x16x32_bf16 v[32:35], v[88:91], v[194:197], v[32:35]
	v_mfma_f32_16x16x32_bf16 v[20:23], v[76:79], v[202:205], v[20:23]
	v_mfma_f32_16x16x32_bf16 v[16:19], v[88:91], v[202:205], v[16:19]
	v_mfma_f32_16x16x32_bf16 v[4:7], v[76:79], v[210:213], v[4:7]
	v_mfma_f32_16x16x32_bf16 v[0:3], v[88:91], v[210:213], v[0:3]
	v_mfma_f32_16x16x32_bf16 v[52:55], v[80:83], v[190:193], v[52:55]
	v_mfma_f32_16x16x32_bf16 v[48:51], v[92:95], v[190:193], v[48:51]
	v_mfma_f32_16x16x32_bf16 v[36:39], v[80:83], v[198:201], v[36:39]
	v_mfma_f32_16x16x32_bf16 v[32:35], v[92:95], v[198:201], v[32:35]
	v_mfma_f32_16x16x32_bf16 v[20:23], v[80:83], v[206:209], v[20:23]
	v_mfma_f32_16x16x32_bf16 v[16:19], v[92:95], v[206:209], v[16:19]
	v_mfma_f32_16x16x32_bf16 v[4:7], v[80:83], v[214:217], v[4:7]
	v_mfma_f32_16x16x32_bf16 v[0:3], v[92:95], v[214:217], v[0:3]
	s_setprio 0
	s_barrier
	s_add_i32 s28, 0, 0x18000
	s_add_i32 s29, 0, 0x1c000
	v_add_u32_e32 v72, s28, v171
	v_add_u32_e32 v92, s29, v171
	ds_read_b128 v[60:63], v72
	ds_read_b128 v[64:67], v72 offset:1024
	ds_read_b128 v[68:71], v72 offset:2048
	ds_read_b128 v[72:75], v72 offset:3072
	ds_read_b128 v[76:79], v92
	ds_read_b128 v[80:83], v92 offset:1024
	ds_read_b128 v[88:91], v92 offset:2048
	ds_read_b128 v[92:95], v92 offset:3072
	s_add_u32 s20, s70, 0xb0000
	s_addc_u32 s21, s71, 0
	s_mov_b32 m0, s73
	v_lshl_add_u64 v[226:227], s[20:21], 0, v[162:163]
	ds_read_b128 v[186:189], v246 offset:32768
	ds_read_b128 v[190:193], v246 offset:33792
	ds_read_b128 v[194:197], v246 offset:34816
	ds_read_b128 v[198:201], v246 offset:35840
	ds_read_b128 v[202:205], v246 offset:36864
	ds_read_b128 v[206:209], v246 offset:37888
	ds_read_b128 v[210:213], v246 offset:38912
	ds_read_b128 v[214:217], v246 offset:39936
	global_load_lds_dwordx4 v[226:227], off
	v_lshl_add_u64 v[226:227], s[20:21], 0, v[164:165]
	s_mov_b32 m0, s76
	s_nop 0
	global_load_lds_dwordx4 v[226:227], off
	s_waitcnt vmcnt(8)
	s_waitcnt lgkmcnt(0)
	s_barrier
	s_setprio 1
	s_waitcnt lgkmcnt(0)
	v_mfma_f32_16x16x32_bf16 v[156:159], v[60:63], v[186:189], v[156:159]
	v_mfma_f32_16x16x32_bf16 v[152:155], v[68:71], v[186:189], v[152:155]
	v_mfma_f32_16x16x32_bf16 v[140:143], v[60:63], v[194:197], v[140:143]
	v_mfma_f32_16x16x32_bf16 v[136:139], v[68:71], v[194:197], v[136:139]
	v_mfma_f32_16x16x32_bf16 v[124:127], v[60:63], v[202:205], v[124:127]
	v_mfma_f32_16x16x32_bf16 v[120:123], v[68:71], v[202:205], v[120:123]
	v_mfma_f32_16x16x32_bf16 v[108:111], v[60:63], v[210:213], v[108:111]
	v_mfma_f32_16x16x32_bf16 v[104:107], v[68:71], v[210:213], v[104:107]
	v_mfma_f32_16x16x32_bf16 v[156:159], v[64:67], v[190:193], v[156:159]
	v_mfma_f32_16x16x32_bf16 v[152:155], v[72:75], v[190:193], v[152:155]
	v_mfma_f32_16x16x32_bf16 v[140:143], v[64:67], v[198:201], v[140:143]
	v_mfma_f32_16x16x32_bf16 v[136:139], v[72:75], v[198:201], v[136:139]
	v_mfma_f32_16x16x32_bf16 v[124:127], v[64:67], v[206:209], v[124:127]
	v_mfma_f32_16x16x32_bf16 v[120:123], v[72:75], v[206:209], v[120:123]
	v_mfma_f32_16x16x32_bf16 v[108:111], v[64:67], v[214:217], v[108:111]
	v_mfma_f32_16x16x32_bf16 v[104:107], v[72:75], v[214:217], v[104:107]
	v_mfma_f32_16x16x32_bf16 v[148:151], v[76:79], v[186:189], v[148:151]
	v_mfma_f32_16x16x32_bf16 v[144:147], v[88:91], v[186:189], v[144:147]
	v_mfma_f32_16x16x32_bf16 v[132:135], v[76:79], v[194:197], v[132:135]
	v_mfma_f32_16x16x32_bf16 v[128:131], v[88:91], v[194:197], v[128:131]
	v_mfma_f32_16x16x32_bf16 v[116:119], v[76:79], v[202:205], v[116:119]
	v_mfma_f32_16x16x32_bf16 v[112:115], v[88:91], v[202:205], v[112:115]
	v_mfma_f32_16x16x32_bf16 v[100:103], v[76:79], v[210:213], v[100:103]
	v_mfma_f32_16x16x32_bf16 v[96:99], v[88:91], v[210:213], v[96:99]
	v_mfma_f32_16x16x32_bf16 v[148:151], v[80:83], v[190:193], v[148:151]
	v_mfma_f32_16x16x32_bf16 v[144:147], v[92:95], v[190:193], v[144:147]
	v_mfma_f32_16x16x32_bf16 v[132:135], v[80:83], v[198:201], v[132:135]
	v_mfma_f32_16x16x32_bf16 v[128:131], v[92:95], v[198:201], v[128:131]
	v_mfma_f32_16x16x32_bf16 v[116:119], v[80:83], v[206:209], v[116:119]
	v_mfma_f32_16x16x32_bf16 v[112:115], v[92:95], v[206:209], v[112:115]
	v_mfma_f32_16x16x32_bf16 v[100:103], v[80:83], v[214:217], v[100:103]
	v_mfma_f32_16x16x32_bf16 v[96:99], v[92:95], v[214:217], v[96:99]
	s_setprio 0
	s_barrier
; #define PG8_STAGE(bufoff, gbase, voff) do { _Pragma("unroll") for (int _i = 0; _i < 2; ++_i) \
;         __builtin_amdgcn_global_load_lds((const unsigned*)((const char*)(gbase) + (voff)[_i]), (LAS unsigned*)(lds + (bufoff) + ldsw + _i * 8192), 16, 0, 0); } while (0)
; #define PG8_LDA(dst, b, h) do { _Pragma("unroll") for (int m = 0; m < 4; ++m) _Pragma("unroll") for (int k = 0; k < 2; ++k) dst[m][k] = *(const LAS bf16x8*)(lds + PG8_SA(b, h) + aoff + m * 2048 + k * 1024); } while (0)
; #define PG8_MMA(ai, bj, At, Bt) do { __builtin_amdgcn_s_setprio(1); _Pragma("unroll") for (int m = 0; m < 4; ++m) _Pragma("unroll") for (int n = 0; n < 2; ++n) _Pragma("unroll") for (int k = 0; k < 2; ++k) \
;         acc[ai][bj][m][n] = __builtin_amdgcn_mfma_f32_16x16x32_bf16(Bt[n][k], At[m][k], acc[ai][bj][m][n], 0, 0, 0); __builtin_amdgcn_s_setprio(0); } while (0)
; #define PG8_WAIT_V(n) asm volatile("s_waitcnt vmcnt(" #n ")" ::: "memory")
; #define PG8_WAIT_L(n) asm volatile("s_waitcnt lgkmcnt(" #n ")" ::: "memory")
; #define PG8_BAR __builtin_amdgcn_s_barrier()
; #define PG8_SCHED __builtin_amdgcn_sched_barrier(0)
; template <class Epi>
; __device__ __forceinline__ void gemm_phase(LAS unsigned char* lds, const Gemm g, const StaticOrder& S, const Epi& E) {
;     ...
;             PG8_LDA(At, 1, 1); PG8_STAGE(PG8_SB(1, 0), b3, voffB); PG8_STAGE(PG8_SB(1, 1), b3 + hstepB, voffB); PG8_STAGE(PG8_SA(1, 0), a3, voffA);
;             PG8_WAIT_V(8); PG8_WAIT_L(0); PG8_BAR; PG8_MMA(1, 0, At, B0); PG8_MMA(1, 1, At, B1); PG8_BAR; PG8_SCHED;
;         }
;         if (wr == 0) PG8_BAR;
	s_add_i32 s20, s28, s25
	v_lshl_add_u64 v[218:219], v[218:219], 0, s[52:53]
	s_mov_b32 m0, s20
	ds_read_b128 v[186:189], v246 offset:49152
	ds_read_b128 v[190:193], v246 offset:50176
	ds_read_b128 v[194:197], v246 offset:51200
	ds_read_b128 v[198:201], v246 offset:52224
	ds_read_b128 v[202:205], v246 offset:53248
	ds_read_b128 v[206:209], v246 offset:54272
	ds_read_b128 v[210:213], v246 offset:55296
	ds_read_b128 v[214:217], v246 offset:56320
	global_load_lds_dwordx4 v[218:219], off
	s_add_i32 m0, s20, 0x2000
	s_add_u32 s20, s68, 0xb0080
	v_lshl_add_u64 v[218:219], v[220:221], 0, s[52:53]
	s_addc_u32 s21, s69, 0
	s_add_i32 s28, s29, s25
	global_load_lds_dwordx4 v[218:219], off
	v_lshl_add_u64 v[218:219], s[20:21], 0, v[162:163]
	s_mov_b32 m0, s28
	s_nop 0
	global_load_lds_dwordx4 v[218:219], off
	v_lshl_add_u64 v[218:219], s[20:21], 0, v[164:165]
	s_add_i32 m0, s28, 0x2000
	s_nop 0
	global_load_lds_dwordx4 v[218:219], off
	v_lshl_add_u64 v[218:219], v[222:223], 0, s[52:53]
	s_mov_b32 m0, s78
	s_nop 0
	global_load_lds_dwordx4 v[218:219], off
	v_lshl_add_u64 v[218:219], v[224:225], 0, s[52:53]
	s_mov_b32 m0, s79
	s_nop 0
	global_load_lds_dwordx4 v[218:219], off
	s_waitcnt vmcnt(8)
	s_waitcnt lgkmcnt(0)
	s_barrier
	s_setprio 1
	s_waitcnt lgkmcnt(0)
	v_mfma_f32_16x16x32_bf16 v[84:87], v[60:63], v[186:189], v[84:87]
	v_mfma_f32_16x16x32_bf16 v[56:59], v[68:71], v[186:189], v[56:59]
	v_mfma_f32_16x16x32_bf16 v[44:47], v[60:63], v[194:197], v[44:47]
	v_mfma_f32_16x16x32_bf16 v[40:43], v[68:71], v[194:197], v[40:43]
	v_mfma_f32_16x16x32_bf16 v[28:31], v[60:63], v[202:205], v[28:31]
	v_mfma_f32_16x16x32_bf16 v[24:27], v[68:71], v[202:205], v[24:27]
	v_mfma_f32_16x16x32_bf16 v[12:15], v[60:63], v[210:213], v[12:15]
	v_mfma_f32_16x16x32_bf16 v[8:11], v[68:71], v[210:213], v[8:11]
	v_mfma_f32_16x16x32_bf16 v[84:87], v[64:67], v[190:193], v[84:87]
	v_mfma_f32_16x16x32_bf16 v[56:59], v[72:75], v[190:193], v[56:59]
	v_mfma_f32_16x16x32_bf16 v[44:47], v[64:67], v[198:201], v[44:47]
	v_mfma_f32_16x16x32_bf16 v[40:43], v[72:75], v[198:201], v[40:43]
	v_mfma_f32_16x16x32_bf16 v[28:31], v[64:67], v[206:209], v[28:31]
	v_mfma_f32_16x16x32_bf16 v[24:27], v[72:75], v[206:209], v[24:27]
	v_mfma_f32_16x16x32_bf16 v[12:15], v[64:67], v[214:217], v[12:15]
	v_mfma_f32_16x16x32_bf16 v[8:11], v[72:75], v[214:217], v[8:11]
	v_mfma_f32_16x16x32_bf16 v[52:55], v[76:79], v[186:189], v[52:55]
	v_mfma_f32_16x16x32_bf16 v[48:51], v[88:91], v[186:189], v[48:51]
	v_mfma_f32_16x16x32_bf16 v[36:39], v[76:79], v[194:197], v[36:39]
	v_mfma_f32_16x16x32_bf16 v[32:35], v[88:91], v[194:197], v[32:35]
	v_mfma_f32_16x16x32_bf16 v[20:23], v[76:79], v[202:205], v[20:23]
	v_mfma_f32_16x16x32_bf16 v[16:19], v[88:91], v[202:205], v[16:19]
	v_mfma_f32_16x16x32_bf16 v[4:7], v[76:79], v[210:213], v[4:7]
	v_mfma_f32_16x16x32_bf16 v[0:3], v[88:91], v[210:213], v[0:3]
	v_mfma_f32_16x16x32_bf16 v[52:55], v[80:83], v[190:193], v[52:55]
	v_mfma_f32_16x16x32_bf16 v[48:51], v[92:95], v[190:193], v[48:51]
	v_mfma_f32_16x16x32_bf16 v[36:39], v[80:83], v[198:201], v[36:39]
	v_mfma_f32_16x16x32_bf16 v[32:35], v[92:95], v[198:201], v[32:35]
	v_mfma_f32_16x16x32_bf16 v[20:23], v[80:83], v[206:209], v[20:23]
	v_mfma_f32_16x16x32_bf16 v[16:19], v[92:95], v[206:209], v[16:19]
	v_mfma_f32_16x16x32_bf16 v[4:7], v[80:83], v[214:217], v[4:7]
	v_mfma_f32_16x16x32_bf16 v[0:3], v[92:95], v[214:217], v[0:3]
	s_setprio 0
	s_barrier
	s_add_i32 vcc_lo, vcc_lo, 2
	s_add_u32 s46, s46, 0x100
	s_addc_u32 s47, s47, 0
	s_cmp_gt_u32 vcc_lo, 41
	s_mov_b64 s[58:59], s[60:61]
	s_cbranch_scc0 .LBB0_360
	s_and_b64 vcc, exec, s[54:55]
	s_cbranch_vccz .LBB0_363
	s_barrier

; #define PG8_STAGE(bufoff, gbase, voff) do { _Pragma("unroll") for (int _i = 0; _i < 2; ++_i) \
;         __builtin_amdgcn_global_load_lds((const unsigned*)((const char*)(gbase) + (voff)[_i]), (LAS unsigned*)(lds + (bufoff) + ldsw + _i * 8192), 16, 0, 0); } while (0)
; #define PG8_LDA(dst, b, h) do { _Pragma("unroll") for (int m = 0; m < 4; ++m) _Pragma("unroll") for (int k = 0; k < 2; ++k) dst[m][k] = *(const LAS bf16x8*)(lds + PG8_SA(b, h) + aoff + m * 2048 + k * 1024); } while (0)
; #define PG8_LDB(dst, b, h) do { _Pragma("unroll") for (int n = 0; n < 2; ++n) _Pragma("unroll") for (int k = 0; k < 2; ++k) dst[n][k] = *(const LAS bf16x8*)(lds + PG8_SB(b, h) + boff + n * 2048 + k * 1024); } while (0)
; #define PG8_MMA(ai, bj, At, Bt) do { __builtin_amdgcn_s_setprio(1); _Pragma("unroll") for (int m = 0; m < 4; ++m) _Pragma("unroll") for (int n = 0; n < 2; ++n) _Pragma("unroll") for (int k = 0; k < 2; ++k) \
;         acc[ai][bj][m][n] = __builtin_amdgcn_mfma_f32_16x16x32_bf16(Bt[n][k], At[m][k], acc[ai][bj][m][n], 0, 0, 0); __builtin_amdgcn_s_setprio(0); } while (0)
; #define PG8_WAIT_V(n) asm volatile("s_waitcnt vmcnt(" #n ")" ::: "memory")
; #define PG8_WAIT_L(n) asm volatile("s_waitcnt lgkmcnt(" #n ")" ::: "memory")
; #define PG8_BAR __builtin_amdgcn_s_barrier()
; #define PG8_SCHED __builtin_amdgcn_sched_barrier(0)
; template <class Epi>
; __device__ __forceinline__ void gemm_phase(LAS unsigned char* lds, const Gemm g, const StaticOrder& S, const Epi& E) {
;     ...
;             const bool last = (t == nt - 2);
;             const char* a1 = cA + (size_t)(t + 1) * kstep;
;             const char* a2 = last ? nA : cA + (size_t)(t + 2) * kstep; const char* b2 = last ? nB : cB + (size_t)(t + 2) * kstep;
;             const char* a3 = a2 + kstep; const char* b3 = b2 + kstep;
;             PG8_LDB(B0, 0, 0); PG8_LDB(B1, 0, 1); PG8_SCHED; PG8_LDA(At, 0, 0); PG8_STAGE(PG8_SA(1, 1), a1 + hstepA, voffA);
;             PG8_WAIT_V(8); PG8_WAIT_L(0); PG8_BAR; PG8_MMA(0, 0, At, B0); PG8_MMA(0, 1, At, B1); PG8_BAR; PG8_SCHED;
;             PG8_LDA(At, 0, 1); PG8_STAGE(PG8_SB(0, 0), b2, voffB); PG8_STAGE(PG8_SB(0, 1), b2 + hstepB, voffB); PG8_STAGE(PG8_SA(0, 0), a2, voffA);
;             PG8_WAIT_V(8); PG8_WAIT_L(0); PG8_BAR; PG8_MMA(1, 0, At, B0); PG8_MMA(1, 1, At, B1); PG8_BAR; PG8_SCHED;
.LBB0_452:
	ds_read_b128 v[128:131], v171
	ds_read_b128 v[132:135], v171 offset:1024
	ds_read_b128 v[136:139], v171 offset:2048
	ds_read_b128 v[140:143], v171 offset:3072
	ds_read_b128 v[172:175], v181
	ds_read_b128 v[182:185], v181 offset:1024
	ds_read_b128 v[186:189], v181 offset:2048
	ds_read_b128 v[194:197], v181 offset:3072
	s_add_u32 s20, s40, 0xfffc0080
	s_addc_u32 s21, s41, -1
	s_cmp_eq_u32 s82, 12
	s_cselect_b32 s55, s17, s21
	s_cselect_b32 s54, s35, s20
	s_cselect_b32 s53, s13, s81
	s_cselect_b32 s52, s46, s47
	v_lshl_add_u64 v[166:167], s[40:41], 0, v[156:157]
	s_add_i32 m0, s58, 0xc000
	ds_read_b128 v[198:201], v192
	ds_read_b128 v[202:205], v192 offset:1024
	ds_read_b128 v[206:209], v192 offset:2048
	ds_read_b128 v[210:213], v192 offset:3072
	ds_read_b128 v[214:217], v192 offset:4096
	ds_read_b128 v[218:221], v192 offset:5120
	ds_read_b128 v[222:225], v192 offset:6144
	ds_read_b128 v[226:229], v192 offset:7168
	global_load_lds_dwordx4 v[166:167], off
	v_lshl_add_u64 v[166:167], s[40:41], 0, v[158:159]
	s_add_i32 m0, s58, 0xe000
	s_nop 0
	global_load_lds_dwordx4 v[166:167], off
	s_waitcnt vmcnt(8)
	s_waitcnt lgkmcnt(0)
	s_barrier
	s_setprio 1
	s_waitcnt lgkmcnt(0)
	v_mfma_f32_16x16x32_bf16 v[124:127], v[128:131], v[198:201], v[124:127]
	v_mfma_f32_16x16x32_bf16 v[120:123], v[136:139], v[198:201], v[120:123]
	v_mfma_f32_16x16x32_bf16 v[108:111], v[128:131], v[206:209], v[108:111]
	v_mfma_f32_16x16x32_bf16 v[104:107], v[136:139], v[206:209], v[104:107]
	v_mfma_f32_16x16x32_bf16 v[100:103], v[128:131], v[214:217], v[100:103]
	v_mfma_f32_16x16x32_bf16 v[92:95], v[136:139], v[214:217], v[92:95]
	v_mfma_f32_16x16x32_bf16 v[84:87], v[128:131], v[222:225], v[84:87]
	v_mfma_f32_16x16x32_bf16 v[76:79], v[136:139], v[222:225], v[76:79]
	v_mfma_f32_16x16x32_bf16 v[124:127], v[132:135], v[202:205], v[124:127]
	v_mfma_f32_16x16x32_bf16 v[120:123], v[140:143], v[202:205], v[120:123]
	v_mfma_f32_16x16x32_bf16 v[108:111], v[132:135], v[210:213], v[108:111]
	v_mfma_f32_16x16x32_bf16 v[104:107], v[140:143], v[210:213], v[104:107]
	v_mfma_f32_16x16x32_bf16 v[100:103], v[132:135], v[218:221], v[100:103]
	v_mfma_f32_16x16x32_bf16 v[92:95], v[140:143], v[218:221], v[92:95]
	v_mfma_f32_16x16x32_bf16 v[84:87], v[132:135], v[226:229], v[84:87]
	v_mfma_f32_16x16x32_bf16 v[76:79], v[140:143], v[226:229], v[76:79]
	v_mfma_f32_16x16x32_bf16 v[116:119], v[172:175], v[198:201], v[116:119]
	v_mfma_f32_16x16x32_bf16 v[112:115], v[186:189], v[198:201], v[112:115]
	v_mfma_f32_16x16x32_bf16 v[96:99], v[172:175], v[206:209], v[96:99]
	v_mfma_f32_16x16x32_bf16 v[88:91], v[186:189], v[206:209], v[88:91]
	v_mfma_f32_16x16x32_bf16 v[80:83], v[172:175], v[214:217], v[80:83]
	v_mfma_f32_16x16x32_bf16 v[72:75], v[186:189], v[214:217], v[72:75]
	v_mfma_f32_16x16x32_bf16 v[68:71], v[172:175], v[222:225], v[68:71]
	v_mfma_f32_16x16x32_bf16 v[64:67], v[186:189], v[222:225], v[64:67]
	v_mfma_f32_16x16x32_bf16 v[116:119], v[182:185], v[202:205], v[116:119]
	v_mfma_f32_16x16x32_bf16 v[112:115], v[194:197], v[202:205], v[112:115]
	v_mfma_f32_16x16x32_bf16 v[96:99], v[182:185], v[210:213], v[96:99]
	v_mfma_f32_16x16x32_bf16 v[88:91], v[194:197], v[210:213], v[88:91]
	v_mfma_f32_16x16x32_bf16 v[80:83], v[182:185], v[218:221], v[80:83]
	v_mfma_f32_16x16x32_bf16 v[72:75], v[194:197], v[218:221], v[72:75]
	v_mfma_f32_16x16x32_bf16 v[68:71], v[182:185], v[226:229], v[68:71]
	v_mfma_f32_16x16x32_bf16 v[64:67], v[194:197], v[226:229], v[64:67]
	s_setprio 0
	s_barrier
	s_add_i32 s20, s73, s25
	v_lshl_add_u64 v[166:167], s[52:53], 0, v[148:149]
	s_mov_b32 m0, s20
	ds_read_b128 v[198:201], v192 offset:16384
	ds_read_b128 v[202:205], v192 offset:17408
	ds_read_b128 v[206:209], v192 offset:18432
	ds_read_b128 v[210:213], v192 offset:19456
	ds_read_b128 v[214:217], v192 offset:20480
	ds_read_b128 v[218:221], v192 offset:21504
	ds_read_b128 v[222:225], v192 offset:22528
	ds_read_b128 v[226:229], v192 offset:23552
	global_load_lds_dwordx4 v[166:167], off
	s_add_i32 m0, s20, 0x2000
	s_add_u32 s20, s52, 0x40000
	v_lshl_add_u64 v[190:191], s[52:53], 0, v[144:145]
	s_addc_u32 s21, s53, 0
	s_add_i32 s28, s76, s25
	global_load_lds_dwordx4 v[190:191], off
	v_lshl_add_u64 v[230:231], s[20:21], 0, v[148:149]
	s_mov_b32 m0, s28
	v_lshl_add_u64 v[232:233], s[54:55], 0, v[146:147]
	global_load_lds_dwordx4 v[230:231], off
	v_lshl_add_u64 v[230:231], s[20:21], 0, v[144:145]
	s_add_i32 m0, s28, 0x2000
	s_nop 0
	global_load_lds_dwordx4 v[230:231], off
	v_lshl_add_u64 v[230:231], s[54:55], 0, v[150:151]
	s_mov_b32 m0, s58
	s_nop 0
	global_load_lds_dwordx4 v[230:231], off
	s_mov_b32 m0, s59
	s_nop 0
	global_load_lds_dwordx4 v[232:233], off
	s_waitcnt vmcnt(8)
	s_waitcnt lgkmcnt(0)
	s_barrier
; #define PG8_STAGE(bufoff, gbase, voff) do { _Pragma("unroll") for (int _i = 0; _i < 2; ++_i) \
;         __builtin_amdgcn_global_load_lds((const unsigned*)((const char*)(gbase) + (voff)[_i]), (LAS unsigned*)(lds + (bufoff) + ldsw + _i * 8192), 16, 0, 0); } while (0)
; #define PG8_LDA(dst, b, h) do { _Pragma("unroll") for (int m = 0; m < 4; ++m) _Pragma("unroll") for (int k = 0; k < 2; ++k) dst[m][k] = *(const LAS bf16x8*)(lds + PG8_SA(b, h) + aoff + m * 2048 + k * 1024); } while (0)
; #define PG8_LDB(dst, b, h) do { _Pragma("unroll") for (int n = 0; n < 2; ++n) _Pragma("unroll") for (int k = 0; k < 2; ++k) dst[n][k] = *(const LAS bf16x8*)(lds + PG8_SB(b, h) + boff + n * 2048 + k * 1024); } while (0)
; #define PG8_MMA(ai, bj, At, Bt) do { __builtin_amdgcn_s_setprio(1); _Pragma("unroll") for (int m = 0; m < 4; ++m) _Pragma("unroll") for (int n = 0; n < 2; ++n) _Pragma("unroll") for (int k = 0; k < 2; ++k) \
;         acc[ai][bj][m][n] = __builtin_amdgcn_mfma_f32_16x16x32_bf16(Bt[n][k], At[m][k], acc[ai][bj][m][n], 0, 0, 0); __builtin_amdgcn_s_setprio(0); } while (0)
; #define PG8_WAIT_V(n) asm volatile("s_waitcnt vmcnt(" #n ")" ::: "memory")
; #define PG8_WAIT_L(n) asm volatile("s_waitcnt lgkmcnt(" #n ")" ::: "memory")
; #define PG8_BAR __builtin_amdgcn_s_barrier()
; #define PG8_SCHED __builtin_amdgcn_sched_barrier(0)
; template <class Epi>
; __device__ __forceinline__ void gemm_phase(LAS unsigned char* lds, const Gemm g, const StaticOrder& S, const Epi& E) {
;     ...
;             PG8_WAIT_V(8); PG8_WAIT_L(0); PG8_BAR; PG8_MMA(1, 0, At, B0); PG8_MMA(1, 1, At, B1); PG8_BAR; PG8_SCHED;
;             PG8_LDB(B0, 1, 0); PG8_LDB(B1, 1, 1); PG8_SCHED; PG8_LDA(At, 1, 0); PG8_STAGE(PG8_SA(0, 1), a2 + hstepA, voffA);
;             PG8_WAIT_V(8); PG8_WAIT_L(0); PG8_BAR; PG8_MMA(0, 0, At, B0); PG8_MMA(0, 1, At, B1); PG8_BAR; PG8_SCHED;
	s_setprio 1
	s_waitcnt lgkmcnt(0)
	v_mfma_f32_16x16x32_bf16 v[60:63], v[128:131], v[198:201], v[60:63]
	v_mfma_f32_16x16x32_bf16 v[56:59], v[136:139], v[198:201], v[56:59]
	v_mfma_f32_16x16x32_bf16 v[52:55], v[128:131], v[206:209], v[52:55]
	v_mfma_f32_16x16x32_bf16 v[44:47], v[136:139], v[206:209], v[44:47]
	v_mfma_f32_16x16x32_bf16 v[36:39], v[128:131], v[214:217], v[36:39]
	v_mfma_f32_16x16x32_bf16 v[28:31], v[136:139], v[214:217], v[28:31]
	v_mfma_f32_16x16x32_bf16 v[20:23], v[128:131], v[222:225], v[20:23]
	v_mfma_f32_16x16x32_bf16 v[12:15], v[136:139], v[222:225], v[12:15]
	v_mfma_f32_16x16x32_bf16 v[60:63], v[132:135], v[202:205], v[60:63]
	v_mfma_f32_16x16x32_bf16 v[56:59], v[140:143], v[202:205], v[56:59]
	v_mfma_f32_16x16x32_bf16 v[52:55], v[132:135], v[210:213], v[52:55]
	v_mfma_f32_16x16x32_bf16 v[44:47], v[140:143], v[210:213], v[44:47]
	v_mfma_f32_16x16x32_bf16 v[36:39], v[132:135], v[218:221], v[36:39]
	v_mfma_f32_16x16x32_bf16 v[28:31], v[140:143], v[218:221], v[28:31]
	v_mfma_f32_16x16x32_bf16 v[20:23], v[132:135], v[226:229], v[20:23]
	v_mfma_f32_16x16x32_bf16 v[12:15], v[140:143], v[226:229], v[12:15]
	v_mfma_f32_16x16x32_bf16 v[48:51], v[172:175], v[198:201], v[48:51]
	v_mfma_f32_16x16x32_bf16 v[40:43], v[186:189], v[198:201], v[40:43]
	v_mfma_f32_16x16x32_bf16 v[32:35], v[172:175], v[206:209], v[32:35]
	v_mfma_f32_16x16x32_bf16 v[24:27], v[186:189], v[206:209], v[24:27]
	v_mfma_f32_16x16x32_bf16 v[16:19], v[172:175], v[214:217], v[16:19]
	v_mfma_f32_16x16x32_bf16 v[8:11], v[186:189], v[214:217], v[8:11]
	v_mfma_f32_16x16x32_bf16 v[4:7], v[172:175], v[222:225], v[4:7]
	v_mfma_f32_16x16x32_bf16 v[0:3], v[186:189], v[222:225], v[0:3]
	v_mfma_f32_16x16x32_bf16 v[48:51], v[182:185], v[202:205], v[48:51]
	v_mfma_f32_16x16x32_bf16 v[40:43], v[194:197], v[202:205], v[40:43]
	v_mfma_f32_16x16x32_bf16 v[32:35], v[182:185], v[210:213], v[32:35]
	v_mfma_f32_16x16x32_bf16 v[24:27], v[194:197], v[210:213], v[24:27]
	v_mfma_f32_16x16x32_bf16 v[16:19], v[182:185], v[218:221], v[16:19]
	v_mfma_f32_16x16x32_bf16 v[8:11], v[194:197], v[218:221], v[8:11]
	v_mfma_f32_16x16x32_bf16 v[4:7], v[182:185], v[226:229], v[4:7]
	v_mfma_f32_16x16x32_bf16 v[0:3], v[194:197], v[226:229], v[0:3]
	s_setprio 0
	s_barrier
	s_add_i32 s28, 0, 0x18000
	s_add_i32 s29, 0, 0x1c000
	v_add_u32_e32 v140, s28, v169
	v_add_u32_e32 v152, s29, v169
	ds_read_b128 v[128:131], v140
	ds_read_b128 v[132:135], v140 offset:1024
	ds_read_b128 v[136:139], v140 offset:2048
	ds_read_b128 v[140:143], v140 offset:3072
	ds_read_b128 v[172:175], v152
	ds_read_b128 v[182:185], v152 offset:1024
	ds_read_b128 v[186:189], v152 offset:2048
	ds_read_b128 v[194:197], v152 offset:3072
	s_add_u32 s20, s54, 0x40000
	s_addc_u32 s21, s55, 0
	s_mov_b32 m0, s60
	v_lshl_add_u64 v[234:235], s[20:21], 0, v[150:151]
	ds_read_b128 v[198:201], v192 offset:32768
	ds_read_b128 v[202:205], v192 offset:33792
	ds_read_b128 v[206:209], v192 offset:34816
	ds_read_b128 v[210:213], v192 offset:35840
	ds_read_b128 v[214:217], v192 offset:36864
	ds_read_b128 v[218:221], v192 offset:37888
	ds_read_b128 v[222:225], v192 offset:38912
	ds_read_b128 v[226:229], v192 offset:39936
	global_load_lds_dwordx4 v[234:235], off
	v_lshl_add_u64 v[234:235], s[20:21], 0, v[146:147]
	s_mov_b32 m0, s61
	s_nop 0
	global_load_lds_dwordx4 v[234:235], off
	s_waitcnt vmcnt(8)
	s_waitcnt lgkmcnt(0)
	s_barrier
	s_setprio 1
	s_waitcnt lgkmcnt(0)
	v_mfma_f32_16x16x32_bf16 v[124:127], v[128:131], v[198:201], v[124:127]
	v_mfma_f32_16x16x32_bf16 v[120:123], v[136:139], v[198:201], v[120:123]
	v_mfma_f32_16x16x32_bf16 v[108:111], v[128:131], v[206:209], v[108:111]
	v_mfma_f32_16x16x32_bf16 v[104:107], v[136:139], v[206:209], v[104:107]
	v_mfma_f32_16x16x32_bf16 v[100:103], v[128:131], v[214:217], v[100:103]
	v_mfma_f32_16x16x32_bf16 v[92:95], v[136:139], v[214:217], v[92:95]
	v_mfma_f32_16x16x32_bf16 v[84:87], v[128:131], v[222:225], v[84:87]
	v_mfma_f32_16x16x32_bf16 v[76:79], v[136:139], v[222:225], v[76:79]
	v_mfma_f32_16x16x32_bf16 v[124:127], v[132:135], v[202:205], v[124:127]
	v_mfma_f32_16x16x32_bf16 v[120:123], v[140:143], v[202:205], v[120:123]
	v_mfma_f32_16x16x32_bf16 v[108:111], v[132:135], v[210:213], v[108:111]
	v_mfma_f32_16x16x32_bf16 v[104:107], v[140:143], v[210:213], v[104:107]
	v_mfma_f32_16x16x32_bf16 v[100:103], v[132:135], v[218:221], v[100:103]
	v_mfma_f32_16x16x32_bf16 v[92:95], v[140:143], v[218:221], v[92:95]
	v_mfma_f32_16x16x32_bf16 v[84:87], v[132:135], v[226:229], v[84:87]
	v_mfma_f32_16x16x32_bf16 v[76:79], v[140:143], v[226:229], v[76:79]
	v_mfma_f32_16x16x32_bf16 v[116:119], v[172:175], v[198:201], v[116:119]
	v_mfma_f32_16x16x32_bf16 v[112:115], v[186:189], v[198:201], v[112:115]
	v_mfma_f32_16x16x32_bf16 v[96:99], v[172:175], v[206:209], v[96:99]
	v_mfma_f32_16x16x32_bf16 v[88:91], v[186:189], v[206:209], v[88:91]
	v_mfma_f32_16x16x32_bf16 v[80:83], v[172:175], v[214:217], v[80:83]
	v_mfma_f32_16x16x32_bf16 v[72:75], v[186:189], v[214:217], v[72:75]
	v_mfma_f32_16x16x32_bf16 v[68:71], v[172:175], v[222:225], v[68:71]
	v_mfma_f32_16x16x32_bf16 v[64:67], v[186:189], v[222:225], v[64:67]
	v_mfma_f32_16x16x32_bf16 v[116:119], v[182:185], v[202:205], v[116:119]
	v_mfma_f32_16x16x32_bf16 v[112:115], v[194:197], v[202:205], v[112:115]
	v_mfma_f32_16x16x32_bf16 v[96:99], v[182:185], v[210:213], v[96:99]
	v_mfma_f32_16x16x32_bf16 v[88:91], v[194:197], v[210:213], v[88:91]
	v_mfma_f32_16x16x32_bf16 v[80:83], v[182:185], v[218:221], v[80:83]
	v_mfma_f32_16x16x32_bf16 v[72:75], v[194:197], v[218:221], v[72:75]
	v_mfma_f32_16x16x32_bf16 v[68:71], v[182:185], v[226:229], v[68:71]
	v_mfma_f32_16x16x32_bf16 v[64:67], v[194:197], v[226:229], v[64:67]
	s_setprio 0
	s_barrier
; #define PG8_STAGE(bufoff, gbase, voff) do { _Pragma("unroll") for (int _i = 0; _i < 2; ++_i) \
;         __builtin_amdgcn_global_load_lds((const unsigned*)((const char*)(gbase) + (voff)[_i]), (LAS unsigned*)(lds + (bufoff) + ldsw + _i * 8192), 16, 0, 0); } while (0)
; #define PG8_LDA(dst, b, h) do { _Pragma("unroll") for (int m = 0; m < 4; ++m) _Pragma("unroll") for (int k = 0; k < 2; ++k) dst[m][k] = *(const LAS bf16x8*)(lds + PG8_SA(b, h) + aoff + m * 2048 + k * 1024); } while (0)
; #define PG8_MMA(ai, bj, At, Bt) do { __builtin_amdgcn_s_setprio(1); _Pragma("unroll") for (int m = 0; m < 4; ++m) _Pragma("unroll") for (int n = 0; n < 2; ++n) _Pragma("unroll") for (int k = 0; k < 2; ++k) \
;         acc[ai][bj][m][n] = __builtin_amdgcn_mfma_f32_16x16x32_bf16(Bt[n][k], At[m][k], acc[ai][bj][m][n], 0, 0, 0); __builtin_amdgcn_s_setprio(0); } while (0)
; #define PG8_WAIT_V(n) asm volatile("s_waitcnt vmcnt(" #n ")" ::: "memory")
; #define PG8_WAIT_L(n) asm volatile("s_waitcnt lgkmcnt(" #n ")" ::: "memory")
; #define PG8_BAR __builtin_amdgcn_s_barrier()
; #define PG8_SCHED __builtin_amdgcn_sched_barrier(0)
; template <class Epi>
; __device__ __forceinline__ void gemm_phase(LAS unsigned char* lds, const Gemm g, const StaticOrder& S, const Epi& E) {
;     ...
;             PG8_LDA(At, 1, 1); PG8_STAGE(PG8_SB(1, 0), b3, voffB); PG8_STAGE(PG8_SB(1, 1), b3 + hstepB, voffB); PG8_STAGE(PG8_SA(1, 0), a3, voffA);
;             PG8_WAIT_V(8); PG8_WAIT_L(0); PG8_BAR; PG8_MMA(1, 0, At, B0); PG8_MMA(1, 1, At, B1); PG8_BAR; PG8_SCHED;
;         }
;         if (wr == 0) PG8_BAR;
	s_add_i32 s20, s28, s25
	v_lshl_add_u64 v[166:167], v[166:167], 0, s[8:9]
	s_mov_b32 m0, s20
	ds_read_b128 v[198:201], v192 offset:49152
	ds_read_b128 v[202:205], v192 offset:50176
	ds_read_b128 v[206:209], v192 offset:51200
	ds_read_b128 v[210:213], v192 offset:52224
	ds_read_b128 v[214:217], v192 offset:53248
	ds_read_b128 v[218:221], v192 offset:54272
	ds_read_b128 v[222:225], v192 offset:55296
	ds_read_b128 v[226:229], v192 offset:56320
	global_load_lds_dwordx4 v[166:167], off
	s_add_i32 m0, s20, 0x2000
	s_add_u32 s20, s52, 0x40080
	v_lshl_add_u64 v[166:167], v[190:191], 0, s[8:9]
	s_addc_u32 s21, s53, 0
	s_add_i32 s28, s29, s25
	global_load_lds_dwordx4 v[166:167], off
	v_lshl_add_u64 v[166:167], s[20:21], 0, v[148:149]
	s_mov_b32 m0, s28
	s_nop 0
	global_load_lds_dwordx4 v[166:167], off
	v_lshl_add_u64 v[166:167], s[20:21], 0, v[144:145]
	s_add_i32 m0, s28, 0x2000
	s_nop 0
	global_load_lds_dwordx4 v[166:167], off
	v_lshl_add_u64 v[166:167], v[230:231], 0, s[8:9]
	s_mov_b32 m0, s69
	s_nop 0
	global_load_lds_dwordx4 v[166:167], off
	v_lshl_add_u64 v[166:167], v[232:233], 0, s[8:9]
	s_mov_b32 m0, s70
	s_nop 0
	global_load_lds_dwordx4 v[166:167], off
	s_waitcnt vmcnt(8)
	s_waitcnt lgkmcnt(0)
	s_barrier
	s_setprio 1
	s_waitcnt lgkmcnt(0)
	v_mfma_f32_16x16x32_bf16 v[60:63], v[128:131], v[198:201], v[60:63]
	v_mfma_f32_16x16x32_bf16 v[56:59], v[136:139], v[198:201], v[56:59]
	v_mfma_f32_16x16x32_bf16 v[52:55], v[128:131], v[206:209], v[52:55]
	v_mfma_f32_16x16x32_bf16 v[44:47], v[136:139], v[206:209], v[44:47]
	v_mfma_f32_16x16x32_bf16 v[36:39], v[128:131], v[214:217], v[36:39]
	v_mfma_f32_16x16x32_bf16 v[28:31], v[136:139], v[214:217], v[28:31]
	v_mfma_f32_16x16x32_bf16 v[20:23], v[128:131], v[222:225], v[20:23]
	v_mfma_f32_16x16x32_bf16 v[12:15], v[136:139], v[222:225], v[12:15]
	v_mfma_f32_16x16x32_bf16 v[60:63], v[132:135], v[202:205], v[60:63]
	v_mfma_f32_16x16x32_bf16 v[56:59], v[140:143], v[202:205], v[56:59]
	v_mfma_f32_16x16x32_bf16 v[52:55], v[132:135], v[210:213], v[52:55]
	v_mfma_f32_16x16x32_bf16 v[44:47], v[140:143], v[210:213], v[44:47]
	v_mfma_f32_16x16x32_bf16 v[36:39], v[132:135], v[218:221], v[36:39]
	v_mfma_f32_16x16x32_bf16 v[28:31], v[140:143], v[218:221], v[28:31]
	v_mfma_f32_16x16x32_bf16 v[20:23], v[132:135], v[226:229], v[20:23]
	v_mfma_f32_16x16x32_bf16 v[12:15], v[140:143], v[226:229], v[12:15]
	v_mfma_f32_16x16x32_bf16 v[48:51], v[172:175], v[198:201], v[48:51]
	v_mfma_f32_16x16x32_bf16 v[40:43], v[186:189], v[198:201], v[40:43]
	v_mfma_f32_16x16x32_bf16 v[32:35], v[172:175], v[206:209], v[32:35]
	v_mfma_f32_16x16x32_bf16 v[24:27], v[186:189], v[206:209], v[24:27]
	v_mfma_f32_16x16x32_bf16 v[16:19], v[172:175], v[214:217], v[16:19]
	v_mfma_f32_16x16x32_bf16 v[8:11], v[186:189], v[214:217], v[8:11]
	v_mfma_f32_16x16x32_bf16 v[4:7], v[172:175], v[222:225], v[4:7]
	v_mfma_f32_16x16x32_bf16 v[0:3], v[186:189], v[222:225], v[0:3]
	v_mfma_f32_16x16x32_bf16 v[48:51], v[182:185], v[202:205], v[48:51]
	v_mfma_f32_16x16x32_bf16 v[40:43], v[194:197], v[202:205], v[40:43]
	v_mfma_f32_16x16x32_bf16 v[32:35], v[182:185], v[210:213], v[32:35]
	v_mfma_f32_16x16x32_bf16 v[24:27], v[194:197], v[210:213], v[24:27]
	v_mfma_f32_16x16x32_bf16 v[16:19], v[182:185], v[218:221], v[16:19]
	v_mfma_f32_16x16x32_bf16 v[8:11], v[194:197], v[218:221], v[8:11]
	v_mfma_f32_16x16x32_bf16 v[4:7], v[182:185], v[226:229], v[4:7]
	v_mfma_f32_16x16x32_bf16 v[0:3], v[194:197], v[226:229], v[0:3]
	s_setprio 0
	s_barrier
	s_add_i32 s82, s82, 2
	s_add_u32 s40, s40, 0x100
	s_addc_u32 s41, s41, 0
	s_add_u32 s47, s47, 0x100
	s_addc_u32 s81, s81, 0
	s_cmp_gt_u32 s82, 13
	s_cbranch_scc0 .LBB0_452
	s_and_b64 vcc, exec, s[10:11]
	s_cbranch_vccz .LBB0_455
	s_barrier

; #define PG8_STAGE(bufoff, gbase, voff) do { _Pragma("unroll") for (int _i = 0; _i < 2; ++_i) \
;         __builtin_amdgcn_global_load_lds((const unsigned*)((const char*)(gbase) + (voff)[_i]), (LAS unsigned*)(lds + (bufoff) + ldsw + _i * 8192), 16, 0, 0); } while (0)
; #define PG8_LDA(dst, b, h) do { _Pragma("unroll") for (int m = 0; m < 4; ++m) _Pragma("unroll") for (int k = 0; k < 2; ++k) dst[m][k] = *(const LAS bf16x8*)(lds + PG8_SA(b, h) + aoff + m * 2048 + k * 1024); } while (0)
; #define PG8_LDB(dst, b, h) do { _Pragma("unroll") for (int n = 0; n < 2; ++n) _Pragma("unroll") for (int k = 0; k < 2; ++k) dst[n][k] = *(const LAS bf16x8*)(lds + PG8_SB(b, h) + boff + n * 2048 + k * 1024); } while (0)
; #define PG8_MMA(ai, bj, At, Bt) do { __builtin_amdgcn_s_setprio(1); _Pragma("unroll") for (int m = 0; m < 4; ++m) _Pragma("unroll") for (int n = 0; n < 2; ++n) _Pragma("unroll") for (int k = 0; k < 2; ++k) \
;         acc[ai][bj][m][n] = __builtin_amdgcn_mfma_f32_16x16x32_bf16(Bt[n][k], At[m][k], acc[ai][bj][m][n], 0, 0, 0); __builtin_amdgcn_s_setprio(0); } while (0)
; #define PG8_WAIT_V(n) asm volatile("s_waitcnt vmcnt(" #n ")" ::: "memory")
; #define PG8_WAIT_L(n) asm volatile("s_waitcnt lgkmcnt(" #n ")" ::: "memory")
; #define PG8_BAR __builtin_amdgcn_s_barrier()
; #define PG8_SCHED __builtin_amdgcn_sched_barrier(0)
; template <class Epi>
; __device__ __forceinline__ void gemm_phase(LAS unsigned char* lds, const Gemm g, const StaticOrder& S, const Epi& E) {
;     ...
;             const bool last = (t == nt - 2);
;             const char* a1 = cA + (size_t)(t + 1) * kstep;
;             const char* a2 = last ? nA : cA + (size_t)(t + 2) * kstep; const char* b2 = last ? nB : cB + (size_t)(t + 2) * kstep;
;             const char* a3 = a2 + kstep; const char* b3 = b2 + kstep;
;             PG8_LDB(B0, 0, 0); PG8_LDB(B1, 0, 1); PG8_SCHED; PG8_LDA(At, 0, 0); PG8_STAGE(PG8_SA(1, 1), a1 + hstepA, voffA);
;             PG8_WAIT_V(8); PG8_WAIT_L(0); PG8_BAR; PG8_MMA(0, 0, At, B0); PG8_MMA(0, 1, At, B1); PG8_BAR; PG8_SCHED;
;             PG8_LDA(At, 0, 1); PG8_STAGE(PG8_SB(0, 0), b2, voffB); PG8_STAGE(PG8_SB(0, 1), b2 + hstepB, voffB); PG8_STAGE(PG8_SA(0, 0), a2, voffA);
;             PG8_WAIT_V(8); PG8_WAIT_L(0); PG8_BAR; PG8_MMA(1, 0, At, B0); PG8_MMA(1, 1, At, B1); PG8_BAR; PG8_SCHED;
.LBB0_609:
	ds_read_b128 v[154:157], v150
	ds_read_b128 v[162:165], v150 offset:1024
	ds_read_b128 v[172:175], v150 offset:2048
	ds_read_b128 v[184:187], v150 offset:3072
	ds_read_b128 v[188:191], v151
	ds_read_b128 v[192:195], v151 offset:1024
	ds_read_b128 v[196:199], v151 offset:2048
	ds_read_b128 v[200:203], v151 offset:3072
	s_add_u32 s38, s36, 0x100
	s_addc_u32 s39, s37, 0
	s_cmp_eq_u32 s78, 2
	s_cselect_b32 s53, s7, s39
	s_cselect_b32 s52, s6, s38
	s_cselect_b32 s41, s19, s47
	s_cselect_b32 s40, s18, s46
	v_lshl_add_u64 v[146:147], s[36:37], 0, v[138:139]
	s_add_i32 m0, s56, 0xc000
	ds_read_b128 v[204:207], v152
	ds_read_b128 v[208:211], v152 offset:1024
	ds_read_b128 v[212:215], v152 offset:2048
	ds_read_b128 v[216:219], v152 offset:3072
	ds_read_b128 v[220:223], v152 offset:4096
	ds_read_b128 v[224:227], v152 offset:5120
	ds_read_b128 v[228:231], v152 offset:6144
	ds_read_b128 v[232:235], v152 offset:7168
	global_load_lds_dwordx4 v[146:147], off
	v_lshl_add_u64 v[146:147], s[36:37], 0, v[140:141]
	s_add_i32 m0, s56, 0xe000
	s_nop 0
	global_load_lds_dwordx4 v[146:147], off
	s_waitcnt vmcnt(8)
	s_waitcnt lgkmcnt(0)
	s_barrier
	s_setprio 1
	s_waitcnt lgkmcnt(0)
	v_mfma_f32_16x16x32_bf16 v[124:127], v[154:157], v[204:207], v[124:127]
	v_mfma_f32_16x16x32_bf16 v[120:123], v[172:175], v[204:207], v[120:123]
	v_mfma_f32_16x16x32_bf16 v[116:119], v[154:157], v[212:215], v[116:119]
	v_mfma_f32_16x16x32_bf16 v[108:111], v[172:175], v[212:215], v[108:111]
	v_mfma_f32_16x16x32_bf16 v[100:103], v[154:157], v[220:223], v[100:103]
	v_mfma_f32_16x16x32_bf16 v[92:95], v[172:175], v[220:223], v[92:95]
	v_mfma_f32_16x16x32_bf16 v[84:87], v[154:157], v[228:231], v[84:87]
	v_mfma_f32_16x16x32_bf16 v[76:79], v[172:175], v[228:231], v[76:79]
	v_mfma_f32_16x16x32_bf16 v[124:127], v[162:165], v[208:211], v[124:127]
	v_mfma_f32_16x16x32_bf16 v[120:123], v[184:187], v[208:211], v[120:123]
	v_mfma_f32_16x16x32_bf16 v[116:119], v[162:165], v[216:219], v[116:119]
	v_mfma_f32_16x16x32_bf16 v[108:111], v[184:187], v[216:219], v[108:111]
	v_mfma_f32_16x16x32_bf16 v[100:103], v[162:165], v[224:227], v[100:103]
	v_mfma_f32_16x16x32_bf16 v[92:95], v[184:187], v[224:227], v[92:95]
	v_mfma_f32_16x16x32_bf16 v[84:87], v[162:165], v[232:235], v[84:87]
	v_mfma_f32_16x16x32_bf16 v[76:79], v[184:187], v[232:235], v[76:79]
	v_mfma_f32_16x16x32_bf16 v[112:115], v[188:191], v[204:207], v[112:115]
	v_mfma_f32_16x16x32_bf16 v[104:107], v[196:199], v[204:207], v[104:107]
	v_mfma_f32_16x16x32_bf16 v[96:99], v[188:191], v[212:215], v[96:99]
	v_mfma_f32_16x16x32_bf16 v[88:91], v[196:199], v[212:215], v[88:91]
	v_mfma_f32_16x16x32_bf16 v[80:83], v[188:191], v[220:223], v[80:83]
	v_mfma_f32_16x16x32_bf16 v[72:75], v[196:199], v[220:223], v[72:75]
	v_mfma_f32_16x16x32_bf16 v[68:71], v[188:191], v[228:231], v[68:71]
	v_mfma_f32_16x16x32_bf16 v[64:67], v[196:199], v[228:231], v[64:67]
	v_mfma_f32_16x16x32_bf16 v[112:115], v[192:195], v[208:211], v[112:115]
	v_mfma_f32_16x16x32_bf16 v[104:107], v[200:203], v[208:211], v[104:107]
	v_mfma_f32_16x16x32_bf16 v[96:99], v[192:195], v[216:219], v[96:99]
	v_mfma_f32_16x16x32_bf16 v[88:91], v[200:203], v[216:219], v[88:91]
	v_mfma_f32_16x16x32_bf16 v[80:83], v[192:195], v[224:227], v[80:83]
	v_mfma_f32_16x16x32_bf16 v[72:75], v[200:203], v[224:227], v[72:75]
	v_mfma_f32_16x16x32_bf16 v[68:71], v[192:195], v[232:235], v[68:71]
	v_mfma_f32_16x16x32_bf16 v[64:67], v[200:203], v[232:235], v[64:67]
	s_setprio 0
	s_barrier
	s_add_i32 s20, s70, s54
	v_lshl_add_u64 v[146:147], s[40:41], 0, v[132:133]
	s_mov_b32 m0, s20
	ds_read_b128 v[204:207], v152 offset:16384
	ds_read_b128 v[208:211], v152 offset:17408
	ds_read_b128 v[212:215], v152 offset:18432
	ds_read_b128 v[216:219], v152 offset:19456
	ds_read_b128 v[220:223], v152 offset:20480
	ds_read_b128 v[224:227], v152 offset:21504
	ds_read_b128 v[228:231], v152 offset:22528
	ds_read_b128 v[232:235], v152 offset:23552
	global_load_lds_dwordx4 v[146:147], off
	s_add_i32 m0, s20, 0x2000
	s_add_u32 s20, s40, 0x18000
	v_lshl_add_u64 v[158:159], s[40:41], 0, v[128:129]
	s_addc_u32 s21, s41, 0
	s_add_i32 s28, s71, s54
	global_load_lds_dwordx4 v[158:159], off
	v_lshl_add_u64 v[166:167], s[20:21], 0, v[132:133]
	s_mov_b32 m0, s28
	v_lshl_add_u64 v[240:241], s[52:53], 0, v[130:131]
	global_load_lds_dwordx4 v[166:167], off
	v_lshl_add_u64 v[166:167], s[20:21], 0, v[128:129]
	s_add_i32 m0, s28, 0x2000
	s_nop 0
	global_load_lds_dwordx4 v[166:167], off
	v_lshl_add_u64 v[166:167], s[52:53], 0, v[134:135]
	s_mov_b32 m0, s56
	s_nop 0
	global_load_lds_dwordx4 v[166:167], off
	s_mov_b32 m0, s57
	s_nop 0
	global_load_lds_dwordx4 v[240:241], off
	s_waitcnt vmcnt(8)
	s_waitcnt lgkmcnt(0)
	s_barrier
; #define PG8_STAGE(bufoff, gbase, voff) do { _Pragma("unroll") for (int _i = 0; _i < 2; ++_i) \
;         __builtin_amdgcn_global_load_lds((const unsigned*)((const char*)(gbase) + (voff)[_i]), (LAS unsigned*)(lds + (bufoff) + ldsw + _i * 8192), 16, 0, 0); } while (0)
; #define PG8_LDA(dst, b, h) do { _Pragma("unroll") for (int m = 0; m < 4; ++m) _Pragma("unroll") for (int k = 0; k < 2; ++k) dst[m][k] = *(const LAS bf16x8*)(lds + PG8_SA(b, h) + aoff + m * 2048 + k * 1024); } while (0)
; #define PG8_LDB(dst, b, h) do { _Pragma("unroll") for (int n = 0; n < 2; ++n) _Pragma("unroll") for (int k = 0; k < 2; ++k) dst[n][k] = *(const LAS bf16x8*)(lds + PG8_SB(b, h) + boff + n * 2048 + k * 1024); } while (0)
; #define PG8_MMA(ai, bj, At, Bt) do { __builtin_amdgcn_s_setprio(1); _Pragma("unroll") for (int m = 0; m < 4; ++m) _Pragma("unroll") for (int n = 0; n < 2; ++n) _Pragma("unroll") for (int k = 0; k < 2; ++k) \
;         acc[ai][bj][m][n] = __builtin_amdgcn_mfma_f32_16x16x32_bf16(Bt[n][k], At[m][k], acc[ai][bj][m][n], 0, 0, 0); __builtin_amdgcn_s_setprio(0); } while (0)
; #define PG8_WAIT_V(n) asm volatile("s_waitcnt vmcnt(" #n ")" ::: "memory")
; #define PG8_WAIT_L(n) asm volatile("s_waitcnt lgkmcnt(" #n ")" ::: "memory")
; #define PG8_BAR __builtin_amdgcn_s_barrier()
; #define PG8_SCHED __builtin_amdgcn_sched_barrier(0)
; template <class Epi>
; __device__ __forceinline__ void gemm_phase(LAS unsigned char* lds, const Gemm g, const StaticOrder& S, const Epi& E) {
;     ...
;             PG8_WAIT_V(8); PG8_WAIT_L(0); PG8_BAR; PG8_MMA(1, 0, At, B0); PG8_MMA(1, 1, At, B1); PG8_BAR; PG8_SCHED;
;             PG8_LDB(B0, 1, 0); PG8_LDB(B1, 1, 1); PG8_SCHED; PG8_LDA(At, 1, 0); PG8_STAGE(PG8_SA(0, 1), a2 + hstepA, voffA);
;             PG8_WAIT_V(8); PG8_WAIT_L(0); PG8_BAR; PG8_MMA(0, 0, At, B0); PG8_MMA(0, 1, At, B1); PG8_BAR; PG8_SCHED;
	s_setprio 1
	s_waitcnt lgkmcnt(0)
	v_mfma_f32_16x16x32_bf16 v[60:63], v[154:157], v[204:207], v[60:63]
	v_mfma_f32_16x16x32_bf16 v[56:59], v[172:175], v[204:207], v[56:59]
	v_mfma_f32_16x16x32_bf16 v[52:55], v[154:157], v[212:215], v[52:55]
	v_mfma_f32_16x16x32_bf16 v[44:47], v[172:175], v[212:215], v[44:47]
	v_mfma_f32_16x16x32_bf16 v[36:39], v[154:157], v[220:223], v[36:39]
	v_mfma_f32_16x16x32_bf16 v[28:31], v[172:175], v[220:223], v[28:31]
	v_mfma_f32_16x16x32_bf16 v[20:23], v[154:157], v[228:231], v[20:23]
	v_mfma_f32_16x16x32_bf16 v[12:15], v[172:175], v[228:231], v[12:15]
	v_mfma_f32_16x16x32_bf16 v[60:63], v[162:165], v[208:211], v[60:63]
	v_mfma_f32_16x16x32_bf16 v[56:59], v[184:187], v[208:211], v[56:59]
	v_mfma_f32_16x16x32_bf16 v[52:55], v[162:165], v[216:219], v[52:55]
	v_mfma_f32_16x16x32_bf16 v[44:47], v[184:187], v[216:219], v[44:47]
	v_mfma_f32_16x16x32_bf16 v[36:39], v[162:165], v[224:227], v[36:39]
	v_mfma_f32_16x16x32_bf16 v[28:31], v[184:187], v[224:227], v[28:31]
	v_mfma_f32_16x16x32_bf16 v[20:23], v[162:165], v[232:235], v[20:23]
	v_mfma_f32_16x16x32_bf16 v[12:15], v[184:187], v[232:235], v[12:15]
	v_mfma_f32_16x16x32_bf16 v[48:51], v[188:191], v[204:207], v[48:51]
	v_mfma_f32_16x16x32_bf16 v[40:43], v[196:199], v[204:207], v[40:43]
	v_mfma_f32_16x16x32_bf16 v[32:35], v[188:191], v[212:215], v[32:35]
	v_mfma_f32_16x16x32_bf16 v[24:27], v[196:199], v[212:215], v[24:27]
	v_mfma_f32_16x16x32_bf16 v[16:19], v[188:191], v[220:223], v[16:19]
	v_mfma_f32_16x16x32_bf16 v[8:11], v[196:199], v[220:223], v[8:11]
	v_mfma_f32_16x16x32_bf16 v[4:7], v[188:191], v[228:231], v[4:7]
	v_mfma_f32_16x16x32_bf16 v[0:3], v[196:199], v[228:231], v[0:3]
	v_mfma_f32_16x16x32_bf16 v[48:51], v[192:195], v[208:211], v[48:51]
	v_mfma_f32_16x16x32_bf16 v[40:43], v[200:203], v[208:211], v[40:43]
	v_mfma_f32_16x16x32_bf16 v[32:35], v[192:195], v[216:219], v[32:35]
	v_mfma_f32_16x16x32_bf16 v[24:27], v[200:203], v[216:219], v[24:27]
	v_mfma_f32_16x16x32_bf16 v[16:19], v[192:195], v[224:227], v[16:19]
	v_mfma_f32_16x16x32_bf16 v[8:11], v[200:203], v[224:227], v[8:11]
	v_mfma_f32_16x16x32_bf16 v[4:7], v[192:195], v[232:235], v[4:7]
	v_mfma_f32_16x16x32_bf16 v[0:3], v[200:203], v[232:235], v[0:3]
	s_setprio 0
	s_barrier
	s_add_i32 s28, 0, 0x18000
	v_add_u32_e32 v153, s28, v149
	s_add_i32 s29, 0, 0x1c000
	ds_read_b128 v[154:157], v153
	ds_read_b128 v[162:165], v153 offset:1024
	ds_read_b128 v[172:175], v153 offset:2048
	ds_read_b128 v[184:187], v153 offset:3072
	v_add_u32_e32 v153, s29, v149
	ds_read_b128 v[188:191], v153
	ds_read_b128 v[192:195], v153 offset:1024
	ds_read_b128 v[196:199], v153 offset:2048
	ds_read_b128 v[200:203], v153 offset:3072
	s_add_u32 s20, s52, 0x90000
	s_addc_u32 s21, s53, 0
	s_mov_b32 m0, s58
	v_lshl_add_u64 v[242:243], s[20:21], 0, v[134:135]
	ds_read_b128 v[204:207], v152 offset:32768
	ds_read_b128 v[208:211], v152 offset:33792
	ds_read_b128 v[212:215], v152 offset:34816
	ds_read_b128 v[216:219], v152 offset:35840
	ds_read_b128 v[220:223], v152 offset:36864
	ds_read_b128 v[224:227], v152 offset:37888
	ds_read_b128 v[228:231], v152 offset:38912
	ds_read_b128 v[232:235], v152 offset:39936
	global_load_lds_dwordx4 v[242:243], off
	v_lshl_add_u64 v[242:243], s[20:21], 0, v[130:131]
	s_mov_b32 m0, s59
	s_nop 0
	global_load_lds_dwordx4 v[242:243], off
	s_waitcnt vmcnt(8)
	s_waitcnt lgkmcnt(0)
	s_barrier
	s_setprio 1
	s_waitcnt lgkmcnt(0)
	v_mfma_f32_16x16x32_bf16 v[124:127], v[154:157], v[204:207], v[124:127]
	v_mfma_f32_16x16x32_bf16 v[120:123], v[172:175], v[204:207], v[120:123]
	v_mfma_f32_16x16x32_bf16 v[116:119], v[154:157], v[212:215], v[116:119]
	v_mfma_f32_16x16x32_bf16 v[108:111], v[172:175], v[212:215], v[108:111]
	v_mfma_f32_16x16x32_bf16 v[100:103], v[154:157], v[220:223], v[100:103]
	v_mfma_f32_16x16x32_bf16 v[92:95], v[172:175], v[220:223], v[92:95]
	v_mfma_f32_16x16x32_bf16 v[84:87], v[154:157], v[228:231], v[84:87]
	v_mfma_f32_16x16x32_bf16 v[76:79], v[172:175], v[228:231], v[76:79]
	v_mfma_f32_16x16x32_bf16 v[124:127], v[162:165], v[208:211], v[124:127]
	v_mfma_f32_16x16x32_bf16 v[120:123], v[184:187], v[208:211], v[120:123]
	v_mfma_f32_16x16x32_bf16 v[116:119], v[162:165], v[216:219], v[116:119]
	v_mfma_f32_16x16x32_bf16 v[108:111], v[184:187], v[216:219], v[108:111]
	v_mfma_f32_16x16x32_bf16 v[100:103], v[162:165], v[224:227], v[100:103]
	v_mfma_f32_16x16x32_bf16 v[92:95], v[184:187], v[224:227], v[92:95]
	v_mfma_f32_16x16x32_bf16 v[84:87], v[162:165], v[232:235], v[84:87]
	v_mfma_f32_16x16x32_bf16 v[76:79], v[184:187], v[232:235], v[76:79]
	v_mfma_f32_16x16x32_bf16 v[112:115], v[188:191], v[204:207], v[112:115]
	v_mfma_f32_16x16x32_bf16 v[104:107], v[196:199], v[204:207], v[104:107]
	v_mfma_f32_16x16x32_bf16 v[96:99], v[188:191], v[212:215], v[96:99]
	v_mfma_f32_16x16x32_bf16 v[88:91], v[196:199], v[212:215], v[88:91]
	v_mfma_f32_16x16x32_bf16 v[80:83], v[188:191], v[220:223], v[80:83]
	v_mfma_f32_16x16x32_bf16 v[72:75], v[196:199], v[220:223], v[72:75]
	v_mfma_f32_16x16x32_bf16 v[68:71], v[188:191], v[228:231], v[68:71]
	v_mfma_f32_16x16x32_bf16 v[64:67], v[196:199], v[228:231], v[64:67]
	v_mfma_f32_16x16x32_bf16 v[112:115], v[192:195], v[208:211], v[112:115]
	v_mfma_f32_16x16x32_bf16 v[104:107], v[200:203], v[208:211], v[104:107]
	v_mfma_f32_16x16x32_bf16 v[96:99], v[192:195], v[216:219], v[96:99]
	v_mfma_f32_16x16x32_bf16 v[88:91], v[200:203], v[216:219], v[88:91]
	v_mfma_f32_16x16x32_bf16 v[80:83], v[192:195], v[224:227], v[80:83]
	v_mfma_f32_16x16x32_bf16 v[72:75], v[200:203], v[224:227], v[72:75]
	v_mfma_f32_16x16x32_bf16 v[68:71], v[192:195], v[232:235], v[68:71]
	v_mfma_f32_16x16x32_bf16 v[64:67], v[200:203], v[232:235], v[64:67]
	s_setprio 0
	s_barrier
; #define PG8_STAGE(bufoff, gbase, voff) do { _Pragma("unroll") for (int _i = 0; _i < 2; ++_i) \
;         __builtin_amdgcn_global_load_lds((const unsigned*)((const char*)(gbase) + (voff)[_i]), (LAS unsigned*)(lds + (bufoff) + ldsw + _i * 8192), 16, 0, 0); } while (0)
; #define PG8_LDA(dst, b, h) do { _Pragma("unroll") for (int m = 0; m < 4; ++m) _Pragma("unroll") for (int k = 0; k < 2; ++k) dst[m][k] = *(const LAS bf16x8*)(lds + PG8_SA(b, h) + aoff + m * 2048 + k * 1024); } while (0)
; #define PG8_MMA(ai, bj, At, Bt) do { __builtin_amdgcn_s_setprio(1); _Pragma("unroll") for (int m = 0; m < 4; ++m) _Pragma("unroll") for (int n = 0; n < 2; ++n) _Pragma("unroll") for (int k = 0; k < 2; ++k) \
;         acc[ai][bj][m][n] = __builtin_amdgcn_mfma_f32_16x16x32_bf16(Bt[n][k], At[m][k], acc[ai][bj][m][n], 0, 0, 0); __builtin_amdgcn_s_setprio(0); } while (0)
; #define PG8_WAIT_V(n) asm volatile("s_waitcnt vmcnt(" #n ")" ::: "memory")
; #define PG8_WAIT_L(n) asm volatile("s_waitcnt lgkmcnt(" #n ")" ::: "memory")
; #define PG8_BAR __builtin_amdgcn_s_barrier()
; #define PG8_SCHED __builtin_amdgcn_sched_barrier(0)
; template <class Epi>
; __device__ __forceinline__ void gemm_phase(LAS unsigned char* lds, const Gemm g, const StaticOrder& S, const Epi& E) {
;     ...
;             PG8_LDA(At, 1, 1); PG8_STAGE(PG8_SB(1, 0), b3, voffB); PG8_STAGE(PG8_SB(1, 1), b3 + hstepB, voffB); PG8_STAGE(PG8_SA(1, 0), a3, voffA);
;             PG8_WAIT_V(8); PG8_WAIT_L(0); PG8_BAR; PG8_MMA(1, 0, At, B0); PG8_MMA(1, 1, At, B1); PG8_BAR; PG8_SCHED;
;         }
;         if (wr == 0) PG8_BAR;
	s_add_i32 s20, s28, s54
	v_lshl_add_u64 v[146:147], v[146:147], 0, s[12:13]
	s_mov_b32 m0, s20
	ds_read_b128 v[204:207], v152 offset:49152
	ds_read_b128 v[208:211], v152 offset:50176
	ds_read_b128 v[212:215], v152 offset:51200
	ds_read_b128 v[216:219], v152 offset:52224
	ds_read_b128 v[220:223], v152 offset:53248
	ds_read_b128 v[224:227], v152 offset:54272
	ds_read_b128 v[228:231], v152 offset:55296
	ds_read_b128 v[232:235], v152 offset:56320
	global_load_lds_dwordx4 v[146:147], off
	s_add_i32 m0, s20, 0x2000
	s_add_u32 s20, s40, 0x18080
	v_lshl_add_u64 v[146:147], v[158:159], 0, s[12:13]
	s_addc_u32 s21, s41, 0
	s_add_i32 s28, s29, s54
	global_load_lds_dwordx4 v[146:147], off
	v_lshl_add_u64 v[146:147], s[20:21], 0, v[132:133]
	s_mov_b32 m0, s28
	s_nop 0
	global_load_lds_dwordx4 v[146:147], off
	v_lshl_add_u64 v[146:147], s[20:21], 0, v[128:129]
	s_add_i32 m0, s28, 0x2000
	s_nop 0
	global_load_lds_dwordx4 v[146:147], off
	v_lshl_add_u64 v[146:147], v[166:167], 0, s[12:13]
	s_mov_b32 m0, s60
	s_nop 0
	global_load_lds_dwordx4 v[146:147], off
	v_lshl_add_u64 v[146:147], v[240:241], 0, s[12:13]
	s_mov_b32 m0, s61
	s_nop 0
	global_load_lds_dwordx4 v[146:147], off
	s_waitcnt vmcnt(8)
	s_waitcnt lgkmcnt(0)
	s_barrier
	s_setprio 1
	s_waitcnt lgkmcnt(0)
	v_mfma_f32_16x16x32_bf16 v[60:63], v[154:157], v[204:207], v[60:63]
	v_mfma_f32_16x16x32_bf16 v[56:59], v[172:175], v[204:207], v[56:59]
	v_mfma_f32_16x16x32_bf16 v[52:55], v[154:157], v[212:215], v[52:55]
	v_mfma_f32_16x16x32_bf16 v[44:47], v[172:175], v[212:215], v[44:47]
	v_mfma_f32_16x16x32_bf16 v[36:39], v[154:157], v[220:223], v[36:39]
	v_mfma_f32_16x16x32_bf16 v[28:31], v[172:175], v[220:223], v[28:31]
	v_mfma_f32_16x16x32_bf16 v[20:23], v[154:157], v[228:231], v[20:23]
	v_mfma_f32_16x16x32_bf16 v[12:15], v[172:175], v[228:231], v[12:15]
	v_mfma_f32_16x16x32_bf16 v[60:63], v[162:165], v[208:211], v[60:63]
	v_mfma_f32_16x16x32_bf16 v[56:59], v[184:187], v[208:211], v[56:59]
	v_mfma_f32_16x16x32_bf16 v[52:55], v[162:165], v[216:219], v[52:55]
	v_mfma_f32_16x16x32_bf16 v[44:47], v[184:187], v[216:219], v[44:47]
	v_mfma_f32_16x16x32_bf16 v[36:39], v[162:165], v[224:227], v[36:39]
	v_mfma_f32_16x16x32_bf16 v[28:31], v[184:187], v[224:227], v[28:31]
	v_mfma_f32_16x16x32_bf16 v[20:23], v[162:165], v[232:235], v[20:23]
	v_mfma_f32_16x16x32_bf16 v[12:15], v[184:187], v[232:235], v[12:15]
	v_mfma_f32_16x16x32_bf16 v[48:51], v[188:191], v[204:207], v[48:51]
	v_mfma_f32_16x16x32_bf16 v[40:43], v[196:199], v[204:207], v[40:43]
	v_mfma_f32_16x16x32_bf16 v[32:35], v[188:191], v[212:215], v[32:35]
	v_mfma_f32_16x16x32_bf16 v[24:27], v[196:199], v[212:215], v[24:27]
	v_mfma_f32_16x16x32_bf16 v[16:19], v[188:191], v[220:223], v[16:19]
	v_mfma_f32_16x16x32_bf16 v[8:11], v[196:199], v[220:223], v[8:11]
	v_mfma_f32_16x16x32_bf16 v[4:7], v[188:191], v[228:231], v[4:7]
	v_mfma_f32_16x16x32_bf16 v[0:3], v[196:199], v[228:231], v[0:3]
	v_mfma_f32_16x16x32_bf16 v[48:51], v[192:195], v[208:211], v[48:51]
	v_mfma_f32_16x16x32_bf16 v[40:43], v[200:203], v[208:211], v[40:43]
	v_mfma_f32_16x16x32_bf16 v[32:35], v[192:195], v[216:219], v[32:35]
	v_mfma_f32_16x16x32_bf16 v[24:27], v[200:203], v[216:219], v[24:27]
	v_mfma_f32_16x16x32_bf16 v[16:19], v[192:195], v[224:227], v[16:19]
	v_mfma_f32_16x16x32_bf16 v[8:11], v[200:203], v[224:227], v[8:11]
	v_mfma_f32_16x16x32_bf16 v[4:7], v[192:195], v[232:235], v[4:7]
	v_mfma_f32_16x16x32_bf16 v[0:3], v[200:203], v[232:235], v[0:3]
	s_setprio 0
	s_barrier
	s_add_i32 s78, s78, 2
	s_add_u32 s46, s46, 0x100
	s_addc_u32 s47, s47, 0
	s_cmp_gt_u32 s78, 3
	s_mov_b64 s[36:37], s[38:39]
	s_cbranch_scc0 .LBB0_609
	s_and_b64 vcc, exec, s[14:15]
	s_cbranch_vccz .LBB0_612
	s_barrier

; #define PG8_STAGE(bufoff, gbase, voff) do { _Pragma("unroll") for (int _i = 0; _i < 2; ++_i) \
;         __builtin_amdgcn_global_load_lds((const unsigned*)((const char*)(gbase) + (voff)[_i]), (LAS unsigned*)(lds + (bufoff) + ldsw + _i * 8192), 16, 0, 0); } while (0)
; #define PG8_LDA(dst, b, h) do { _Pragma("unroll") for (int m = 0; m < 4; ++m) _Pragma("unroll") for (int k = 0; k < 2; ++k) dst[m][k] = *(const LAS bf16x8*)(lds + PG8_SA(b, h) + aoff + m * 2048 + k * 1024); } while (0)
; #define PG8_LDB(dst, b, h) do { _Pragma("unroll") for (int n = 0; n < 2; ++n) _Pragma("unroll") for (int k = 0; k < 2; ++k) dst[n][k] = *(const LAS bf16x8*)(lds + PG8_SB(b, h) + boff + n * 2048 + k * 1024); } while (0)
; #define PG8_MMA(ai, bj, At, Bt) do { __builtin_amdgcn_s_setprio(1); _Pragma("unroll") for (int m = 0; m < 4; ++m) _Pragma("unroll") for (int n = 0; n < 2; ++n) _Pragma("unroll") for (int k = 0; k < 2; ++k) \
;         acc[ai][bj][m][n] = __builtin_amdgcn_mfma_f32_16x16x32_bf16(Bt[n][k], At[m][k], acc[ai][bj][m][n], 0, 0, 0); __builtin_amdgcn_s_setprio(0); } while (0)
; #define PG8_WAIT_V(n) asm volatile("s_waitcnt vmcnt(" #n ")" ::: "memory")
; #define PG8_BAR __builtin_amdgcn_s_barrier()
; template <class Epi>
; __device__ __forceinline__ void gemm_phase(LAS unsigned char* lds, const Gemm g, const StaticOrder& S, const Epi& E) {
;     ...
;         const char* nA = has_next ? (const char*)g.A + (size_t)nxt.pm * tstepA : cA; const char* nB = has_next ? (const char*)g.Bt + (size_t)nxt.pn * tstepB : cB;
;         for (int t = 0; t < nt; t += 2) {
;             const bool last = (t == nt - 2);
;             const char* a1 = cA + (size_t)(t + 1) * kstep;
;             const char* a2 = last ? nA : cA + (size_t)(t + 2) * kstep; const char* b2 = last ? nB : cB + (size_t)(t + 2) * kstep;
;             const char* a3 = a2 + kstep; const char* b3 = b2 + kstep;
;             PG8_LDB(B0, 0, 0); PG8_LDB(B1, 0, 1); PG8_SCHED; PG8_LDA(At, 0, 0); PG8_STAGE(PG8_SA(1, 1), a1 + hstepA, voffA);
;             PG8_WAIT_V(8); PG8_WAIT_L(0); PG8_BAR; PG8_MMA(0, 0, At, B0); PG8_MMA(0, 1, At, B1); PG8_BAR; PG8_SCHED;
;             PG8_LDA(At, 0, 1); PG8_STAGE(PG8_SB(0, 0), b2, voffB); PG8_STAGE(PG8_SB(0, 1), b2 + hstepB, voffB); PG8_STAGE(PG8_SA(0, 0), a2, voffA);
;             PG8_WAIT_V(8); PG8_WAIT_L(0); PG8_BAR; PG8_MMA(1, 0, At, B0); PG8_MMA(1, 1, At, B1); PG8_BAR; PG8_SCHED;
.LBB0_625:
	s_add_u32 s28, s40, s58
	s_addc_u32 s29, s41, 0
	s_add_u32 s30, s28, 0x100
	s_addc_u32 s31, s29, 0
	s_and_b64 s[20:21], s[56:57], exec
	s_cselect_b32 s61, s17, s31
	s_cselect_b32 s60, s46, s30
	s_add_u32 s20, s36, s58
	s_addc_u32 s21, s37, 0
	s_add_u32 s30, s20, 0x100
	s_addc_u32 s31, s21, 0
	s_and_b64 s[20:21], s[56:57], exec
	s_cselect_b32 s69, s15, s31
	s_cselect_b32 s68, s47, s30
	s_add_u32 s72, s28, 0x10080
	ds_read_b128 v[148:151], v144
	ds_read_b128 v[152:155], v144 offset:1024
	ds_read_b128 v[156:159], v144 offset:2048
	ds_read_b128 v[162:165], v144 offset:3072
	ds_read_b128 v[172:175], v145
	ds_read_b128 v[184:187], v145 offset:1024
	ds_read_b128 v[188:191], v145 offset:2048
	ds_read_b128 v[192:195], v145 offset:3072
	s_addc_u32 s73, s29, 0
	s_add_i32 s31, s97, s25
	s_add_i32 m0, s3, 0xc000
	s_add_i32 s78, s3, 0xe000
	s_add_i32 s28, s31, 0x2000
	s_add_u32 s70, s68, 0x10000
	s_addc_u32 s71, s69, 0
	s_add_i32 s29, s4, s25
	s_add_i32 s30, s29, 0x2000
	s_add_i32 s21, 0, 0x18000
	s_add_i32 vcc_lo, 0, 0x1c000
	s_add_u32 s58, s60, 0x10000
	s_addc_u32 s59, s61, 0
	s_add_i32 vcc_hi, s21, s25
	s_add_i32 s75, vcc_hi, 0x2000
	s_add_u32 s56, s68, 0x10080
	s_addc_u32 s57, s69, 0
	s_add_i32 s74, vcc_lo, s25
	s_add_i32 s20, s74, 0x2000
	v_lshl_add_u64 v[166:167], s[72:73], 0, v[134:135]
	ds_read_b128 v[196:199], v146
	ds_read_b128 v[200:203], v146 offset:1024
	ds_read_b128 v[204:207], v146 offset:2048
	ds_read_b128 v[208:211], v146 offset:3072
	ds_read_b128 v[212:215], v146 offset:4096
	ds_read_b128 v[216:219], v146 offset:5120
	ds_read_b128 v[220:223], v146 offset:6144
	ds_read_b128 v[224:227], v146 offset:7168
	global_load_lds_dwordx4 v[166:167], off
	v_lshl_add_u64 v[166:167], s[72:73], 0, v[130:131]
	s_mov_b32 m0, s78
	s_nop 0
	global_load_lds_dwordx4 v[166:167], off
	s_waitcnt vmcnt(8)
	s_waitcnt lgkmcnt(0)
	s_barrier
	s_setprio 1
	s_waitcnt lgkmcnt(0)
	v_mfma_f32_16x16x32_bf16 v[124:127], v[148:151], v[196:199], v[124:127]
	v_mfma_f32_16x16x32_bf16 v[120:123], v[156:159], v[196:199], v[120:123]
	v_mfma_f32_16x16x32_bf16 v[116:119], v[148:151], v[204:207], v[116:119]
	v_mfma_f32_16x16x32_bf16 v[112:115], v[156:159], v[204:207], v[112:115]
	v_mfma_f32_16x16x32_bf16 v[100:103], v[148:151], v[212:215], v[100:103]
	v_mfma_f32_16x16x32_bf16 v[96:99], v[156:159], v[212:215], v[96:99]
	v_mfma_f32_16x16x32_bf16 v[84:87], v[148:151], v[220:223], v[84:87]
	v_mfma_f32_16x16x32_bf16 v[80:83], v[156:159], v[220:223], v[80:83]
	v_mfma_f32_16x16x32_bf16 v[124:127], v[152:155], v[200:203], v[124:127]
	v_mfma_f32_16x16x32_bf16 v[120:123], v[162:165], v[200:203], v[120:123]
	v_mfma_f32_16x16x32_bf16 v[116:119], v[152:155], v[208:211], v[116:119]
	v_mfma_f32_16x16x32_bf16 v[112:115], v[162:165], v[208:211], v[112:115]
	v_mfma_f32_16x16x32_bf16 v[100:103], v[152:155], v[216:219], v[100:103]
	v_mfma_f32_16x16x32_bf16 v[96:99], v[162:165], v[216:219], v[96:99]
	v_mfma_f32_16x16x32_bf16 v[84:87], v[152:155], v[224:227], v[84:87]
	v_mfma_f32_16x16x32_bf16 v[80:83], v[162:165], v[224:227], v[80:83]
	v_mfma_f32_16x16x32_bf16 v[108:111], v[172:175], v[196:199], v[108:111]
	v_mfma_f32_16x16x32_bf16 v[104:107], v[188:191], v[196:199], v[104:107]
	v_mfma_f32_16x16x32_bf16 v[92:95], v[172:175], v[204:207], v[92:95]
	v_mfma_f32_16x16x32_bf16 v[88:91], v[188:191], v[204:207], v[88:91]
	v_mfma_f32_16x16x32_bf16 v[76:79], v[172:175], v[212:215], v[76:79]
	v_mfma_f32_16x16x32_bf16 v[72:75], v[188:191], v[212:215], v[72:75]
	v_mfma_f32_16x16x32_bf16 v[68:71], v[172:175], v[220:223], v[68:71]
	v_mfma_f32_16x16x32_bf16 v[64:67], v[188:191], v[220:223], v[64:67]
	v_mfma_f32_16x16x32_bf16 v[108:111], v[184:187], v[200:203], v[108:111]
	v_mfma_f32_16x16x32_bf16 v[104:107], v[192:195], v[200:203], v[104:107]
	v_mfma_f32_16x16x32_bf16 v[92:95], v[184:187], v[208:211], v[92:95]
	v_mfma_f32_16x16x32_bf16 v[88:91], v[192:195], v[208:211], v[88:91]
	v_mfma_f32_16x16x32_bf16 v[76:79], v[184:187], v[216:219], v[76:79]
	v_mfma_f32_16x16x32_bf16 v[72:75], v[192:195], v[216:219], v[72:75]
	v_mfma_f32_16x16x32_bf16 v[68:71], v[184:187], v[224:227], v[68:71]
	v_mfma_f32_16x16x32_bf16 v[64:67], v[192:195], v[224:227], v[64:67]
	s_setprio 0
	s_barrier
	s_mov_b32 m0, s31
	v_lshl_add_u64 v[166:167], s[68:69], 0, v[132:133]
	ds_read_b128 v[196:199], v146 offset:16384
	ds_read_b128 v[200:203], v146 offset:17408
	ds_read_b128 v[204:207], v146 offset:18432
	ds_read_b128 v[208:211], v146 offset:19456
	ds_read_b128 v[212:215], v146 offset:20480
	ds_read_b128 v[216:219], v146 offset:21504
	ds_read_b128 v[220:223], v146 offset:22528
	ds_read_b128 v[224:227], v146 offset:23552
	global_load_lds_dwordx4 v[166:167], off
	v_lshl_add_u64 v[228:229], s[68:69], 0, v[128:129]
	s_mov_b32 m0, s28
	v_lshl_add_u64 v[230:231], s[70:71], 0, v[132:133]
	global_load_lds_dwordx4 v[228:229], off
	s_mov_b32 m0, s29
	v_lshl_add_u64 v[232:233], s[60:61], 0, v[130:131]
	global_load_lds_dwordx4 v[230:231], off
	v_lshl_add_u64 v[230:231], s[70:71], 0, v[128:129]
	s_mov_b32 m0, s30
	s_nop 0
	global_load_lds_dwordx4 v[230:231], off
	v_lshl_add_u64 v[230:231], s[60:61], 0, v[134:135]
	s_mov_b32 m0, s3
	s_nop 0
	global_load_lds_dwordx4 v[230:231], off
	s_mov_b32 m0, s79
	s_nop 0
	global_load_lds_dwordx4 v[232:233], off
	s_waitcnt vmcnt(8)
	s_waitcnt lgkmcnt(0)
	s_barrier
; #define PG8_STAGE(bufoff, gbase, voff) do { _Pragma("unroll") for (int _i = 0; _i < 2; ++_i) \
;         __builtin_amdgcn_global_load_lds((const unsigned*)((const char*)(gbase) + (voff)[_i]), (LAS unsigned*)(lds + (bufoff) + ldsw + _i * 8192), 16, 0, 0); } while (0)
; #define PG8_LDA(dst, b, h) do { _Pragma("unroll") for (int m = 0; m < 4; ++m) _Pragma("unroll") for (int k = 0; k < 2; ++k) dst[m][k] = *(const LAS bf16x8*)(lds + PG8_SA(b, h) + aoff + m * 2048 + k * 1024); } while (0)
; #define PG8_LDB(dst, b, h) do { _Pragma("unroll") for (int n = 0; n < 2; ++n) _Pragma("unroll") for (int k = 0; k < 2; ++k) dst[n][k] = *(const LAS bf16x8*)(lds + PG8_SB(b, h) + boff + n * 2048 + k * 1024); } while (0)
; #define PG8_MMA(ai, bj, At, Bt) do { __builtin_amdgcn_s_setprio(1); _Pragma("unroll") for (int m = 0; m < 4; ++m) _Pragma("unroll") for (int n = 0; n < 2; ++n) _Pragma("unroll") for (int k = 0; k < 2; ++k) \
;         acc[ai][bj][m][n] = __builtin_amdgcn_mfma_f32_16x16x32_bf16(Bt[n][k], At[m][k], acc[ai][bj][m][n], 0, 0, 0); __builtin_amdgcn_s_setprio(0); } while (0)
; #define PG8_WAIT_V(n) asm volatile("s_waitcnt vmcnt(" #n ")" ::: "memory")
; #define PG8_WAIT_L(n) asm volatile("s_waitcnt lgkmcnt(" #n ")" ::: "memory")
; #define PG8_BAR __builtin_amdgcn_s_barrier()
; #define PG8_SCHED __builtin_amdgcn_sched_barrier(0)
; template <class Epi>
; __device__ __forceinline__ void gemm_phase(LAS unsigned char* lds, const Gemm g, const StaticOrder& S, const Epi& E) {
;     ...
;             PG8_WAIT_V(8); PG8_WAIT_L(0); PG8_BAR; PG8_MMA(1, 0, At, B0); PG8_MMA(1, 1, At, B1); PG8_BAR; PG8_SCHED;
;             PG8_LDB(B0, 1, 0); PG8_LDB(B1, 1, 1); PG8_SCHED; PG8_LDA(At, 1, 0); PG8_STAGE(PG8_SA(0, 1), a2 + hstepA, voffA);
;             PG8_WAIT_V(8); PG8_WAIT_L(0); PG8_BAR; PG8_MMA(0, 0, At, B0); PG8_MMA(0, 1, At, B1); PG8_BAR; PG8_SCHED;
	s_setprio 1
	s_waitcnt lgkmcnt(0)
	v_mfma_f32_16x16x32_bf16 v[60:63], v[148:151], v[196:199], v[60:63]
	v_mfma_f32_16x16x32_bf16 v[56:59], v[156:159], v[196:199], v[56:59]
	v_mfma_f32_16x16x32_bf16 v[52:55], v[148:151], v[204:207], v[52:55]
	v_mfma_f32_16x16x32_bf16 v[48:51], v[156:159], v[204:207], v[48:51]
	v_mfma_f32_16x16x32_bf16 v[36:39], v[148:151], v[212:215], v[36:39]
	v_mfma_f32_16x16x32_bf16 v[32:35], v[156:159], v[212:215], v[32:35]
	v_mfma_f32_16x16x32_bf16 v[20:23], v[148:151], v[220:223], v[20:23]
	v_mfma_f32_16x16x32_bf16 v[16:19], v[156:159], v[220:223], v[16:19]
	v_mfma_f32_16x16x32_bf16 v[60:63], v[152:155], v[200:203], v[60:63]
	v_mfma_f32_16x16x32_bf16 v[56:59], v[162:165], v[200:203], v[56:59]
	v_mfma_f32_16x16x32_bf16 v[52:55], v[152:155], v[208:211], v[52:55]
	v_mfma_f32_16x16x32_bf16 v[48:51], v[162:165], v[208:211], v[48:51]
	v_mfma_f32_16x16x32_bf16 v[36:39], v[152:155], v[216:219], v[36:39]
	v_mfma_f32_16x16x32_bf16 v[32:35], v[162:165], v[216:219], v[32:35]
	v_mfma_f32_16x16x32_bf16 v[20:23], v[152:155], v[224:227], v[20:23]
	v_mfma_f32_16x16x32_bf16 v[16:19], v[162:165], v[224:227], v[16:19]
	v_mfma_f32_16x16x32_bf16 v[44:47], v[172:175], v[196:199], v[44:47]
	v_mfma_f32_16x16x32_bf16 v[40:43], v[188:191], v[196:199], v[40:43]
	v_mfma_f32_16x16x32_bf16 v[28:31], v[172:175], v[204:207], v[28:31]
	v_mfma_f32_16x16x32_bf16 v[24:27], v[188:191], v[204:207], v[24:27]
	v_mfma_f32_16x16x32_bf16 v[12:15], v[172:175], v[212:215], v[12:15]
	v_mfma_f32_16x16x32_bf16 v[8:11], v[188:191], v[212:215], v[8:11]
	v_mfma_f32_16x16x32_bf16 v[4:7], v[172:175], v[220:223], v[4:7]
	v_mfma_f32_16x16x32_bf16 v[0:3], v[188:191], v[220:223], v[0:3]
	v_mfma_f32_16x16x32_bf16 v[44:47], v[184:187], v[200:203], v[44:47]
	v_mfma_f32_16x16x32_bf16 v[40:43], v[192:195], v[200:203], v[40:43]
	v_mfma_f32_16x16x32_bf16 v[28:31], v[184:187], v[208:211], v[28:31]
	v_mfma_f32_16x16x32_bf16 v[24:27], v[192:195], v[208:211], v[24:27]
	v_mfma_f32_16x16x32_bf16 v[12:15], v[184:187], v[216:219], v[12:15]
	v_mfma_f32_16x16x32_bf16 v[8:11], v[192:195], v[216:219], v[8:11]
	v_mfma_f32_16x16x32_bf16 v[4:7], v[184:187], v[224:227], v[4:7]
	v_mfma_f32_16x16x32_bf16 v[0:3], v[192:195], v[224:227], v[0:3]
	s_setprio 0
	s_barrier
	v_add_u32_e32 v147, s21, v143
	ds_read_b128 v[148:151], v147
	ds_read_b128 v[152:155], v147 offset:1024
	ds_read_b128 v[156:159], v147 offset:2048
	ds_read_b128 v[162:165], v147 offset:3072
	v_add_u32_e32 v147, vcc_lo, v143
	ds_read_b128 v[172:175], v147
	ds_read_b128 v[184:187], v147 offset:1024
	ds_read_b128 v[188:191], v147 offset:2048
	ds_read_b128 v[192:195], v147 offset:3072
	s_mov_b32 m0, s80
	v_lshl_add_u64 v[234:235], s[58:59], 0, v[134:135]
	ds_read_b128 v[196:199], v146 offset:32768
	ds_read_b128 v[200:203], v146 offset:33792
	ds_read_b128 v[204:207], v146 offset:34816
	ds_read_b128 v[208:211], v146 offset:35840
	ds_read_b128 v[212:215], v146 offset:36864
	ds_read_b128 v[216:219], v146 offset:37888
	ds_read_b128 v[220:223], v146 offset:38912
	ds_read_b128 v[224:227], v146 offset:39936
	global_load_lds_dwordx4 v[234:235], off
	v_lshl_add_u64 v[234:235], s[58:59], 0, v[130:131]
	s_mov_b32 m0, s81
	s_nop 0
	global_load_lds_dwordx4 v[234:235], off
	s_waitcnt vmcnt(8)
	s_waitcnt lgkmcnt(0)
	s_barrier
	s_setprio 1
	s_waitcnt lgkmcnt(0)
	v_mfma_f32_16x16x32_bf16 v[124:127], v[148:151], v[196:199], v[124:127]
	v_mfma_f32_16x16x32_bf16 v[120:123], v[156:159], v[196:199], v[120:123]
	v_mfma_f32_16x16x32_bf16 v[116:119], v[148:151], v[204:207], v[116:119]
	v_mfma_f32_16x16x32_bf16 v[112:115], v[156:159], v[204:207], v[112:115]
	v_mfma_f32_16x16x32_bf16 v[100:103], v[148:151], v[212:215], v[100:103]
	v_mfma_f32_16x16x32_bf16 v[96:99], v[156:159], v[212:215], v[96:99]
	v_mfma_f32_16x16x32_bf16 v[84:87], v[148:151], v[220:223], v[84:87]
	v_mfma_f32_16x16x32_bf16 v[80:83], v[156:159], v[220:223], v[80:83]
	v_mfma_f32_16x16x32_bf16 v[124:127], v[152:155], v[200:203], v[124:127]
	v_mfma_f32_16x16x32_bf16 v[120:123], v[162:165], v[200:203], v[120:123]
	v_mfma_f32_16x16x32_bf16 v[116:119], v[152:155], v[208:211], v[116:119]
	v_mfma_f32_16x16x32_bf16 v[112:115], v[162:165], v[208:211], v[112:115]
	v_mfma_f32_16x16x32_bf16 v[100:103], v[152:155], v[216:219], v[100:103]
	v_mfma_f32_16x16x32_bf16 v[96:99], v[162:165], v[216:219], v[96:99]
	v_mfma_f32_16x16x32_bf16 v[84:87], v[152:155], v[224:227], v[84:87]
	v_mfma_f32_16x16x32_bf16 v[80:83], v[162:165], v[224:227], v[80:83]
	v_mfma_f32_16x16x32_bf16 v[108:111], v[172:175], v[196:199], v[108:111]
	v_mfma_f32_16x16x32_bf16 v[104:107], v[188:191], v[196:199], v[104:107]
	v_mfma_f32_16x16x32_bf16 v[92:95], v[172:175], v[204:207], v[92:95]
	v_mfma_f32_16x16x32_bf16 v[88:91], v[188:191], v[204:207], v[88:91]
	v_mfma_f32_16x16x32_bf16 v[76:79], v[172:175], v[212:215], v[76:79]
	v_mfma_f32_16x16x32_bf16 v[72:75], v[188:191], v[212:215], v[72:75]
	v_mfma_f32_16x16x32_bf16 v[68:71], v[172:175], v[220:223], v[68:71]
	v_mfma_f32_16x16x32_bf16 v[64:67], v[188:191], v[220:223], v[64:67]
	v_mfma_f32_16x16x32_bf16 v[108:111], v[184:187], v[200:203], v[108:111]
	v_mfma_f32_16x16x32_bf16 v[104:107], v[192:195], v[200:203], v[104:107]
	v_mfma_f32_16x16x32_bf16 v[92:95], v[184:187], v[208:211], v[92:95]
	v_mfma_f32_16x16x32_bf16 v[88:91], v[192:195], v[208:211], v[88:91]
	v_mfma_f32_16x16x32_bf16 v[76:79], v[184:187], v[216:219], v[76:79]
	v_mfma_f32_16x16x32_bf16 v[72:75], v[192:195], v[216:219], v[72:75]
	v_mfma_f32_16x16x32_bf16 v[68:71], v[184:187], v[224:227], v[68:71]
	v_mfma_f32_16x16x32_bf16 v[64:67], v[192:195], v[224:227], v[64:67]
	s_setprio 0
	s_barrier
; #define PG8_STAGE(bufoff, gbase, voff) do { _Pragma("unroll") for (int _i = 0; _i < 2; ++_i) \
;         __builtin_amdgcn_global_load_lds((const unsigned*)((const char*)(gbase) + (voff)[_i]), (LAS unsigned*)(lds + (bufoff) + ldsw + _i * 8192), 16, 0, 0); } while (0)
; #define PG8_LDA(dst, b, h) do { _Pragma("unroll") for (int m = 0; m < 4; ++m) _Pragma("unroll") for (int k = 0; k < 2; ++k) dst[m][k] = *(const LAS bf16x8*)(lds + PG8_SA(b, h) + aoff + m * 2048 + k * 1024); } while (0)
; #define PG8_MMA(ai, bj, At, Bt) do { __builtin_amdgcn_s_setprio(1); _Pragma("unroll") for (int m = 0; m < 4; ++m) _Pragma("unroll") for (int n = 0; n < 2; ++n) _Pragma("unroll") for (int k = 0; k < 2; ++k) \
;         acc[ai][bj][m][n] = __builtin_amdgcn_mfma_f32_16x16x32_bf16(Bt[n][k], At[m][k], acc[ai][bj][m][n], 0, 0, 0); __builtin_amdgcn_s_setprio(0); } while (0)
; #define PG8_WAIT_V(n) asm volatile("s_waitcnt vmcnt(" #n ")" ::: "memory")
; #define PG8_WAIT_L(n) asm volatile("s_waitcnt lgkmcnt(" #n ")" ::: "memory")
; #define PG8_BAR __builtin_amdgcn_s_barrier()
; #define PG8_SCHED __builtin_amdgcn_sched_barrier(0)
; template <class Epi>
; __device__ __forceinline__ void gemm_phase(LAS unsigned char* lds, const Gemm g, const StaticOrder& S, const Epi& E) {
;     ...
;             PG8_LDA(At, 1, 1); PG8_STAGE(PG8_SB(1, 0), b3, voffB); PG8_STAGE(PG8_SB(1, 1), b3 + hstepB, voffB); PG8_STAGE(PG8_SA(1, 0), a3, voffA);
;             PG8_WAIT_V(8); PG8_WAIT_L(0); PG8_BAR; PG8_MMA(1, 0, At, B0); PG8_MMA(1, 1, At, B1); PG8_BAR; PG8_SCHED;
;         }
;         if (wr == 0) PG8_BAR;
	s_mov_b32 m0, vcc_hi
	v_lshl_add_u64 v[166:167], v[166:167], 0, s[10:11]
	ds_read_b128 v[196:199], v146 offset:49152
	ds_read_b128 v[200:203], v146 offset:50176
	ds_read_b128 v[204:207], v146 offset:51200
	ds_read_b128 v[208:211], v146 offset:52224
	ds_read_b128 v[212:215], v146 offset:53248
	ds_read_b128 v[216:219], v146 offset:54272
	ds_read_b128 v[220:223], v146 offset:55296
	ds_read_b128 v[224:227], v146 offset:56320
	global_load_lds_dwordx4 v[166:167], off
	v_lshl_add_u64 v[166:167], v[228:229], 0, s[10:11]
	s_mov_b32 m0, s75
	s_nop 0
	global_load_lds_dwordx4 v[166:167], off
	v_lshl_add_u64 v[166:167], s[56:57], 0, v[132:133]
	s_mov_b32 m0, s74
	s_nop 0
	global_load_lds_dwordx4 v[166:167], off
	v_lshl_add_u64 v[166:167], s[56:57], 0, v[128:129]
	s_mov_b32 m0, s20
	s_nop 0
	global_load_lds_dwordx4 v[166:167], off
	v_lshl_add_u64 v[166:167], v[230:231], 0, s[10:11]
	s_mov_b32 m0, s82
	s_nop 0
	global_load_lds_dwordx4 v[166:167], off
	v_lshl_add_u64 v[166:167], v[232:233], 0, s[10:11]
	s_mov_b32 m0, s83
	s_nop 0
	global_load_lds_dwordx4 v[166:167], off
	s_waitcnt vmcnt(8)
	s_waitcnt lgkmcnt(0)
	s_barrier
	s_setprio 1
	s_waitcnt lgkmcnt(0)
	v_mfma_f32_16x16x32_bf16 v[60:63], v[148:151], v[196:199], v[60:63]
	v_mfma_f32_16x16x32_bf16 v[56:59], v[156:159], v[196:199], v[56:59]
	v_mfma_f32_16x16x32_bf16 v[52:55], v[148:151], v[204:207], v[52:55]
	v_mfma_f32_16x16x32_bf16 v[48:51], v[156:159], v[204:207], v[48:51]
	v_mfma_f32_16x16x32_bf16 v[36:39], v[148:151], v[212:215], v[36:39]
	v_mfma_f32_16x16x32_bf16 v[32:35], v[156:159], v[212:215], v[32:35]
	v_mfma_f32_16x16x32_bf16 v[20:23], v[148:151], v[220:223], v[20:23]
	v_mfma_f32_16x16x32_bf16 v[16:19], v[156:159], v[220:223], v[16:19]
	v_mfma_f32_16x16x32_bf16 v[60:63], v[152:155], v[200:203], v[60:63]
	v_mfma_f32_16x16x32_bf16 v[56:59], v[162:165], v[200:203], v[56:59]
	v_mfma_f32_16x16x32_bf16 v[52:55], v[152:155], v[208:211], v[52:55]
	v_mfma_f32_16x16x32_bf16 v[48:51], v[162:165], v[208:211], v[48:51]
	v_mfma_f32_16x16x32_bf16 v[36:39], v[152:155], v[216:219], v[36:39]
	v_mfma_f32_16x16x32_bf16 v[32:35], v[162:165], v[216:219], v[32:35]
	v_mfma_f32_16x16x32_bf16 v[20:23], v[152:155], v[224:227], v[20:23]
	v_mfma_f32_16x16x32_bf16 v[16:19], v[162:165], v[224:227], v[16:19]
	v_mfma_f32_16x16x32_bf16 v[44:47], v[172:175], v[196:199], v[44:47]
	v_mfma_f32_16x16x32_bf16 v[40:43], v[188:191], v[196:199], v[40:43]
	v_mfma_f32_16x16x32_bf16 v[28:31], v[172:175], v[204:207], v[28:31]
	v_mfma_f32_16x16x32_bf16 v[24:27], v[188:191], v[204:207], v[24:27]
	v_mfma_f32_16x16x32_bf16 v[12:15], v[172:175], v[212:215], v[12:15]
	v_mfma_f32_16x16x32_bf16 v[8:11], v[188:191], v[212:215], v[8:11]
	v_mfma_f32_16x16x32_bf16 v[4:7], v[172:175], v[220:223], v[4:7]
	v_mfma_f32_16x16x32_bf16 v[0:3], v[188:191], v[220:223], v[0:3]
	v_mfma_f32_16x16x32_bf16 v[44:47], v[184:187], v[200:203], v[44:47]
	v_mfma_f32_16x16x32_bf16 v[40:43], v[192:195], v[200:203], v[40:43]
	v_mfma_f32_16x16x32_bf16 v[28:31], v[184:187], v[208:211], v[28:31]
	v_mfma_f32_16x16x32_bf16 v[24:27], v[192:195], v[208:211], v[24:27]
	v_mfma_f32_16x16x32_bf16 v[12:15], v[184:187], v[216:219], v[12:15]
	v_mfma_f32_16x16x32_bf16 v[8:11], v[192:195], v[216:219], v[8:11]
	v_mfma_f32_16x16x32_bf16 v[4:7], v[184:187], v[224:227], v[4:7]
	v_mfma_f32_16x16x32_bf16 v[0:3], v[192:195], v[224:227], v[0:3]
	s_setprio 0
	s_barrier
	s_movk_i32 s58, 0x100
	s_andn2_b64 vcc, exec, s[52:53]
	s_mov_b64 s[56:57], -1
	s_mov_b64 s[52:53], 0
	s_cbranch_vccz .LBB0_625
	s_and_b64 vcc, exec, s[12:13]
	s_cbranch_vccz .LBB0_628
	s_barrier

; #define PG8_STAGE(bufoff, gbase, voff) do { _Pragma("unroll") for (int _i = 0; _i < 2; ++_i) \
;         __builtin_amdgcn_global_load_lds((const unsigned*)((const char*)(gbase) + (voff)[_i]), (LAS unsigned*)(lds + (bufoff) + ldsw + _i * 8192), 16, 0, 0); } while (0)
; #define PG8_LDA(dst, b, h) do { _Pragma("unroll") for (int m = 0; m < 4; ++m) _Pragma("unroll") for (int k = 0; k < 2; ++k) dst[m][k] = *(const LAS bf16x8*)(lds + PG8_SA(b, h) + aoff + m * 2048 + k * 1024); } while (0)
; #define PG8_LDB(dst, b, h) do { _Pragma("unroll") for (int n = 0; n < 2; ++n) _Pragma("unroll") for (int k = 0; k < 2; ++k) dst[n][k] = *(const LAS bf16x8*)(lds + PG8_SB(b, h) + boff + n * 2048 + k * 1024); } while (0)
; #define PG8_MMA(ai, bj, At, Bt) do { __builtin_amdgcn_s_setprio(1); _Pragma("unroll") for (int m = 0; m < 4; ++m) _Pragma("unroll") for (int n = 0; n < 2; ++n) _Pragma("unroll") for (int k = 0; k < 2; ++k) \
;         acc[ai][bj][m][n] = __builtin_amdgcn_mfma_f32_16x16x32_bf16(Bt[n][k], At[m][k], acc[ai][bj][m][n], 0, 0, 0); __builtin_amdgcn_s_setprio(0); } while (0)
; #define PG8_WAIT_V(n) asm volatile("s_waitcnt vmcnt(" #n ")" ::: "memory")
; #define PG8_WAIT_L(n) asm volatile("s_waitcnt lgkmcnt(" #n ")" ::: "memory")
; #define PG8_BAR __builtin_amdgcn_s_barrier()
; #define PG8_SCHED __builtin_amdgcn_sched_barrier(0)
; template <class Epi>
; __device__ __forceinline__ void gemm_phase(LAS unsigned char* lds, const Gemm g, const StaticOrder& S, const Epi& E) {
;     ...
;         for (int t = 0; t < nt; t += 2) {
;             const bool last = (t == nt - 2);
;             const char* a1 = cA + (size_t)(t + 1) * kstep;
;             const char* a2 = last ? nA : cA + (size_t)(t + 2) * kstep; const char* b2 = last ? nB : cB + (size_t)(t + 2) * kstep;
;             const char* a3 = a2 + kstep; const char* b3 = b2 + kstep;
;             PG8_LDB(B0, 0, 0); PG8_LDB(B1, 0, 1); PG8_SCHED; PG8_LDA(At, 0, 0); PG8_STAGE(PG8_SA(1, 1), a1 + hstepA, voffA);
;             PG8_WAIT_V(8); PG8_WAIT_L(0); PG8_BAR; PG8_MMA(0, 0, At, B0); PG8_MMA(0, 1, At, B1); PG8_BAR; PG8_SCHED;
;             PG8_LDA(At, 0, 1); PG8_STAGE(PG8_SB(0, 0), b2, voffB); PG8_STAGE(PG8_SB(0, 1), b2 + hstepB, voffB); PG8_STAGE(PG8_SA(0, 0), a2, voffA);
;             PG8_WAIT_V(8); PG8_WAIT_L(0); PG8_BAR; PG8_MMA(1, 0, At, B0); PG8_MMA(1, 1, At, B1); PG8_BAR; PG8_SCHED;
.LBB0_905:
	ds_read_b128 v[60:63], v248
	ds_read_b128 v[64:67], v248 offset:1024
	ds_read_b128 v[68:71], v248 offset:2048
	ds_read_b128 v[72:75], v248 offset:3072
	ds_read_b128 v[76:79], v249
	ds_read_b128 v[80:83], v249 offset:1024
	ds_read_b128 v[84:87], v249 offset:2048
	ds_read_b128 v[88:91], v249 offset:3072
	s_add_u32 s64, s62, 0xfffc0080
	s_addc_u32 s65, s63, -1
	s_cmp_eq_u32 s81, 12
	s_cselect_b32 s69, s41, s65
	s_cselect_b32 s68, s46, s64
	s_cselect_b32 s65, s39, s80
	s_cselect_b32 s64, s47, s59
	v_lshl_add_u64 v[220:221], s[62:63], 0, v[200:201]
	s_add_i32 m0, s25, 0xc000
	ds_read_b128 v[92:95], v250
	ds_read_b128 v[96:99], v250 offset:1024
	ds_read_b128 v[100:103], v250 offset:2048
	ds_read_b128 v[108:111], v250 offset:3072
	ds_read_b128 v[204:207], v250 offset:4096
	ds_read_b128 v[208:211], v250 offset:5120
	ds_read_b128 v[212:215], v250 offset:6144
	ds_read_b128 v[216:219], v250 offset:7168
	global_load_lds_dwordx4 v[220:221], off
	v_lshl_add_u64 v[220:221], s[62:63], 0, v[202:203]
	s_add_i32 m0, s25, 0xe000
	s_nop 0
	global_load_lds_dwordx4 v[220:221], off
	s_waitcnt vmcnt(8)
	s_waitcnt lgkmcnt(0)
	s_barrier
	s_setprio 1
	s_waitcnt lgkmcnt(0)
	v_mfma_f32_16x16x32_bf16 v[172:175], v[60:63], v[92:95], v[172:175]
	v_mfma_f32_16x16x32_bf16 v[168:171], v[68:71], v[92:95], v[168:171]
	v_mfma_f32_16x16x32_bf16 v[156:159], v[60:63], v[100:103], v[156:159]
	v_mfma_f32_16x16x32_bf16 v[152:155], v[68:71], v[100:103], v[152:155]
	v_mfma_f32_16x16x32_bf16 v[140:143], v[60:63], v[204:207], v[140:143]
	v_mfma_f32_16x16x32_bf16 v[136:139], v[68:71], v[204:207], v[136:139]
	v_mfma_f32_16x16x32_bf16 v[124:127], v[60:63], v[212:215], v[124:127]
	v_mfma_f32_16x16x32_bf16 v[120:123], v[68:71], v[212:215], v[120:123]
	v_mfma_f32_16x16x32_bf16 v[172:175], v[64:67], v[96:99], v[172:175]
	v_mfma_f32_16x16x32_bf16 v[168:171], v[72:75], v[96:99], v[168:171]
	v_mfma_f32_16x16x32_bf16 v[156:159], v[64:67], v[108:111], v[156:159]
	v_mfma_f32_16x16x32_bf16 v[152:155], v[72:75], v[108:111], v[152:155]
	v_mfma_f32_16x16x32_bf16 v[140:143], v[64:67], v[208:211], v[140:143]
	v_mfma_f32_16x16x32_bf16 v[136:139], v[72:75], v[208:211], v[136:139]
	v_mfma_f32_16x16x32_bf16 v[124:127], v[64:67], v[216:219], v[124:127]
	v_mfma_f32_16x16x32_bf16 v[120:123], v[72:75], v[216:219], v[120:123]
	v_mfma_f32_16x16x32_bf16 v[164:167], v[76:79], v[92:95], v[164:167]
	v_mfma_f32_16x16x32_bf16 v[92:95], v[84:87], v[92:95], v[160:163]
	v_mfma_f32_16x16x32_bf16 v[164:167], v[80:83], v[96:99], v[164:167]
	v_mfma_f32_16x16x32_bf16 v[92:95], v[88:91], v[96:99], v[92:95]
	v_mfma_f32_16x16x32_bf16 v[96:99], v[76:79], v[100:103], v[148:151]
	v_mfma_f32_16x16x32_bf16 v[100:103], v[84:87], v[100:103], v[144:147]
	v_mfma_f32_16x16x32_bf16 v[128:131], v[84:87], v[204:207], v[128:131]
	v_mfma_f32_16x16x32_bf16 v[116:119], v[76:79], v[212:215], v[116:119]
	v_mfma_f32_16x16x32_bf16 v[112:115], v[84:87], v[212:215], v[112:115]
	v_mfma_f32_16x16x32_bf16 v[96:99], v[80:83], v[108:111], v[96:99]
	v_mfma_f32_16x16x32_bf16 v[100:103], v[88:91], v[108:111], v[100:103]
	v_mfma_f32_16x16x32_bf16 v[108:111], v[76:79], v[204:207], v[132:135]
	v_mfma_f32_16x16x32_bf16 v[128:131], v[88:91], v[208:211], v[128:131]
	v_mfma_f32_16x16x32_bf16 v[116:119], v[80:83], v[216:219], v[116:119]
	v_mfma_f32_16x16x32_bf16 v[112:115], v[88:91], v[216:219], v[112:115]
	v_mfma_f32_16x16x32_bf16 v[108:111], v[80:83], v[208:211], v[108:111]
	s_setprio 0
	s_barrier
	s_add_i32 s74, s78, s3
	v_lshl_add_u64 v[228:229], s[64:65], 0, v[194:195]
	s_mov_b32 m0, s74
	ds_read_b128 v[132:135], v250 offset:16384
	ds_read_b128 v[144:147], v250 offset:17408
	ds_read_b128 v[148:151], v250 offset:18432
	ds_read_b128 v[160:163], v250 offset:19456
	ds_read_b128 v[204:207], v250 offset:20480
	ds_read_b128 v[208:211], v250 offset:21504
	ds_read_b128 v[212:215], v250 offset:22528
	ds_read_b128 v[216:219], v250 offset:23552
	global_load_lds_dwordx4 v[228:229], off
	s_add_i32 m0, s74, 0x2000
	s_add_u32 s74, s64, 0x40000
	v_lshl_add_u64 v[230:231], s[64:65], 0, v[196:197]
	s_addc_u32 s75, s65, 0
	s_add_i32 s82, s79, s3
	global_load_lds_dwordx4 v[230:231], off
	v_lshl_add_u64 v[220:221], s[74:75], 0, v[194:195]
	s_mov_b32 m0, s82
	v_lshl_add_u64 v[232:233], s[68:69], 0, v[194:195]
	global_load_lds_dwordx4 v[220:221], off
	v_lshl_add_u64 v[220:221], s[74:75], 0, v[196:197]
	s_add_i32 m0, s82, 0x2000
	v_lshl_add_u64 v[234:235], s[68:69], 0, v[196:197]
	global_load_lds_dwordx4 v[220:221], off
	s_mov_b32 m0, s25
	s_nop 0
	global_load_lds_dwordx4 v[232:233], off
	s_mov_b32 m0, s33
	s_nop 0
	global_load_lds_dwordx4 v[234:235], off
	s_waitcnt vmcnt(8)
	s_waitcnt lgkmcnt(0)
	s_barrier
; #define PG8_STAGE(bufoff, gbase, voff) do { _Pragma("unroll") for (int _i = 0; _i < 2; ++_i) \
;         __builtin_amdgcn_global_load_lds((const unsigned*)((const char*)(gbase) + (voff)[_i]), (LAS unsigned*)(lds + (bufoff) + ldsw + _i * 8192), 16, 0, 0); } while (0)
; #define PG8_LDA(dst, b, h) do { _Pragma("unroll") for (int m = 0; m < 4; ++m) _Pragma("unroll") for (int k = 0; k < 2; ++k) dst[m][k] = *(const LAS bf16x8*)(lds + PG8_SA(b, h) + aoff + m * 2048 + k * 1024); } while (0)
; #define PG8_LDB(dst, b, h) do { _Pragma("unroll") for (int n = 0; n < 2; ++n) _Pragma("unroll") for (int k = 0; k < 2; ++k) dst[n][k] = *(const LAS bf16x8*)(lds + PG8_SB(b, h) + boff + n * 2048 + k * 1024); } while (0)
; #define PG8_MMA(ai, bj, At, Bt) do { __builtin_amdgcn_s_setprio(1); _Pragma("unroll") for (int m = 0; m < 4; ++m) _Pragma("unroll") for (int n = 0; n < 2; ++n) _Pragma("unroll") for (int k = 0; k < 2; ++k) \
;         acc[ai][bj][m][n] = __builtin_amdgcn_mfma_f32_16x16x32_bf16(Bt[n][k], At[m][k], acc[ai][bj][m][n], 0, 0, 0); __builtin_amdgcn_s_setprio(0); } while (0)
; #define PG8_WAIT_V(n) asm volatile("s_waitcnt vmcnt(" #n ")" ::: "memory")
; #define PG8_WAIT_L(n) asm volatile("s_waitcnt lgkmcnt(" #n ")" ::: "memory")
; #define PG8_BAR __builtin_amdgcn_s_barrier()
; #define PG8_SCHED __builtin_amdgcn_sched_barrier(0)
; template <class Epi>
; __device__ __forceinline__ void gemm_phase(LAS unsigned char* lds, const Gemm g, const StaticOrder& S, const Epi& E) {
;     ...
;             PG8_WAIT_V(8); PG8_WAIT_L(0); PG8_BAR; PG8_MMA(1, 0, At, B0); PG8_MMA(1, 1, At, B1); PG8_BAR; PG8_SCHED;
;             PG8_LDB(B0, 1, 0); PG8_LDB(B1, 1, 1); PG8_SCHED; PG8_LDA(At, 1, 0); PG8_STAGE(PG8_SA(0, 1), a2 + hstepA, voffA);
;             PG8_WAIT_V(8); PG8_WAIT_L(0); PG8_BAR; PG8_MMA(0, 0, At, B0); PG8_MMA(0, 1, At, B1); PG8_BAR; PG8_SCHED;
	s_setprio 1
	s_waitcnt lgkmcnt(0)
	v_mfma_f32_16x16x32_bf16 v[104:107], v[60:63], v[132:135], v[104:107]
	v_mfma_f32_16x16x32_bf16 v[56:59], v[68:71], v[132:135], v[56:59]
	v_mfma_f32_16x16x32_bf16 v[44:47], v[60:63], v[148:151], v[44:47]
	v_mfma_f32_16x16x32_bf16 v[40:43], v[68:71], v[148:151], v[40:43]
	v_mfma_f32_16x16x32_bf16 v[28:31], v[60:63], v[204:207], v[28:31]
	v_mfma_f32_16x16x32_bf16 v[24:27], v[68:71], v[204:207], v[24:27]
	v_mfma_f32_16x16x32_bf16 v[12:15], v[60:63], v[212:215], v[12:15]
	v_mfma_f32_16x16x32_bf16 v[8:11], v[68:71], v[212:215], v[8:11]
	v_mfma_f32_16x16x32_bf16 v[104:107], v[64:67], v[144:147], v[104:107]
	v_mfma_f32_16x16x32_bf16 v[56:59], v[72:75], v[144:147], v[56:59]
	v_mfma_f32_16x16x32_bf16 v[44:47], v[64:67], v[160:163], v[44:47]
	v_mfma_f32_16x16x32_bf16 v[40:43], v[72:75], v[160:163], v[40:43]
	v_mfma_f32_16x16x32_bf16 v[28:31], v[64:67], v[208:211], v[28:31]
	v_mfma_f32_16x16x32_bf16 v[24:27], v[72:75], v[208:211], v[24:27]
	v_mfma_f32_16x16x32_bf16 v[12:15], v[64:67], v[216:219], v[12:15]
	v_mfma_f32_16x16x32_bf16 v[8:11], v[72:75], v[216:219], v[8:11]
	v_mfma_f32_16x16x32_bf16 v[52:55], v[76:79], v[132:135], v[52:55]
	v_mfma_f32_16x16x32_bf16 v[48:51], v[84:87], v[132:135], v[48:51]
	v_mfma_f32_16x16x32_bf16 v[36:39], v[76:79], v[148:151], v[36:39]
	v_mfma_f32_16x16x32_bf16 v[32:35], v[84:87], v[148:151], v[32:35]
	v_mfma_f32_16x16x32_bf16 v[20:23], v[76:79], v[204:207], v[20:23]
	v_mfma_f32_16x16x32_bf16 v[16:19], v[84:87], v[204:207], v[16:19]
	v_mfma_f32_16x16x32_bf16 v[4:7], v[76:79], v[212:215], v[4:7]
	v_mfma_f32_16x16x32_bf16 v[0:3], v[84:87], v[212:215], v[0:3]
	v_mfma_f32_16x16x32_bf16 v[52:55], v[80:83], v[144:147], v[52:55]
	v_mfma_f32_16x16x32_bf16 v[48:51], v[88:91], v[144:147], v[48:51]
	v_mfma_f32_16x16x32_bf16 v[36:39], v[80:83], v[160:163], v[36:39]
	v_mfma_f32_16x16x32_bf16 v[32:35], v[88:91], v[160:163], v[32:35]
	v_mfma_f32_16x16x32_bf16 v[20:23], v[80:83], v[208:211], v[20:23]
	v_mfma_f32_16x16x32_bf16 v[16:19], v[88:91], v[208:211], v[16:19]
	v_mfma_f32_16x16x32_bf16 v[4:7], v[80:83], v[216:219], v[4:7]
	v_mfma_f32_16x16x32_bf16 v[0:3], v[88:91], v[216:219], v[0:3]
	s_setprio 0
	s_barrier
	s_add_i32 s74, 0, 0x18000
	s_add_i32 s75, 0, 0x1c000
	v_add_u32_e32 v72, s74, v193
	v_add_u32_e32 v88, s75, v193
	ds_read_b128 v[60:63], v72
	ds_read_b128 v[64:67], v72 offset:1024
	ds_read_b128 v[68:71], v72 offset:2048
	ds_read_b128 v[72:75], v72 offset:3072
	ds_read_b128 v[76:79], v88
	ds_read_b128 v[80:83], v88 offset:1024
	ds_read_b128 v[84:87], v88 offset:2048
	ds_read_b128 v[88:91], v88 offset:3072
	s_add_u32 s68, s68, 0x40000
	s_addc_u32 s69, s69, 0
	s_mov_b32 m0, s61
	v_lshl_add_u64 v[148:149], s[68:69], 0, v[194:195]
	ds_read_b128 v[132:135], v250 offset:32768
	ds_read_b128 v[144:147], v250 offset:33792
	ds_read_b128 v[204:207], v250 offset:34816
	ds_read_b128 v[208:211], v250 offset:35840
	ds_read_b128 v[212:215], v250 offset:36864
	ds_read_b128 v[216:219], v250 offset:37888
	ds_read_b128 v[220:223], v250 offset:38912
	ds_read_b128 v[224:227], v250 offset:39936
	global_load_lds_dwordx4 v[148:149], off
	v_lshl_add_u64 v[148:149], s[68:69], 0, v[196:197]
	s_mov_b32 m0, s67
	s_nop 0
	global_load_lds_dwordx4 v[148:149], off
	s_waitcnt vmcnt(8)
	s_waitcnt lgkmcnt(0)
	s_barrier
	s_setprio 1
	s_waitcnt lgkmcnt(0)
	v_mfma_f32_16x16x32_bf16 v[148:151], v[60:63], v[132:135], v[172:175]
	v_mfma_f32_16x16x32_bf16 v[172:175], v[64:67], v[144:147], v[148:151]
	v_mfma_f32_16x16x32_bf16 v[148:151], v[68:71], v[132:135], v[168:171]
	v_mfma_f32_16x16x32_bf16 v[168:171], v[72:75], v[144:147], v[148:151]
	v_mfma_f32_16x16x32_bf16 v[148:151], v[60:63], v[204:207], v[156:159]
	v_mfma_f32_16x16x32_bf16 v[156:159], v[64:67], v[208:211], v[148:151]
	v_mfma_f32_16x16x32_bf16 v[148:151], v[68:71], v[204:207], v[152:155]
	v_mfma_f32_16x16x32_bf16 v[140:143], v[60:63], v[212:215], v[140:143]
	v_mfma_f32_16x16x32_bf16 v[136:139], v[68:71], v[212:215], v[136:139]
	v_mfma_f32_16x16x32_bf16 v[124:127], v[60:63], v[220:223], v[124:127]
	v_mfma_f32_16x16x32_bf16 v[120:123], v[68:71], v[220:223], v[120:123]
	v_mfma_f32_16x16x32_bf16 v[152:155], v[72:75], v[208:211], v[148:151]
	v_mfma_f32_16x16x32_bf16 v[140:143], v[64:67], v[216:219], v[140:143]
	v_mfma_f32_16x16x32_bf16 v[136:139], v[72:75], v[216:219], v[136:139]
	v_mfma_f32_16x16x32_bf16 v[124:127], v[64:67], v[224:227], v[124:127]
	v_mfma_f32_16x16x32_bf16 v[120:123], v[72:75], v[224:227], v[120:123]
	v_mfma_f32_16x16x32_bf16 v[92:95], v[84:87], v[132:135], v[92:95]
	v_mfma_f32_16x16x32_bf16 v[148:151], v[76:79], v[132:135], v[164:167]
	v_mfma_f32_16x16x32_bf16 v[160:163], v[88:91], v[144:147], v[92:95]
	v_mfma_f32_16x16x32_bf16 v[92:95], v[76:79], v[204:207], v[96:99]
	v_mfma_f32_16x16x32_bf16 v[164:167], v[80:83], v[144:147], v[148:151]
	v_mfma_f32_16x16x32_bf16 v[148:151], v[80:83], v[208:211], v[92:95]
	v_mfma_f32_16x16x32_bf16 v[92:95], v[84:87], v[204:207], v[100:103]
	v_mfma_f32_16x16x32_bf16 v[144:147], v[88:91], v[208:211], v[92:95]
	v_mfma_f32_16x16x32_bf16 v[92:95], v[76:79], v[212:215], v[108:111]
	v_mfma_f32_16x16x32_bf16 v[132:135], v[80:83], v[216:219], v[92:95]
	v_mfma_f32_16x16x32_bf16 v[92:95], v[84:87], v[212:215], v[128:131]
	v_mfma_f32_16x16x32_bf16 v[128:131], v[88:91], v[216:219], v[92:95]
	v_mfma_f32_16x16x32_bf16 v[92:95], v[76:79], v[220:223], v[116:119]
	v_mfma_f32_16x16x32_bf16 v[116:119], v[80:83], v[224:227], v[92:95]
	v_mfma_f32_16x16x32_bf16 v[92:95], v[84:87], v[220:223], v[112:115]
	v_mfma_f32_16x16x32_bf16 v[112:115], v[88:91], v[224:227], v[92:95]
	s_setprio 0
	s_barrier
; #define PG8_STAGE(bufoff, gbase, voff) do { _Pragma("unroll") for (int _i = 0; _i < 2; ++_i) \
;         __builtin_amdgcn_global_load_lds((const unsigned*)((const char*)(gbase) + (voff)[_i]), (LAS unsigned*)(lds + (bufoff) + ldsw + _i * 8192), 16, 0, 0); } while (0)
; #define PG8_LDA(dst, b, h) do { _Pragma("unroll") for (int m = 0; m < 4; ++m) _Pragma("unroll") for (int k = 0; k < 2; ++k) dst[m][k] = *(const LAS bf16x8*)(lds + PG8_SA(b, h) + aoff + m * 2048 + k * 1024); } while (0)
; #define PG8_MMA(ai, bj, At, Bt) do { __builtin_amdgcn_s_setprio(1); _Pragma("unroll") for (int m = 0; m < 4; ++m) _Pragma("unroll") for (int n = 0; n < 2; ++n) _Pragma("unroll") for (int k = 0; k < 2; ++k) \
;         acc[ai][bj][m][n] = __builtin_amdgcn_mfma_f32_16x16x32_bf16(Bt[n][k], At[m][k], acc[ai][bj][m][n], 0, 0, 0); __builtin_amdgcn_s_setprio(0); } while (0)
; #define PG8_WAIT_V(n) asm volatile("s_waitcnt vmcnt(" #n ")" ::: "memory")
; #define PG8_WAIT_L(n) asm volatile("s_waitcnt lgkmcnt(" #n ")" ::: "memory")
; #define PG8_BAR __builtin_amdgcn_s_barrier()
; #define PG8_SCHED __builtin_amdgcn_sched_barrier(0)
; template <class Epi>
; __device__ __forceinline__ void gemm_phase(LAS unsigned char* lds, const Gemm g, const StaticOrder& S, const Epi& E) {
;     ...
;             PG8_LDA(At, 1, 1); PG8_STAGE(PG8_SB(1, 0), b3, voffB); PG8_STAGE(PG8_SB(1, 1), b3 + hstepB, voffB); PG8_STAGE(PG8_SA(1, 0), a3, voffA);
;             PG8_WAIT_V(8); PG8_WAIT_L(0); PG8_BAR; PG8_MMA(1, 0, At, B0); PG8_MMA(1, 1, At, B1); PG8_BAR; PG8_SCHED;
;         }
;         if (wr == 0) PG8_BAR;
	s_add_i32 s68, s74, s3
	v_lshl_add_u64 v[220:221], v[228:229], 0, s[34:35]
	s_mov_b32 m0, s68
	s_nop 1
	ds_read_b128 v[92:95], v250 offset:49152
	ds_read_b128 v[96:99], v250 offset:50176
	ds_read_b128 v[100:103], v250 offset:51200
	ds_read_b128 v[108:111], v250 offset:52224
	ds_read_b128 v[204:207], v250 offset:53248
	ds_read_b128 v[208:211], v250 offset:54272
	ds_read_b128 v[212:215], v250 offset:55296
	ds_read_b128 v[216:219], v250 offset:56320
	global_load_lds_dwordx4 v[220:221], off
	s_add_i32 m0, s68, 0x2000
	s_add_u32 s64, s64, 0x40080
	v_lshl_add_u64 v[220:221], v[230:231], 0, s[34:35]
	s_addc_u32 s65, s65, 0
	s_add_i32 s68, s75, s3
	global_load_lds_dwordx4 v[220:221], off
	v_lshl_add_u64 v[220:221], s[64:65], 0, v[194:195]
	s_mov_b32 m0, s68
	s_nop 0
	global_load_lds_dwordx4 v[220:221], off
	v_lshl_add_u64 v[220:221], s[64:65], 0, v[196:197]
	s_add_i32 m0, s68, 0x2000
	s_nop 0
	global_load_lds_dwordx4 v[220:221], off
	v_lshl_add_u64 v[220:221], v[232:233], 0, s[34:35]
	s_mov_b32 m0, s71
	s_nop 0
	global_load_lds_dwordx4 v[220:221], off
	v_lshl_add_u64 v[220:221], v[234:235], 0, s[34:35]
	s_mov_b32 m0, s72
	s_nop 0
	global_load_lds_dwordx4 v[220:221], off
	s_waitcnt vmcnt(8)
	s_waitcnt lgkmcnt(0)
	s_barrier
	s_setprio 1
	s_waitcnt lgkmcnt(0)
	v_mfma_f32_16x16x32_bf16 v[104:107], v[60:63], v[92:95], v[104:107]
	v_mfma_f32_16x16x32_bf16 v[56:59], v[68:71], v[92:95], v[56:59]
	v_mfma_f32_16x16x32_bf16 v[44:47], v[60:63], v[100:103], v[44:47]
	v_mfma_f32_16x16x32_bf16 v[40:43], v[68:71], v[100:103], v[40:43]
	v_mfma_f32_16x16x32_bf16 v[28:31], v[60:63], v[204:207], v[28:31]
	v_mfma_f32_16x16x32_bf16 v[24:27], v[68:71], v[204:207], v[24:27]
	v_mfma_f32_16x16x32_bf16 v[12:15], v[60:63], v[212:215], v[12:15]
	v_mfma_f32_16x16x32_bf16 v[8:11], v[68:71], v[212:215], v[8:11]
	v_mfma_f32_16x16x32_bf16 v[104:107], v[64:67], v[96:99], v[104:107]
	v_mfma_f32_16x16x32_bf16 v[56:59], v[72:75], v[96:99], v[56:59]
	v_mfma_f32_16x16x32_bf16 v[44:47], v[64:67], v[108:111], v[44:47]
	v_mfma_f32_16x16x32_bf16 v[40:43], v[72:75], v[108:111], v[40:43]
	v_mfma_f32_16x16x32_bf16 v[28:31], v[64:67], v[208:211], v[28:31]
	v_mfma_f32_16x16x32_bf16 v[24:27], v[72:75], v[208:211], v[24:27]
	v_mfma_f32_16x16x32_bf16 v[12:15], v[64:67], v[216:219], v[12:15]
	v_mfma_f32_16x16x32_bf16 v[8:11], v[72:75], v[216:219], v[8:11]
	v_mfma_f32_16x16x32_bf16 v[52:55], v[76:79], v[92:95], v[52:55]
	v_mfma_f32_16x16x32_bf16 v[48:51], v[84:87], v[92:95], v[48:51]
	v_mfma_f32_16x16x32_bf16 v[36:39], v[76:79], v[100:103], v[36:39]
	v_mfma_f32_16x16x32_bf16 v[32:35], v[84:87], v[100:103], v[32:35]
	v_mfma_f32_16x16x32_bf16 v[20:23], v[76:79], v[204:207], v[20:23]
	v_mfma_f32_16x16x32_bf16 v[16:19], v[84:87], v[204:207], v[16:19]
	v_mfma_f32_16x16x32_bf16 v[4:7], v[76:79], v[212:215], v[4:7]
	v_mfma_f32_16x16x32_bf16 v[0:3], v[84:87], v[212:215], v[0:3]
	v_mfma_f32_16x16x32_bf16 v[52:55], v[80:83], v[96:99], v[52:55]
	v_mfma_f32_16x16x32_bf16 v[48:51], v[88:91], v[96:99], v[48:51]
	v_mfma_f32_16x16x32_bf16 v[36:39], v[80:83], v[108:111], v[36:39]
	v_mfma_f32_16x16x32_bf16 v[32:35], v[88:91], v[108:111], v[32:35]
	v_mfma_f32_16x16x32_bf16 v[20:23], v[80:83], v[208:211], v[20:23]
	v_mfma_f32_16x16x32_bf16 v[16:19], v[88:91], v[208:211], v[16:19]
	v_mfma_f32_16x16x32_bf16 v[4:7], v[80:83], v[216:219], v[4:7]
	v_mfma_f32_16x16x32_bf16 v[0:3], v[88:91], v[216:219], v[0:3]
	s_setprio 0
	s_barrier
	s_add_i32 s81, s81, 2
	s_add_u32 s62, s62, 0x100
	s_addc_u32 s63, s63, 0
	s_add_u32 s59, s59, 0x100
	s_addc_u32 s80, s80, 0
	s_cmp_gt_u32 s81, 13
	s_cbranch_scc0 .LBB0_905
	s_and_b64 vcc, exec, s[36:37]
	s_cbranch_vccz .LBB0_908
	s_barrier

; #define PG8_STAGE(bufoff, gbase, voff) do { _Pragma("unroll") for (int _i = 0; _i < 2; ++_i) \
;         __builtin_amdgcn_global_load_lds((const unsigned*)((const char*)(gbase) + (voff)[_i]), (LAS unsigned*)(lds + (bufoff) + ldsw + _i * 8192), 16, 0, 0); } while (0)
; #define PG8_LDA(dst, b, h) do { _Pragma("unroll") for (int m = 0; m < 4; ++m) _Pragma("unroll") for (int k = 0; k < 2; ++k) dst[m][k] = *(const LAS bf16x8*)(lds + PG8_SA(b, h) + aoff + m * 2048 + k * 1024); } while (0)
; #define PG8_LDB(dst, b, h) do { _Pragma("unroll") for (int n = 0; n < 2; ++n) _Pragma("unroll") for (int k = 0; k < 2; ++k) dst[n][k] = *(const LAS bf16x8*)(lds + PG8_SB(b, h) + boff + n * 2048 + k * 1024); } while (0)
; #define PG8_MMA(ai, bj, At, Bt) do { __builtin_amdgcn_s_setprio(1); _Pragma("unroll") for (int m = 0; m < 4; ++m) _Pragma("unroll") for (int n = 0; n < 2; ++n) _Pragma("unroll") for (int k = 0; k < 2; ++k) \
;         acc[ai][bj][m][n] = __builtin_amdgcn_mfma_f32_16x16x32_bf16(Bt[n][k], At[m][k], acc[ai][bj][m][n], 0, 0, 0); __builtin_amdgcn_s_setprio(0); } while (0)
; #define PG8_WAIT_V(n) asm volatile("s_waitcnt vmcnt(" #n ")" ::: "memory")
; #define PG8_WAIT_L(n) asm volatile("s_waitcnt lgkmcnt(" #n ")" ::: "memory")
; #define PG8_BAR __builtin_amdgcn_s_barrier()
; #define PG8_SCHED __builtin_amdgcn_sched_barrier(0)
; template <class Epi>
; __device__ __forceinline__ void gemm_phase(LAS unsigned char* lds, const Gemm g, const StaticOrder& S, const Epi& E) {
;     ...
;         for (int t = 0; t < nt; t += 2) {
;             const bool last = (t == nt - 2);
;             const char* a1 = cA + (size_t)(t + 1) * kstep;
;             const char* a2 = last ? nA : cA + (size_t)(t + 2) * kstep; const char* b2 = last ? nB : cB + (size_t)(t + 2) * kstep;
;             const char* a3 = a2 + kstep; const char* b3 = b2 + kstep;
;             PG8_LDB(B0, 0, 0); PG8_LDB(B1, 0, 1); PG8_SCHED; PG8_LDA(At, 0, 0); PG8_STAGE(PG8_SA(1, 1), a1 + hstepA, voffA);
;             PG8_WAIT_V(8); PG8_WAIT_L(0); PG8_BAR; PG8_MMA(0, 0, At, B0); PG8_MMA(0, 1, At, B1); PG8_BAR; PG8_SCHED;
;             PG8_LDA(At, 0, 1); PG8_STAGE(PG8_SB(0, 0), b2, voffB); PG8_STAGE(PG8_SB(0, 1), b2 + hstepB, voffB); PG8_STAGE(PG8_SA(0, 0), a2, voffA);
;             PG8_WAIT_V(8); PG8_WAIT_L(0); PG8_BAR; PG8_MMA(1, 0, At, B0); PG8_MMA(1, 1, At, B1); PG8_BAR; PG8_SCHED;
.LBB0_997:
	ds_read_b128 v[128:131], v193
	ds_read_b128 v[132:135], v193 offset:1024
	ds_read_b128 v[136:139], v193 offset:2048
	ds_read_b128 v[140:143], v193 offset:3072
	ds_read_b128 v[164:167], v194
	ds_read_b128 v[168:171], v194 offset:1024
	ds_read_b128 v[172:175], v194 offset:2048
	ds_read_b128 v[198:201], v194 offset:3072
	s_add_u32 s52, s40, 0xfffc0080
	s_addc_u32 s53, s41, -1
	s_cmp_eq_u32 s77, 12
	s_cselect_b32 s57, s35, s53
	s_cselect_b32 s56, s46, s52
	s_cselect_b32 s53, s23, s76
	s_cselect_b32 s52, s47, s75
	v_lshl_add_u64 v[234:235], s[40:41], 0, v[156:157]
	s_add_i32 m0, s60, 0xc000
	ds_read_b128 v[202:205], v195
	ds_read_b128 v[206:209], v195 offset:1024
	ds_read_b128 v[210:213], v195 offset:2048
	ds_read_b128 v[214:217], v195 offset:3072
	ds_read_b128 v[218:221], v195 offset:4096
	ds_read_b128 v[222:225], v195 offset:5120
	ds_read_b128 v[226:229], v195 offset:6144
	ds_read_b128 v[230:233], v195 offset:7168
	global_load_lds_dwordx4 v[234:235], off
	v_lshl_add_u64 v[234:235], s[40:41], 0, v[158:159]
	s_add_i32 m0, s60, 0xe000
	s_nop 0
	global_load_lds_dwordx4 v[234:235], off
	s_waitcnt vmcnt(8)
	s_waitcnt lgkmcnt(0)
	s_barrier
	s_setprio 1
	s_waitcnt lgkmcnt(0)
	v_mfma_f32_16x16x32_bf16 v[124:127], v[128:131], v[202:205], v[124:127]
	v_mfma_f32_16x16x32_bf16 v[120:123], v[136:139], v[202:205], v[120:123]
	v_mfma_f32_16x16x32_bf16 v[108:111], v[128:131], v[210:213], v[108:111]
	v_mfma_f32_16x16x32_bf16 v[104:107], v[136:139], v[210:213], v[104:107]
	v_mfma_f32_16x16x32_bf16 v[92:95], v[128:131], v[218:221], v[92:95]
	v_mfma_f32_16x16x32_bf16 v[88:91], v[136:139], v[218:221], v[88:91]
	v_mfma_f32_16x16x32_bf16 v[76:79], v[128:131], v[226:229], v[76:79]
	v_mfma_f32_16x16x32_bf16 v[72:75], v[136:139], v[226:229], v[72:75]
	v_mfma_f32_16x16x32_bf16 v[124:127], v[132:135], v[206:209], v[124:127]
	v_mfma_f32_16x16x32_bf16 v[120:123], v[140:143], v[206:209], v[120:123]
	v_mfma_f32_16x16x32_bf16 v[108:111], v[132:135], v[214:217], v[108:111]
	v_mfma_f32_16x16x32_bf16 v[104:107], v[140:143], v[214:217], v[104:107]
	v_mfma_f32_16x16x32_bf16 v[92:95], v[132:135], v[222:225], v[92:95]
	v_mfma_f32_16x16x32_bf16 v[88:91], v[140:143], v[222:225], v[88:91]
	v_mfma_f32_16x16x32_bf16 v[76:79], v[132:135], v[230:233], v[76:79]
	v_mfma_f32_16x16x32_bf16 v[72:75], v[140:143], v[230:233], v[72:75]
	v_mfma_f32_16x16x32_bf16 v[116:119], v[164:167], v[202:205], v[116:119]
	v_mfma_f32_16x16x32_bf16 v[112:115], v[172:175], v[202:205], v[112:115]
	v_mfma_f32_16x16x32_bf16 v[100:103], v[164:167], v[210:213], v[100:103]
	v_mfma_f32_16x16x32_bf16 v[96:99], v[172:175], v[210:213], v[96:99]
	v_mfma_f32_16x16x32_bf16 v[84:87], v[164:167], v[218:221], v[84:87]
	v_mfma_f32_16x16x32_bf16 v[80:83], v[172:175], v[218:221], v[80:83]
	v_mfma_f32_16x16x32_bf16 v[68:71], v[164:167], v[226:229], v[68:71]
	v_mfma_f32_16x16x32_bf16 v[64:67], v[172:175], v[226:229], v[64:67]
	v_mfma_f32_16x16x32_bf16 v[116:119], v[168:171], v[206:209], v[116:119]
	v_mfma_f32_16x16x32_bf16 v[112:115], v[198:201], v[206:209], v[112:115]
	v_mfma_f32_16x16x32_bf16 v[100:103], v[168:171], v[214:217], v[100:103]
	v_mfma_f32_16x16x32_bf16 v[96:99], v[198:201], v[214:217], v[96:99]
	v_mfma_f32_16x16x32_bf16 v[84:87], v[168:171], v[222:225], v[84:87]
	v_mfma_f32_16x16x32_bf16 v[80:83], v[198:201], v[222:225], v[80:83]
	v_mfma_f32_16x16x32_bf16 v[68:71], v[168:171], v[230:233], v[68:71]
	v_mfma_f32_16x16x32_bf16 v[64:67], v[198:201], v[230:233], v[64:67]
	s_setprio 0
	s_barrier
	s_add_i32 s78, s70, s33
	v_lshl_add_u64 v[234:235], s[52:53], 0, v[148:149]
	s_mov_b32 m0, s78
	ds_read_b128 v[202:205], v195 offset:16384
	ds_read_b128 v[206:209], v195 offset:17408
	ds_read_b128 v[210:213], v195 offset:18432
	ds_read_b128 v[214:217], v195 offset:19456
	ds_read_b128 v[218:221], v195 offset:20480
	ds_read_b128 v[222:225], v195 offset:21504
	ds_read_b128 v[226:229], v195 offset:22528
	ds_read_b128 v[230:233], v195 offset:23552
	global_load_lds_dwordx4 v[234:235], off
	s_add_i32 m0, s78, 0x2000
	s_add_u32 s78, s52, 0x40000
	v_lshl_add_u64 v[236:237], s[52:53], 0, v[144:145]
	s_addc_u32 s79, s53, 0
	s_add_i32 s80, s71, s33
	global_load_lds_dwordx4 v[236:237], off
	v_lshl_add_u64 v[240:241], s[78:79], 0, v[148:149]
	s_mov_b32 m0, s80
	v_lshl_add_u64 v[242:243], s[56:57], 0, v[146:147]
	global_load_lds_dwordx4 v[240:241], off
	v_lshl_add_u64 v[240:241], s[78:79], 0, v[144:145]
	s_add_i32 m0, s80, 0x2000
	s_nop 0
	global_load_lds_dwordx4 v[240:241], off
	v_lshl_add_u64 v[240:241], s[56:57], 0, v[150:151]
	s_mov_b32 m0, s60
	s_nop 0
	global_load_lds_dwordx4 v[240:241], off
	s_mov_b32 m0, s61
	s_nop 0
	global_load_lds_dwordx4 v[242:243], off
	s_waitcnt vmcnt(8)
	s_waitcnt lgkmcnt(0)
	s_barrier
; #define PG8_STAGE(bufoff, gbase, voff) do { _Pragma("unroll") for (int _i = 0; _i < 2; ++_i) \
;         __builtin_amdgcn_global_load_lds((const unsigned*)((const char*)(gbase) + (voff)[_i]), (LAS unsigned*)(lds + (bufoff) + ldsw + _i * 8192), 16, 0, 0); } while (0)
; #define PG8_LDA(dst, b, h) do { _Pragma("unroll") for (int m = 0; m < 4; ++m) _Pragma("unroll") for (int k = 0; k < 2; ++k) dst[m][k] = *(const LAS bf16x8*)(lds + PG8_SA(b, h) + aoff + m * 2048 + k * 1024); } while (0)
; #define PG8_LDB(dst, b, h) do { _Pragma("unroll") for (int n = 0; n < 2; ++n) _Pragma("unroll") for (int k = 0; k < 2; ++k) dst[n][k] = *(const LAS bf16x8*)(lds + PG8_SB(b, h) + boff + n * 2048 + k * 1024); } while (0)
; #define PG8_MMA(ai, bj, At, Bt) do { __builtin_amdgcn_s_setprio(1); _Pragma("unroll") for (int m = 0; m < 4; ++m) _Pragma("unroll") for (int n = 0; n < 2; ++n) _Pragma("unroll") for (int k = 0; k < 2; ++k) \
;         acc[ai][bj][m][n] = __builtin_amdgcn_mfma_f32_16x16x32_bf16(Bt[n][k], At[m][k], acc[ai][bj][m][n], 0, 0, 0); __builtin_amdgcn_s_setprio(0); } while (0)
; #define PG8_WAIT_V(n) asm volatile("s_waitcnt vmcnt(" #n ")" ::: "memory")
; #define PG8_WAIT_L(n) asm volatile("s_waitcnt lgkmcnt(" #n ")" ::: "memory")
; #define PG8_BAR __builtin_amdgcn_s_barrier()
; #define PG8_SCHED __builtin_amdgcn_sched_barrier(0)
; template <class Epi>
; __device__ __forceinline__ void gemm_phase(LAS unsigned char* lds, const Gemm g, const StaticOrder& S, const Epi& E) {
;     ...
;             PG8_WAIT_V(8); PG8_WAIT_L(0); PG8_BAR; PG8_MMA(1, 0, At, B0); PG8_MMA(1, 1, At, B1); PG8_BAR; PG8_SCHED;
;             PG8_LDB(B0, 1, 0); PG8_LDB(B1, 1, 1); PG8_SCHED; PG8_LDA(At, 1, 0); PG8_STAGE(PG8_SA(0, 1), a2 + hstepA, voffA);
;             PG8_WAIT_V(8); PG8_WAIT_L(0); PG8_BAR; PG8_MMA(0, 0, At, B0); PG8_MMA(0, 1, At, B1); PG8_BAR; PG8_SCHED;
	s_setprio 1
	s_waitcnt lgkmcnt(0)
	v_mfma_f32_16x16x32_bf16 v[60:63], v[128:131], v[202:205], v[60:63]
	v_mfma_f32_16x16x32_bf16 v[56:59], v[136:139], v[202:205], v[56:59]
	v_mfma_f32_16x16x32_bf16 v[44:47], v[128:131], v[210:213], v[44:47]
	v_mfma_f32_16x16x32_bf16 v[40:43], v[136:139], v[210:213], v[40:43]
	v_mfma_f32_16x16x32_bf16 v[28:31], v[128:131], v[218:221], v[28:31]
	v_mfma_f32_16x16x32_bf16 v[24:27], v[136:139], v[218:221], v[24:27]
	v_mfma_f32_16x16x32_bf16 v[12:15], v[128:131], v[226:229], v[12:15]
	v_mfma_f32_16x16x32_bf16 v[8:11], v[136:139], v[226:229], v[8:11]
	v_mfma_f32_16x16x32_bf16 v[60:63], v[132:135], v[206:209], v[60:63]
	v_mfma_f32_16x16x32_bf16 v[56:59], v[140:143], v[206:209], v[56:59]
	v_mfma_f32_16x16x32_bf16 v[44:47], v[132:135], v[214:217], v[44:47]
	v_mfma_f32_16x16x32_bf16 v[40:43], v[140:143], v[214:217], v[40:43]
	v_mfma_f32_16x16x32_bf16 v[28:31], v[132:135], v[222:225], v[28:31]
	v_mfma_f32_16x16x32_bf16 v[24:27], v[140:143], v[222:225], v[24:27]
	v_mfma_f32_16x16x32_bf16 v[12:15], v[132:135], v[230:233], v[12:15]
	v_mfma_f32_16x16x32_bf16 v[8:11], v[140:143], v[230:233], v[8:11]
	v_mfma_f32_16x16x32_bf16 v[52:55], v[164:167], v[202:205], v[52:55]
	v_mfma_f32_16x16x32_bf16 v[48:51], v[172:175], v[202:205], v[48:51]
	v_mfma_f32_16x16x32_bf16 v[36:39], v[164:167], v[210:213], v[36:39]
	v_mfma_f32_16x16x32_bf16 v[32:35], v[172:175], v[210:213], v[32:35]
	v_mfma_f32_16x16x32_bf16 v[20:23], v[164:167], v[218:221], v[20:23]
	v_mfma_f32_16x16x32_bf16 v[16:19], v[172:175], v[218:221], v[16:19]
	v_mfma_f32_16x16x32_bf16 v[4:7], v[164:167], v[226:229], v[4:7]
	v_mfma_f32_16x16x32_bf16 v[0:3], v[172:175], v[226:229], v[0:3]
	v_mfma_f32_16x16x32_bf16 v[52:55], v[168:171], v[206:209], v[52:55]
	v_mfma_f32_16x16x32_bf16 v[48:51], v[198:201], v[206:209], v[48:51]
	v_mfma_f32_16x16x32_bf16 v[36:39], v[168:171], v[214:217], v[36:39]
	v_mfma_f32_16x16x32_bf16 v[32:35], v[198:201], v[214:217], v[32:35]
	v_mfma_f32_16x16x32_bf16 v[20:23], v[168:171], v[222:225], v[20:23]
	v_mfma_f32_16x16x32_bf16 v[16:19], v[198:201], v[222:225], v[16:19]
	v_mfma_f32_16x16x32_bf16 v[4:7], v[168:171], v[230:233], v[4:7]
	v_mfma_f32_16x16x32_bf16 v[0:3], v[198:201], v[230:233], v[0:3]
	s_setprio 0
	s_barrier
	s_add_i32 s78, 0, 0x18000
	s_add_i32 s79, 0, 0x1c000
	v_add_u32_e32 v140, s78, v185
	v_add_u32_e32 v152, s79, v185
	ds_read_b128 v[128:131], v140
	ds_read_b128 v[132:135], v140 offset:1024
	ds_read_b128 v[136:139], v140 offset:2048
	ds_read_b128 v[140:143], v140 offset:3072
	ds_read_b128 v[164:167], v152
	ds_read_b128 v[168:171], v152 offset:1024
	ds_read_b128 v[172:175], v152 offset:2048
	ds_read_b128 v[198:201], v152 offset:3072
	s_add_u32 s56, s56, 0x40000
	s_addc_u32 s57, s57, 0
	s_mov_b32 m0, s62
	v_lshl_add_u64 v[248:249], s[56:57], 0, v[150:151]
	ds_read_b128 v[202:205], v195 offset:32768
	ds_read_b128 v[206:209], v195 offset:33792
	ds_read_b128 v[210:213], v195 offset:34816
	ds_read_b128 v[214:217], v195 offset:35840
	ds_read_b128 v[218:221], v195 offset:36864
	ds_read_b128 v[222:225], v195 offset:37888
	ds_read_b128 v[226:229], v195 offset:38912
	ds_read_b128 v[230:233], v195 offset:39936
	global_load_lds_dwordx4 v[248:249], off
	v_lshl_add_u64 v[248:249], s[56:57], 0, v[146:147]
	s_mov_b32 m0, s63
	s_nop 0
	global_load_lds_dwordx4 v[248:249], off
	s_waitcnt vmcnt(8)
	s_waitcnt lgkmcnt(0)
	s_barrier
	s_setprio 1
	s_waitcnt lgkmcnt(0)
	v_mfma_f32_16x16x32_bf16 v[124:127], v[128:131], v[202:205], v[124:127]
	v_mfma_f32_16x16x32_bf16 v[120:123], v[136:139], v[202:205], v[120:123]
	v_mfma_f32_16x16x32_bf16 v[108:111], v[128:131], v[210:213], v[108:111]
	v_mfma_f32_16x16x32_bf16 v[104:107], v[136:139], v[210:213], v[104:107]
	v_mfma_f32_16x16x32_bf16 v[92:95], v[128:131], v[218:221], v[92:95]
	v_mfma_f32_16x16x32_bf16 v[88:91], v[136:139], v[218:221], v[88:91]
	v_mfma_f32_16x16x32_bf16 v[76:79], v[128:131], v[226:229], v[76:79]
	v_mfma_f32_16x16x32_bf16 v[72:75], v[136:139], v[226:229], v[72:75]
	v_mfma_f32_16x16x32_bf16 v[124:127], v[132:135], v[206:209], v[124:127]
	v_mfma_f32_16x16x32_bf16 v[120:123], v[140:143], v[206:209], v[120:123]
	v_mfma_f32_16x16x32_bf16 v[108:111], v[132:135], v[214:217], v[108:111]
	v_mfma_f32_16x16x32_bf16 v[104:107], v[140:143], v[214:217], v[104:107]
	v_mfma_f32_16x16x32_bf16 v[92:95], v[132:135], v[222:225], v[92:95]
	v_mfma_f32_16x16x32_bf16 v[88:91], v[140:143], v[222:225], v[88:91]
	v_mfma_f32_16x16x32_bf16 v[76:79], v[132:135], v[230:233], v[76:79]
	v_mfma_f32_16x16x32_bf16 v[72:75], v[140:143], v[230:233], v[72:75]
	v_mfma_f32_16x16x32_bf16 v[116:119], v[164:167], v[202:205], v[116:119]
	v_mfma_f32_16x16x32_bf16 v[112:115], v[172:175], v[202:205], v[112:115]
	v_mfma_f32_16x16x32_bf16 v[100:103], v[164:167], v[210:213], v[100:103]
	v_mfma_f32_16x16x32_bf16 v[96:99], v[172:175], v[210:213], v[96:99]
	v_mfma_f32_16x16x32_bf16 v[84:87], v[164:167], v[218:221], v[84:87]
	v_mfma_f32_16x16x32_bf16 v[80:83], v[172:175], v[218:221], v[80:83]
	v_mfma_f32_16x16x32_bf16 v[68:71], v[164:167], v[226:229], v[68:71]
	v_mfma_f32_16x16x32_bf16 v[64:67], v[172:175], v[226:229], v[64:67]
	v_mfma_f32_16x16x32_bf16 v[116:119], v[168:171], v[206:209], v[116:119]
	v_mfma_f32_16x16x32_bf16 v[112:115], v[198:201], v[206:209], v[112:115]
	v_mfma_f32_16x16x32_bf16 v[100:103], v[168:171], v[214:217], v[100:103]
	v_mfma_f32_16x16x32_bf16 v[96:99], v[198:201], v[214:217], v[96:99]
	v_mfma_f32_16x16x32_bf16 v[84:87], v[168:171], v[222:225], v[84:87]
	v_mfma_f32_16x16x32_bf16 v[80:83], v[198:201], v[222:225], v[80:83]
	v_mfma_f32_16x16x32_bf16 v[68:71], v[168:171], v[230:233], v[68:71]
	v_mfma_f32_16x16x32_bf16 v[64:67], v[198:201], v[230:233], v[64:67]
	s_setprio 0
	s_barrier
; #define PG8_STAGE(bufoff, gbase, voff) do { _Pragma("unroll") for (int _i = 0; _i < 2; ++_i) \
;         __builtin_amdgcn_global_load_lds((const unsigned*)((const char*)(gbase) + (voff)[_i]), (LAS unsigned*)(lds + (bufoff) + ldsw + _i * 8192), 16, 0, 0); } while (0)
; #define PG8_LDA(dst, b, h) do { _Pragma("unroll") for (int m = 0; m < 4; ++m) _Pragma("unroll") for (int k = 0; k < 2; ++k) dst[m][k] = *(const LAS bf16x8*)(lds + PG8_SA(b, h) + aoff + m * 2048 + k * 1024); } while (0)
; #define PG8_MMA(ai, bj, At, Bt) do { __builtin_amdgcn_s_setprio(1); _Pragma("unroll") for (int m = 0; m < 4; ++m) _Pragma("unroll") for (int n = 0; n < 2; ++n) _Pragma("unroll") for (int k = 0; k < 2; ++k) \
;         acc[ai][bj][m][n] = __builtin_amdgcn_mfma_f32_16x16x32_bf16(Bt[n][k], At[m][k], acc[ai][bj][m][n], 0, 0, 0); __builtin_amdgcn_s_setprio(0); } while (0)
; #define PG8_WAIT_V(n) asm volatile("s_waitcnt vmcnt(" #n ")" ::: "memory")
; #define PG8_WAIT_L(n) asm volatile("s_waitcnt lgkmcnt(" #n ")" ::: "memory")
; #define PG8_BAR __builtin_amdgcn_s_barrier()
; #define PG8_SCHED __builtin_amdgcn_sched_barrier(0)
; template <class Epi>
; __device__ __forceinline__ void gemm_phase(LAS unsigned char* lds, const Gemm g, const StaticOrder& S, const Epi& E) {
;     ...
;             PG8_LDA(At, 1, 1); PG8_STAGE(PG8_SB(1, 0), b3, voffB); PG8_STAGE(PG8_SB(1, 1), b3 + hstepB, voffB); PG8_STAGE(PG8_SA(1, 0), a3, voffA);
;             PG8_WAIT_V(8); PG8_WAIT_L(0); PG8_BAR; PG8_MMA(1, 0, At, B0); PG8_MMA(1, 1, At, B1); PG8_BAR; PG8_SCHED;
;         }
;         if (wr == 0) PG8_BAR;
	s_add_i32 s56, s78, s33
	v_lshl_add_u64 v[234:235], v[234:235], 0, s[18:19]
	s_mov_b32 m0, s56
	ds_read_b128 v[202:205], v195 offset:49152
	ds_read_b128 v[206:209], v195 offset:50176
	ds_read_b128 v[210:213], v195 offset:51200
	ds_read_b128 v[214:217], v195 offset:52224
	ds_read_b128 v[218:221], v195 offset:53248
	ds_read_b128 v[222:225], v195 offset:54272
	ds_read_b128 v[226:229], v195 offset:55296
	ds_read_b128 v[230:233], v195 offset:56320
	global_load_lds_dwordx4 v[234:235], off
	s_add_i32 m0, s56, 0x2000
	s_add_u32 s52, s52, 0x40080
	v_lshl_add_u64 v[234:235], v[236:237], 0, s[18:19]
	s_addc_u32 s53, s53, 0
	s_add_i32 s56, s79, s33
	global_load_lds_dwordx4 v[234:235], off
	v_lshl_add_u64 v[234:235], s[52:53], 0, v[148:149]
	s_mov_b32 m0, s56
	s_nop 0
	global_load_lds_dwordx4 v[234:235], off
	v_lshl_add_u64 v[234:235], s[52:53], 0, v[144:145]
	s_add_i32 m0, s56, 0x2000
	s_nop 0
	global_load_lds_dwordx4 v[234:235], off
	v_lshl_add_u64 v[234:235], v[240:241], 0, s[18:19]
	s_mov_b32 m0, s65
	s_nop 0
	global_load_lds_dwordx4 v[234:235], off
	v_lshl_add_u64 v[234:235], v[242:243], 0, s[18:19]
	s_mov_b32 m0, s67
	s_nop 0
	global_load_lds_dwordx4 v[234:235], off
	s_waitcnt vmcnt(8)
	s_waitcnt lgkmcnt(0)
	s_barrier
	s_setprio 1
	s_waitcnt lgkmcnt(0)
	v_mfma_f32_16x16x32_bf16 v[60:63], v[128:131], v[202:205], v[60:63]
	v_mfma_f32_16x16x32_bf16 v[56:59], v[136:139], v[202:205], v[56:59]
	v_mfma_f32_16x16x32_bf16 v[44:47], v[128:131], v[210:213], v[44:47]
	v_mfma_f32_16x16x32_bf16 v[40:43], v[136:139], v[210:213], v[40:43]
	v_mfma_f32_16x16x32_bf16 v[28:31], v[128:131], v[218:221], v[28:31]
	v_mfma_f32_16x16x32_bf16 v[24:27], v[136:139], v[218:221], v[24:27]
	v_mfma_f32_16x16x32_bf16 v[12:15], v[128:131], v[226:229], v[12:15]
	v_mfma_f32_16x16x32_bf16 v[8:11], v[136:139], v[226:229], v[8:11]
	v_mfma_f32_16x16x32_bf16 v[60:63], v[132:135], v[206:209], v[60:63]
	v_mfma_f32_16x16x32_bf16 v[56:59], v[140:143], v[206:209], v[56:59]
	v_mfma_f32_16x16x32_bf16 v[44:47], v[132:135], v[214:217], v[44:47]
	v_mfma_f32_16x16x32_bf16 v[40:43], v[140:143], v[214:217], v[40:43]
	v_mfma_f32_16x16x32_bf16 v[28:31], v[132:135], v[222:225], v[28:31]
	v_mfma_f32_16x16x32_bf16 v[24:27], v[140:143], v[222:225], v[24:27]
	v_mfma_f32_16x16x32_bf16 v[12:15], v[132:135], v[230:233], v[12:15]
	v_mfma_f32_16x16x32_bf16 v[8:11], v[140:143], v[230:233], v[8:11]
	v_mfma_f32_16x16x32_bf16 v[52:55], v[164:167], v[202:205], v[52:55]
	v_mfma_f32_16x16x32_bf16 v[48:51], v[172:175], v[202:205], v[48:51]
	v_mfma_f32_16x16x32_bf16 v[36:39], v[164:167], v[210:213], v[36:39]
	v_mfma_f32_16x16x32_bf16 v[32:35], v[172:175], v[210:213], v[32:35]
	v_mfma_f32_16x16x32_bf16 v[20:23], v[164:167], v[218:221], v[20:23]
	v_mfma_f32_16x16x32_bf16 v[16:19], v[172:175], v[218:221], v[16:19]
	v_mfma_f32_16x16x32_bf16 v[4:7], v[164:167], v[226:229], v[4:7]
	v_mfma_f32_16x16x32_bf16 v[0:3], v[172:175], v[226:229], v[0:3]
	v_mfma_f32_16x16x32_bf16 v[52:55], v[168:171], v[206:209], v[52:55]
	v_mfma_f32_16x16x32_bf16 v[48:51], v[198:201], v[206:209], v[48:51]
	v_mfma_f32_16x16x32_bf16 v[36:39], v[168:171], v[214:217], v[36:39]
	v_mfma_f32_16x16x32_bf16 v[32:35], v[198:201], v[214:217], v[32:35]
	v_mfma_f32_16x16x32_bf16 v[20:23], v[168:171], v[222:225], v[20:23]
	v_mfma_f32_16x16x32_bf16 v[16:19], v[198:201], v[222:225], v[16:19]
	v_mfma_f32_16x16x32_bf16 v[4:7], v[168:171], v[230:233], v[4:7]
	v_mfma_f32_16x16x32_bf16 v[0:3], v[198:201], v[230:233], v[0:3]
	s_setprio 0
	s_barrier
	s_add_i32 s77, s77, 2
	s_add_u32 s40, s40, 0x100
	s_addc_u32 s41, s41, 0
	s_add_u32 s75, s75, 0x100
	s_addc_u32 s76, s76, 0
	s_cmp_gt_u32 s77, 13
	s_cbranch_scc0 .LBB0_997
	s_and_b64 vcc, exec, s[20:21]
	s_cbranch_vccz .LBB0_1000
	s_barrier

; #define PG8_STAGE(bufoff, gbase, voff) do { _Pragma("unroll") for (int _i = 0; _i < 2; ++_i) \
;         __builtin_amdgcn_global_load_lds((const unsigned*)((const char*)(gbase) + (voff)[_i]), (LAS unsigned*)(lds + (bufoff) + ldsw + _i * 8192), 16, 0, 0); } while (0)
; #define PG8_LDA(dst, b, h) do { _Pragma("unroll") for (int m = 0; m < 4; ++m) _Pragma("unroll") for (int k = 0; k < 2; ++k) dst[m][k] = *(const LAS bf16x8*)(lds + PG8_SA(b, h) + aoff + m * 2048 + k * 1024); } while (0)
; #define PG8_LDB(dst, b, h) do { _Pragma("unroll") for (int n = 0; n < 2; ++n) _Pragma("unroll") for (int k = 0; k < 2; ++k) dst[n][k] = *(const LAS bf16x8*)(lds + PG8_SB(b, h) + boff + n * 2048 + k * 1024); } while (0)
; #define PG8_MMA(ai, bj, At, Bt) do { __builtin_amdgcn_s_setprio(1); _Pragma("unroll") for (int m = 0; m < 4; ++m) _Pragma("unroll") for (int n = 0; n < 2; ++n) _Pragma("unroll") for (int k = 0; k < 2; ++k) \
;         acc[ai][bj][m][n] = __builtin_amdgcn_mfma_f32_16x16x32_bf16(Bt[n][k], At[m][k], acc[ai][bj][m][n], 0, 0, 0); __builtin_amdgcn_s_setprio(0); } while (0)
; #define PG8_WAIT_V(n) asm volatile("s_waitcnt vmcnt(" #n ")" ::: "memory")
; #define PG8_WAIT_L(n) asm volatile("s_waitcnt lgkmcnt(" #n ")" ::: "memory")
; #define PG8_BAR __builtin_amdgcn_s_barrier()
; #define PG8_SCHED __builtin_amdgcn_sched_barrier(0)
; template <class Epi>
; __device__ __forceinline__ void gemm_phase(LAS unsigned char* lds, const Gemm g, const StaticOrder& S, const Epi& E) {
;     ...
;         for (int t = 0; t < nt; t += 2) {
;             const bool last = (t == nt - 2);
;             const char* a1 = cA + (size_t)(t + 1) * kstep;
;             const char* a2 = last ? nA : cA + (size_t)(t + 2) * kstep; const char* b2 = last ? nB : cB + (size_t)(t + 2) * kstep;
;             const char* a3 = a2 + kstep; const char* b3 = b2 + kstep;
;             PG8_LDB(B0, 0, 0); PG8_LDB(B1, 0, 1); PG8_SCHED; PG8_LDA(At, 0, 0); PG8_STAGE(PG8_SA(1, 1), a1 + hstepA, voffA);
;             PG8_WAIT_V(8); PG8_WAIT_L(0); PG8_BAR; PG8_MMA(0, 0, At, B0); PG8_MMA(0, 1, At, B1); PG8_BAR; PG8_SCHED;
;             PG8_LDA(At, 0, 1); PG8_STAGE(PG8_SB(0, 0), b2, voffB); PG8_STAGE(PG8_SB(0, 1), b2 + hstepB, voffB); PG8_STAGE(PG8_SA(0, 0), a2, voffA);
;             PG8_WAIT_V(8); PG8_WAIT_L(0); PG8_BAR; PG8_MMA(1, 0, At, B0); PG8_MMA(1, 1, At, B1); PG8_BAR; PG8_SCHED;
.LBB0_1089:
	ds_read_b128 v[60:63], v248
	ds_read_b128 v[64:67], v248 offset:1024
	ds_read_b128 v[68:71], v248 offset:2048
	ds_read_b128 v[72:75], v248 offset:3072
	ds_read_b128 v[76:79], v249
	ds_read_b128 v[80:83], v249 offset:1024
	ds_read_b128 v[88:91], v249 offset:2048
	ds_read_b128 v[92:95], v249 offset:3072
	s_add_u32 s60, s58, 0x100
	s_addc_u32 s61, s59, 0
	s_cmp_eq_u32 s83, 40
	s_cselect_b32 s65, s1, s61
	s_cselect_b32 s64, s0, s60
	s_cselect_b32 s63, s57, s47
	s_cselect_b32 s62, s56, s46
	v_lshl_add_u64 v[174:175], s[58:59], 0, v[166:167]
	s_add_i32 m0, s67, 0xc000
	ds_read_b128 v[170:173], v250
	ds_read_b128 v[194:197], v250 offset:1024
	ds_read_b128 v[198:201], v250 offset:2048
	ds_read_b128 v[202:205], v250 offset:3072
	ds_read_b128 v[206:209], v250 offset:4096
	ds_read_b128 v[210:213], v250 offset:5120
	ds_read_b128 v[214:217], v250 offset:6144
	ds_read_b128 v[218:221], v250 offset:7168
	global_load_lds_dwordx4 v[174:175], off
	v_lshl_add_u64 v[174:175], s[58:59], 0, v[168:169]
	s_add_i32 m0, s67, 0xe000
	s_nop 0
	global_load_lds_dwordx4 v[174:175], off
	s_waitcnt vmcnt(8)
	s_waitcnt lgkmcnt(0)
	s_barrier
	s_setprio 1
	s_waitcnt lgkmcnt(0)
	v_mfma_f32_16x16x32_bf16 v[156:159], v[60:63], v[170:173], v[156:159]
	v_mfma_f32_16x16x32_bf16 v[152:155], v[68:71], v[170:173], v[152:155]
	v_mfma_f32_16x16x32_bf16 v[140:143], v[60:63], v[198:201], v[140:143]
	v_mfma_f32_16x16x32_bf16 v[136:139], v[68:71], v[198:201], v[136:139]
	v_mfma_f32_16x16x32_bf16 v[124:127], v[60:63], v[206:209], v[124:127]
	v_mfma_f32_16x16x32_bf16 v[120:123], v[68:71], v[206:209], v[120:123]
	v_mfma_f32_16x16x32_bf16 v[108:111], v[60:63], v[214:217], v[108:111]
	v_mfma_f32_16x16x32_bf16 v[104:107], v[68:71], v[214:217], v[104:107]
	v_mfma_f32_16x16x32_bf16 v[156:159], v[64:67], v[194:197], v[156:159]
	v_mfma_f32_16x16x32_bf16 v[152:155], v[72:75], v[194:197], v[152:155]
	v_mfma_f32_16x16x32_bf16 v[140:143], v[64:67], v[202:205], v[140:143]
	v_mfma_f32_16x16x32_bf16 v[136:139], v[72:75], v[202:205], v[136:139]
	v_mfma_f32_16x16x32_bf16 v[124:127], v[64:67], v[210:213], v[124:127]
	v_mfma_f32_16x16x32_bf16 v[120:123], v[72:75], v[210:213], v[120:123]
	v_mfma_f32_16x16x32_bf16 v[108:111], v[64:67], v[218:221], v[108:111]
	v_mfma_f32_16x16x32_bf16 v[104:107], v[72:75], v[218:221], v[104:107]
	v_mfma_f32_16x16x32_bf16 v[148:151], v[76:79], v[170:173], v[148:151]
	v_mfma_f32_16x16x32_bf16 v[144:147], v[88:91], v[170:173], v[144:147]
	v_mfma_f32_16x16x32_bf16 v[132:135], v[76:79], v[198:201], v[132:135]
	v_mfma_f32_16x16x32_bf16 v[128:131], v[88:91], v[198:201], v[128:131]
	v_mfma_f32_16x16x32_bf16 v[116:119], v[76:79], v[206:209], v[116:119]
	v_mfma_f32_16x16x32_bf16 v[112:115], v[88:91], v[206:209], v[112:115]
	v_mfma_f32_16x16x32_bf16 v[100:103], v[76:79], v[214:217], v[100:103]
	v_mfma_f32_16x16x32_bf16 v[96:99], v[88:91], v[214:217], v[96:99]
	v_mfma_f32_16x16x32_bf16 v[148:151], v[80:83], v[194:197], v[148:151]
	v_mfma_f32_16x16x32_bf16 v[144:147], v[92:95], v[194:197], v[144:147]
	v_mfma_f32_16x16x32_bf16 v[132:135], v[80:83], v[202:205], v[132:135]
	v_mfma_f32_16x16x32_bf16 v[128:131], v[92:95], v[202:205], v[128:131]
	v_mfma_f32_16x16x32_bf16 v[116:119], v[80:83], v[210:213], v[116:119]
	v_mfma_f32_16x16x32_bf16 v[112:115], v[92:95], v[210:213], v[112:115]
	v_mfma_f32_16x16x32_bf16 v[100:103], v[80:83], v[218:221], v[100:103]
	v_mfma_f32_16x16x32_bf16 v[96:99], v[92:95], v[218:221], v[96:99]
	s_setprio 0
	s_barrier
	s_add_i32 s58, s77, s33
	v_lshl_add_u64 v[174:175], s[62:63], 0, v[160:161]
	s_mov_b32 m0, s58
	ds_read_b128 v[170:173], v250 offset:16384
	ds_read_b128 v[194:197], v250 offset:17408
	ds_read_b128 v[198:201], v250 offset:18432
	ds_read_b128 v[202:205], v250 offset:19456
	ds_read_b128 v[206:209], v250 offset:20480
	ds_read_b128 v[210:213], v250 offset:21504
	ds_read_b128 v[214:217], v250 offset:22528
	ds_read_b128 v[218:221], v250 offset:23552
	global_load_lds_dwordx4 v[174:175], off
	s_add_i32 m0, s58, 0x2000
	s_add_u32 s58, s62, 0xb0000
	v_lshl_add_u64 v[222:223], s[62:63], 0, v[162:163]
	s_addc_u32 s59, s63, 0
	s_add_i32 s86, s78, s33
	global_load_lds_dwordx4 v[222:223], off
	v_lshl_add_u64 v[224:225], s[58:59], 0, v[160:161]
	s_mov_b32 m0, s86
	v_lshl_add_u64 v[226:227], s[64:65], 0, v[162:163]
	global_load_lds_dwordx4 v[224:225], off
	v_lshl_add_u64 v[224:225], s[58:59], 0, v[162:163]
	s_add_i32 m0, s86, 0x2000
	s_nop 0
	global_load_lds_dwordx4 v[224:225], off
	v_lshl_add_u64 v[224:225], s[64:65], 0, v[160:161]
	s_mov_b32 m0, s67
	s_nop 0
	global_load_lds_dwordx4 v[224:225], off
	s_mov_b32 m0, s68
	s_nop 0
	global_load_lds_dwordx4 v[226:227], off
	s_waitcnt vmcnt(8)
	s_waitcnt lgkmcnt(0)
	s_barrier
; #define PG8_STAGE(bufoff, gbase, voff) do { _Pragma("unroll") for (int _i = 0; _i < 2; ++_i) \
;         __builtin_amdgcn_global_load_lds((const unsigned*)((const char*)(gbase) + (voff)[_i]), (LAS unsigned*)(lds + (bufoff) + ldsw + _i * 8192), 16, 0, 0); } while (0)
; #define PG8_LDA(dst, b, h) do { _Pragma("unroll") for (int m = 0; m < 4; ++m) _Pragma("unroll") for (int k = 0; k < 2; ++k) dst[m][k] = *(const LAS bf16x8*)(lds + PG8_SA(b, h) + aoff + m * 2048 + k * 1024); } while (0)
; #define PG8_LDB(dst, b, h) do { _Pragma("unroll") for (int n = 0; n < 2; ++n) _Pragma("unroll") for (int k = 0; k < 2; ++k) dst[n][k] = *(const LAS bf16x8*)(lds + PG8_SB(b, h) + boff + n * 2048 + k * 1024); } while (0)
; #define PG8_MMA(ai, bj, At, Bt) do { __builtin_amdgcn_s_setprio(1); _Pragma("unroll") for (int m = 0; m < 4; ++m) _Pragma("unroll") for (int n = 0; n < 2; ++n) _Pragma("unroll") for (int k = 0; k < 2; ++k) \
;         acc[ai][bj][m][n] = __builtin_amdgcn_mfma_f32_16x16x32_bf16(Bt[n][k], At[m][k], acc[ai][bj][m][n], 0, 0, 0); __builtin_amdgcn_s_setprio(0); } while (0)
; #define PG8_WAIT_V(n) asm volatile("s_waitcnt vmcnt(" #n ")" ::: "memory")
; #define PG8_WAIT_L(n) asm volatile("s_waitcnt lgkmcnt(" #n ")" ::: "memory")
; #define PG8_BAR __builtin_amdgcn_s_barrier()
; #define PG8_SCHED __builtin_amdgcn_sched_barrier(0)
; template <class Epi>
; __device__ __forceinline__ void gemm_phase(LAS unsigned char* lds, const Gemm g, const StaticOrder& S, const Epi& E) {
;     ...
;             PG8_WAIT_V(8); PG8_WAIT_L(0); PG8_BAR; PG8_MMA(1, 0, At, B0); PG8_MMA(1, 1, At, B1); PG8_BAR; PG8_SCHED;
;             PG8_LDB(B0, 1, 0); PG8_LDB(B1, 1, 1); PG8_SCHED; PG8_LDA(At, 1, 0); PG8_STAGE(PG8_SA(0, 1), a2 + hstepA, voffA);
;             PG8_WAIT_V(8); PG8_WAIT_L(0); PG8_BAR; PG8_MMA(0, 0, At, B0); PG8_MMA(0, 1, At, B1); PG8_BAR; PG8_SCHED;
	s_setprio 1
	s_waitcnt lgkmcnt(0)
	v_mfma_f32_16x16x32_bf16 v[84:87], v[60:63], v[170:173], v[84:87]
	v_mfma_f32_16x16x32_bf16 v[56:59], v[68:71], v[170:173], v[56:59]
	v_mfma_f32_16x16x32_bf16 v[44:47], v[60:63], v[198:201], v[44:47]
	v_mfma_f32_16x16x32_bf16 v[40:43], v[68:71], v[198:201], v[40:43]
	v_mfma_f32_16x16x32_bf16 v[28:31], v[60:63], v[206:209], v[28:31]
	v_mfma_f32_16x16x32_bf16 v[24:27], v[68:71], v[206:209], v[24:27]
	v_mfma_f32_16x16x32_bf16 v[12:15], v[60:63], v[214:217], v[12:15]
	v_mfma_f32_16x16x32_bf16 v[8:11], v[68:71], v[214:217], v[8:11]
	v_mfma_f32_16x16x32_bf16 v[84:87], v[64:67], v[194:197], v[84:87]
	v_mfma_f32_16x16x32_bf16 v[56:59], v[72:75], v[194:197], v[56:59]
	v_mfma_f32_16x16x32_bf16 v[44:47], v[64:67], v[202:205], v[44:47]
	v_mfma_f32_16x16x32_bf16 v[40:43], v[72:75], v[202:205], v[40:43]
	v_mfma_f32_16x16x32_bf16 v[28:31], v[64:67], v[210:213], v[28:31]
	v_mfma_f32_16x16x32_bf16 v[24:27], v[72:75], v[210:213], v[24:27]
	v_mfma_f32_16x16x32_bf16 v[12:15], v[64:67], v[218:221], v[12:15]
	v_mfma_f32_16x16x32_bf16 v[8:11], v[72:75], v[218:221], v[8:11]
	v_mfma_f32_16x16x32_bf16 v[52:55], v[76:79], v[170:173], v[52:55]
	v_mfma_f32_16x16x32_bf16 v[48:51], v[88:91], v[170:173], v[48:51]
	v_mfma_f32_16x16x32_bf16 v[36:39], v[76:79], v[198:201], v[36:39]
	v_mfma_f32_16x16x32_bf16 v[32:35], v[88:91], v[198:201], v[32:35]
	v_mfma_f32_16x16x32_bf16 v[20:23], v[76:79], v[206:209], v[20:23]
	v_mfma_f32_16x16x32_bf16 v[16:19], v[88:91], v[206:209], v[16:19]
	v_mfma_f32_16x16x32_bf16 v[4:7], v[76:79], v[214:217], v[4:7]
	v_mfma_f32_16x16x32_bf16 v[0:3], v[88:91], v[214:217], v[0:3]
	v_mfma_f32_16x16x32_bf16 v[52:55], v[80:83], v[194:197], v[52:55]
	v_mfma_f32_16x16x32_bf16 v[48:51], v[92:95], v[194:197], v[48:51]
	v_mfma_f32_16x16x32_bf16 v[36:39], v[80:83], v[202:205], v[36:39]
	v_mfma_f32_16x16x32_bf16 v[32:35], v[92:95], v[202:205], v[32:35]
	v_mfma_f32_16x16x32_bf16 v[20:23], v[80:83], v[210:213], v[20:23]
	v_mfma_f32_16x16x32_bf16 v[16:19], v[92:95], v[210:213], v[16:19]
	v_mfma_f32_16x16x32_bf16 v[4:7], v[80:83], v[218:221], v[4:7]
	v_mfma_f32_16x16x32_bf16 v[0:3], v[92:95], v[218:221], v[0:3]
	s_setprio 0
	s_barrier
	s_add_i32 s86, 0, 0x18000
	s_add_i32 s87, 0, 0x1c000
	v_add_u32_e32 v72, s86, v193
	v_add_u32_e32 v92, s87, v193
	ds_read_b128 v[60:63], v72
	ds_read_b128 v[64:67], v72 offset:1024
	ds_read_b128 v[68:71], v72 offset:2048
	ds_read_b128 v[72:75], v72 offset:3072
	ds_read_b128 v[76:79], v92
	ds_read_b128 v[80:83], v92 offset:1024
	ds_read_b128 v[88:91], v92 offset:2048
	ds_read_b128 v[92:95], v92 offset:3072
	s_add_u32 s58, s64, 0xb0000
	s_addc_u32 s59, s65, 0
	s_mov_b32 m0, s69
	v_lshl_add_u64 v[228:229], s[58:59], 0, v[160:161]
	ds_read_b128 v[170:173], v250 offset:32768
	ds_read_b128 v[194:197], v250 offset:33792
	ds_read_b128 v[198:201], v250 offset:34816
	ds_read_b128 v[202:205], v250 offset:35840
	ds_read_b128 v[206:209], v250 offset:36864
	ds_read_b128 v[210:213], v250 offset:37888
	ds_read_b128 v[214:217], v250 offset:38912
	ds_read_b128 v[218:221], v250 offset:39936
	global_load_lds_dwordx4 v[228:229], off
	v_lshl_add_u64 v[228:229], s[58:59], 0, v[162:163]
	s_mov_b32 m0, s70
	s_nop 0
	global_load_lds_dwordx4 v[228:229], off
	s_waitcnt vmcnt(8)
	s_waitcnt lgkmcnt(0)
	s_barrier
	s_setprio 1
	s_waitcnt lgkmcnt(0)
	v_mfma_f32_16x16x32_bf16 v[156:159], v[60:63], v[170:173], v[156:159]
	v_mfma_f32_16x16x32_bf16 v[152:155], v[68:71], v[170:173], v[152:155]
	v_mfma_f32_16x16x32_bf16 v[140:143], v[60:63], v[198:201], v[140:143]
	v_mfma_f32_16x16x32_bf16 v[136:139], v[68:71], v[198:201], v[136:139]
	v_mfma_f32_16x16x32_bf16 v[124:127], v[60:63], v[206:209], v[124:127]
	v_mfma_f32_16x16x32_bf16 v[120:123], v[68:71], v[206:209], v[120:123]
	v_mfma_f32_16x16x32_bf16 v[108:111], v[60:63], v[214:217], v[108:111]
	v_mfma_f32_16x16x32_bf16 v[104:107], v[68:71], v[214:217], v[104:107]
	v_mfma_f32_16x16x32_bf16 v[156:159], v[64:67], v[194:197], v[156:159]
	v_mfma_f32_16x16x32_bf16 v[152:155], v[72:75], v[194:197], v[152:155]
	v_mfma_f32_16x16x32_bf16 v[140:143], v[64:67], v[202:205], v[140:143]
	v_mfma_f32_16x16x32_bf16 v[136:139], v[72:75], v[202:205], v[136:139]
	v_mfma_f32_16x16x32_bf16 v[124:127], v[64:67], v[210:213], v[124:127]
	v_mfma_f32_16x16x32_bf16 v[120:123], v[72:75], v[210:213], v[120:123]
	v_mfma_f32_16x16x32_bf16 v[108:111], v[64:67], v[218:221], v[108:111]
	v_mfma_f32_16x16x32_bf16 v[104:107], v[72:75], v[218:221], v[104:107]
	v_mfma_f32_16x16x32_bf16 v[148:151], v[76:79], v[170:173], v[148:151]
	v_mfma_f32_16x16x32_bf16 v[144:147], v[88:91], v[170:173], v[144:147]
	v_mfma_f32_16x16x32_bf16 v[132:135], v[76:79], v[198:201], v[132:135]
	v_mfma_f32_16x16x32_bf16 v[128:131], v[88:91], v[198:201], v[128:131]
	v_mfma_f32_16x16x32_bf16 v[116:119], v[76:79], v[206:209], v[116:119]
	v_mfma_f32_16x16x32_bf16 v[112:115], v[88:91], v[206:209], v[112:115]
	v_mfma_f32_16x16x32_bf16 v[100:103], v[76:79], v[214:217], v[100:103]
	v_mfma_f32_16x16x32_bf16 v[96:99], v[88:91], v[214:217], v[96:99]
	v_mfma_f32_16x16x32_bf16 v[148:151], v[80:83], v[194:197], v[148:151]
	v_mfma_f32_16x16x32_bf16 v[144:147], v[92:95], v[194:197], v[144:147]
	v_mfma_f32_16x16x32_bf16 v[132:135], v[80:83], v[202:205], v[132:135]
	v_mfma_f32_16x16x32_bf16 v[128:131], v[92:95], v[202:205], v[128:131]
	v_mfma_f32_16x16x32_bf16 v[116:119], v[80:83], v[210:213], v[116:119]
	v_mfma_f32_16x16x32_bf16 v[112:115], v[92:95], v[210:213], v[112:115]
	v_mfma_f32_16x16x32_bf16 v[100:103], v[80:83], v[218:221], v[100:103]
	v_mfma_f32_16x16x32_bf16 v[96:99], v[92:95], v[218:221], v[96:99]
	s_setprio 0
	s_barrier
; #define PG8_STAGE(bufoff, gbase, voff) do { _Pragma("unroll") for (int _i = 0; _i < 2; ++_i) \
;         __builtin_amdgcn_global_load_lds((const unsigned*)((const char*)(gbase) + (voff)[_i]), (LAS unsigned*)(lds + (bufoff) + ldsw + _i * 8192), 16, 0, 0); } while (0)
; #define PG8_LDA(dst, b, h) do { _Pragma("unroll") for (int m = 0; m < 4; ++m) _Pragma("unroll") for (int k = 0; k < 2; ++k) dst[m][k] = *(const LAS bf16x8*)(lds + PG8_SA(b, h) + aoff + m * 2048 + k * 1024); } while (0)
; #define PG8_MMA(ai, bj, At, Bt) do { __builtin_amdgcn_s_setprio(1); _Pragma("unroll") for (int m = 0; m < 4; ++m) _Pragma("unroll") for (int n = 0; n < 2; ++n) _Pragma("unroll") for (int k = 0; k < 2; ++k) \
;         acc[ai][bj][m][n] = __builtin_amdgcn_mfma_f32_16x16x32_bf16(Bt[n][k], At[m][k], acc[ai][bj][m][n], 0, 0, 0); __builtin_amdgcn_s_setprio(0); } while (0)
; #define PG8_WAIT_V(n) asm volatile("s_waitcnt vmcnt(" #n ")" ::: "memory")
; #define PG8_WAIT_L(n) asm volatile("s_waitcnt lgkmcnt(" #n ")" ::: "memory")
; #define PG8_BAR __builtin_amdgcn_s_barrier()
; #define PG8_SCHED __builtin_amdgcn_sched_barrier(0)
; template <class Epi>
; __device__ __forceinline__ void gemm_phase(LAS unsigned char* lds, const Gemm g, const StaticOrder& S, const Epi& E) {
;     ...
;             PG8_LDA(At, 1, 1); PG8_STAGE(PG8_SB(1, 0), b3, voffB); PG8_STAGE(PG8_SB(1, 1), b3 + hstepB, voffB); PG8_STAGE(PG8_SA(1, 0), a3, voffA);
;             PG8_WAIT_V(8); PG8_WAIT_L(0); PG8_BAR; PG8_MMA(1, 0, At, B0); PG8_MMA(1, 1, At, B1); PG8_BAR; PG8_SCHED;
;         }
;         if (wr == 0) PG8_BAR;
	s_add_i32 s58, s86, s33
	v_lshl_add_u64 v[174:175], v[174:175], 0, s[40:41]
	s_mov_b32 m0, s58
	ds_read_b128 v[170:173], v250 offset:49152
	ds_read_b128 v[194:197], v250 offset:50176
	ds_read_b128 v[198:201], v250 offset:51200
	ds_read_b128 v[202:205], v250 offset:52224
	ds_read_b128 v[206:209], v250 offset:53248
	ds_read_b128 v[210:213], v250 offset:54272
	ds_read_b128 v[214:217], v250 offset:55296
	ds_read_b128 v[218:221], v250 offset:56320
	global_load_lds_dwordx4 v[174:175], off
	s_add_i32 m0, s58, 0x2000
	s_add_u32 s58, s62, 0xb0080
	v_lshl_add_u64 v[174:175], v[222:223], 0, s[40:41]
	s_addc_u32 s59, s63, 0
	s_add_i32 s62, s87, s33
	global_load_lds_dwordx4 v[174:175], off
	v_lshl_add_u64 v[174:175], s[58:59], 0, v[160:161]
	s_mov_b32 m0, s62
	s_nop 0
	global_load_lds_dwordx4 v[174:175], off
	v_lshl_add_u64 v[174:175], s[58:59], 0, v[162:163]
	s_add_i32 m0, s62, 0x2000
	s_nop 0
	global_load_lds_dwordx4 v[174:175], off
	v_lshl_add_u64 v[174:175], v[224:225], 0, s[40:41]
	s_mov_b32 m0, s72
	s_nop 0
	global_load_lds_dwordx4 v[174:175], off
	v_lshl_add_u64 v[174:175], v[226:227], 0, s[40:41]
	s_mov_b32 m0, s73
	s_nop 0
	global_load_lds_dwordx4 v[174:175], off
	s_waitcnt vmcnt(8)
	s_waitcnt lgkmcnt(0)
	s_barrier
	s_setprio 1
	s_waitcnt lgkmcnt(0)
	v_mfma_f32_16x16x32_bf16 v[84:87], v[60:63], v[170:173], v[84:87]
	v_mfma_f32_16x16x32_bf16 v[56:59], v[68:71], v[170:173], v[56:59]
	v_mfma_f32_16x16x32_bf16 v[44:47], v[60:63], v[198:201], v[44:47]
	v_mfma_f32_16x16x32_bf16 v[40:43], v[68:71], v[198:201], v[40:43]
	v_mfma_f32_16x16x32_bf16 v[28:31], v[60:63], v[206:209], v[28:31]
	v_mfma_f32_16x16x32_bf16 v[24:27], v[68:71], v[206:209], v[24:27]
	v_mfma_f32_16x16x32_bf16 v[12:15], v[60:63], v[214:217], v[12:15]
	v_mfma_f32_16x16x32_bf16 v[8:11], v[68:71], v[214:217], v[8:11]
	v_mfma_f32_16x16x32_bf16 v[84:87], v[64:67], v[194:197], v[84:87]
	v_mfma_f32_16x16x32_bf16 v[56:59], v[72:75], v[194:197], v[56:59]
	v_mfma_f32_16x16x32_bf16 v[44:47], v[64:67], v[202:205], v[44:47]
	v_mfma_f32_16x16x32_bf16 v[40:43], v[72:75], v[202:205], v[40:43]
	v_mfma_f32_16x16x32_bf16 v[28:31], v[64:67], v[210:213], v[28:31]
	v_mfma_f32_16x16x32_bf16 v[24:27], v[72:75], v[210:213], v[24:27]
	v_mfma_f32_16x16x32_bf16 v[12:15], v[64:67], v[218:221], v[12:15]
	v_mfma_f32_16x16x32_bf16 v[8:11], v[72:75], v[218:221], v[8:11]
	v_mfma_f32_16x16x32_bf16 v[52:55], v[76:79], v[170:173], v[52:55]
	v_mfma_f32_16x16x32_bf16 v[48:51], v[88:91], v[170:173], v[48:51]
	v_mfma_f32_16x16x32_bf16 v[36:39], v[76:79], v[198:201], v[36:39]
	v_mfma_f32_16x16x32_bf16 v[32:35], v[88:91], v[198:201], v[32:35]
	v_mfma_f32_16x16x32_bf16 v[20:23], v[76:79], v[206:209], v[20:23]
	v_mfma_f32_16x16x32_bf16 v[16:19], v[88:91], v[206:209], v[16:19]
	v_mfma_f32_16x16x32_bf16 v[4:7], v[76:79], v[214:217], v[4:7]
	v_mfma_f32_16x16x32_bf16 v[0:3], v[88:91], v[214:217], v[0:3]
	v_mfma_f32_16x16x32_bf16 v[52:55], v[80:83], v[194:197], v[52:55]
	v_mfma_f32_16x16x32_bf16 v[48:51], v[92:95], v[194:197], v[48:51]
	v_mfma_f32_16x16x32_bf16 v[36:39], v[80:83], v[202:205], v[36:39]
	v_mfma_f32_16x16x32_bf16 v[32:35], v[92:95], v[202:205], v[32:35]
	v_mfma_f32_16x16x32_bf16 v[20:23], v[80:83], v[210:213], v[20:23]
	v_mfma_f32_16x16x32_bf16 v[16:19], v[92:95], v[210:213], v[16:19]
	v_mfma_f32_16x16x32_bf16 v[4:7], v[80:83], v[218:221], v[4:7]
	v_mfma_f32_16x16x32_bf16 v[0:3], v[92:95], v[218:221], v[0:3]
	s_setprio 0
	s_barrier
	s_add_i32 s83, s83, 2
	s_add_u32 s46, s46, 0x100
	s_addc_u32 s47, s47, 0
	s_cmp_gt_u32 s83, 41
	s_mov_b64 s[58:59], s[60:61]
	s_cbranch_scc0 .LBB0_1089
	s_and_b64 vcc, exec, s[52:53]
	s_cbranch_vccz .LBB0_1092
	s_barrier

; #define PG8_STAGE(bufoff, gbase, voff) do { _Pragma("unroll") for (int _i = 0; _i < 2; ++_i) \
;         __builtin_amdgcn_global_load_lds((const unsigned*)((const char*)(gbase) + (voff)[_i]), (LAS unsigned*)(lds + (bufoff) + ldsw + _i * 8192), 16, 0, 0); } while (0)
; #define PG8_LDA(dst, b, h) do { _Pragma("unroll") for (int m = 0; m < 4; ++m) _Pragma("unroll") for (int k = 0; k < 2; ++k) dst[m][k] = *(const LAS bf16x8*)(lds + PG8_SA(b, h) + aoff + m * 2048 + k * 1024); } while (0)
; #define PG8_LDB(dst, b, h) do { _Pragma("unroll") for (int n = 0; n < 2; ++n) _Pragma("unroll") for (int k = 0; k < 2; ++k) dst[n][k] = *(const LAS bf16x8*)(lds + PG8_SB(b, h) + boff + n * 2048 + k * 1024); } while (0)
; #define PG8_MMA(ai, bj, At, Bt) do { __builtin_amdgcn_s_setprio(1); _Pragma("unroll") for (int m = 0; m < 4; ++m) _Pragma("unroll") for (int n = 0; n < 2; ++n) _Pragma("unroll") for (int k = 0; k < 2; ++k) \
;         acc[ai][bj][m][n] = __builtin_amdgcn_mfma_f32_16x16x32_bf16(Bt[n][k], At[m][k], acc[ai][bj][m][n], 0, 0, 0); __builtin_amdgcn_s_setprio(0); } while (0)
; #define PG8_WAIT_V(n) asm volatile("s_waitcnt vmcnt(" #n ")" ::: "memory")
; #define PG8_WAIT_L(n) asm volatile("s_waitcnt lgkmcnt(" #n ")" ::: "memory")
; #define PG8_BAR __builtin_amdgcn_s_barrier()
; #define PG8_SCHED __builtin_amdgcn_sched_barrier(0)
; template <class Epi>
; __device__ __forceinline__ void gemm_phase(LAS unsigned char* lds, const Gemm g, const StaticOrder& S, const Epi& E) {
;     ...
;         for (int t = 0; t < nt; t += 2) {
;             const bool last = (t == nt - 2);
;             const char* a1 = cA + (size_t)(t + 1) * kstep;
;             const char* a2 = last ? nA : cA + (size_t)(t + 2) * kstep; const char* b2 = last ? nB : cB + (size_t)(t + 2) * kstep;
;             const char* a3 = a2 + kstep; const char* b3 = b2 + kstep;
;             PG8_LDB(B0, 0, 0); PG8_LDB(B1, 0, 1); PG8_SCHED; PG8_LDA(At, 0, 0); PG8_STAGE(PG8_SA(1, 1), a1 + hstepA, voffA);
;             PG8_WAIT_V(8); PG8_WAIT_L(0); PG8_BAR; PG8_MMA(0, 0, At, B0); PG8_MMA(0, 1, At, B1); PG8_BAR; PG8_SCHED;
;             PG8_LDA(At, 0, 1); PG8_STAGE(PG8_SB(0, 0), b2, voffB); PG8_STAGE(PG8_SB(0, 1), b2 + hstepB, voffB); PG8_STAGE(PG8_SA(0, 0), a2, voffA);
;             PG8_WAIT_V(8); PG8_WAIT_L(0); PG8_BAR; PG8_MMA(1, 0, At, B0); PG8_MMA(1, 1, At, B1); PG8_BAR; PG8_SCHED;
.LBB0_1369:
	ds_read_b128 v[88:91], v199
	ds_read_b128 v[92:95], v199 offset:1024
	ds_read_b128 v[104:107], v199 offset:2048
	ds_read_b128 v[108:111], v199 offset:3072
	ds_read_b128 v[162:165], v200
	ds_read_b128 v[166:169], v200 offset:1024
	ds_read_b128 v[170:173], v200 offset:2048
	ds_read_b128 v[194:197], v200 offset:3072
	s_add_u32 s52, s40, 0xfffc0080
	s_addc_u32 s53, s41, -1
	s_cmp_eq_u32 s73, 12
	s_cselect_b32 s57, s13, s53
	s_cselect_b32 s56, s23, s52
	s_cselect_b32 s53, s21, s47
	s_cselect_b32 s52, s39, s46
	v_lshl_add_u64 v[174:175], s[40:41], 0, v[154:155]
	s_add_i32 m0, s25, 0xc000
	ds_read_b128 v[206:209], v201
	ds_read_b128 v[210:213], v201 offset:1024
	ds_read_b128 v[214:217], v201 offset:2048
	ds_read_b128 v[218:221], v201 offset:3072
	ds_read_b128 v[222:225], v201 offset:4096
	ds_read_b128 v[226:229], v201 offset:5120
	ds_read_b128 v[230:233], v201 offset:6144
	ds_read_b128 v[234:237], v201 offset:7168
	global_load_lds_dwordx4 v[174:175], off
	v_lshl_add_u64 v[174:175], s[40:41], 0, v[156:157]
	s_add_i32 m0, s25, 0xe000
	s_nop 0
	global_load_lds_dwordx4 v[174:175], off
	s_waitcnt vmcnt(8)
	s_waitcnt lgkmcnt(0)
	s_barrier
	s_setprio 1
	s_waitcnt lgkmcnt(0)
	v_mfma_f32_16x16x32_bf16 v[140:143], v[88:91], v[206:209], v[140:143]
	v_mfma_f32_16x16x32_bf16 v[136:139], v[104:107], v[206:209], v[136:139]
	v_mfma_f32_16x16x32_bf16 v[124:127], v[88:91], v[214:217], v[124:127]
	v_mfma_f32_16x16x32_bf16 v[120:123], v[104:107], v[214:217], v[120:123]
	v_mfma_f32_16x16x32_bf16 v[100:103], v[88:91], v[222:225], v[100:103]
	v_mfma_f32_16x16x32_bf16 v[96:99], v[104:107], v[222:225], v[96:99]
	v_mfma_f32_16x16x32_bf16 v[76:79], v[88:91], v[230:233], v[76:79]
	v_mfma_f32_16x16x32_bf16 v[72:75], v[104:107], v[230:233], v[72:75]
	v_mfma_f32_16x16x32_bf16 v[140:143], v[92:95], v[210:213], v[140:143]
	v_mfma_f32_16x16x32_bf16 v[136:139], v[108:111], v[210:213], v[136:139]
	v_mfma_f32_16x16x32_bf16 v[124:127], v[92:95], v[218:221], v[124:127]
	v_mfma_f32_16x16x32_bf16 v[120:123], v[108:111], v[218:221], v[120:123]
	v_mfma_f32_16x16x32_bf16 v[100:103], v[92:95], v[226:229], v[100:103]
	v_mfma_f32_16x16x32_bf16 v[96:99], v[108:111], v[226:229], v[96:99]
	v_mfma_f32_16x16x32_bf16 v[76:79], v[92:95], v[234:237], v[76:79]
	v_mfma_f32_16x16x32_bf16 v[72:75], v[108:111], v[234:237], v[72:75]
	v_mfma_f32_16x16x32_bf16 v[132:135], v[162:165], v[206:209], v[132:135]
	v_mfma_f32_16x16x32_bf16 v[128:131], v[170:173], v[206:209], v[128:131]
	v_mfma_f32_16x16x32_bf16 v[116:119], v[162:165], v[214:217], v[116:119]
	v_mfma_f32_16x16x32_bf16 v[112:115], v[170:173], v[214:217], v[112:115]
	v_mfma_f32_16x16x32_bf16 v[84:87], v[162:165], v[222:225], v[84:87]
	v_mfma_f32_16x16x32_bf16 v[80:83], v[170:173], v[222:225], v[80:83]
	v_mfma_f32_16x16x32_bf16 v[68:71], v[162:165], v[230:233], v[68:71]
	v_mfma_f32_16x16x32_bf16 v[64:67], v[170:173], v[230:233], v[64:67]
	v_mfma_f32_16x16x32_bf16 v[132:135], v[166:169], v[210:213], v[132:135]
	v_mfma_f32_16x16x32_bf16 v[128:131], v[194:197], v[210:213], v[128:131]
	v_mfma_f32_16x16x32_bf16 v[116:119], v[166:169], v[218:221], v[116:119]
	v_mfma_f32_16x16x32_bf16 v[112:115], v[194:197], v[218:221], v[112:115]
	v_mfma_f32_16x16x32_bf16 v[84:87], v[166:169], v[226:229], v[84:87]
	v_mfma_f32_16x16x32_bf16 v[80:83], v[194:197], v[226:229], v[80:83]
	v_mfma_f32_16x16x32_bf16 v[68:71], v[166:169], v[234:237], v[68:71]
	v_mfma_f32_16x16x32_bf16 v[64:67], v[194:197], v[234:237], v[64:67]
	s_setprio 0
	s_barrier
	s_add_i32 s74, s68, s3
	v_lshl_add_u64 v[174:175], s[52:53], 0, v[146:147]
	s_mov_b32 m0, s74
	ds_read_b128 v[206:209], v201 offset:16384
	ds_read_b128 v[210:213], v201 offset:17408
	ds_read_b128 v[214:217], v201 offset:18432
	ds_read_b128 v[218:221], v201 offset:19456
	ds_read_b128 v[222:225], v201 offset:20480
	ds_read_b128 v[226:229], v201 offset:21504
	ds_read_b128 v[230:233], v201 offset:22528
	ds_read_b128 v[234:237], v201 offset:23552
	global_load_lds_dwordx4 v[174:175], off
	s_add_i32 m0, s74, 0x2000
	s_add_u32 s74, s52, 0x40000
	v_lshl_add_u64 v[240:241], s[52:53], 0, v[150:151]
	s_addc_u32 s75, s53, 0
	s_add_i32 s76, s69, s3
	global_load_lds_dwordx4 v[240:241], off
	v_lshl_add_u64 v[242:243], s[74:75], 0, v[146:147]
	s_mov_b32 m0, s76
	v_lshl_add_u64 v[248:249], s[56:57], 0, v[148:149]
	global_load_lds_dwordx4 v[242:243], off
	v_lshl_add_u64 v[242:243], s[74:75], 0, v[150:151]
	s_add_i32 m0, s76, 0x2000
	s_nop 0
	global_load_lds_dwordx4 v[242:243], off
	v_lshl_add_u64 v[242:243], s[56:57], 0, v[144:145]
	s_mov_b32 m0, s25
	s_nop 0
	global_load_lds_dwordx4 v[242:243], off
	s_mov_b32 m0, s33
	s_nop 0
	global_load_lds_dwordx4 v[248:249], off
	s_waitcnt vmcnt(8)
	s_waitcnt lgkmcnt(0)
	s_barrier
; #define PG8_STAGE(bufoff, gbase, voff) do { _Pragma("unroll") for (int _i = 0; _i < 2; ++_i) \
;         __builtin_amdgcn_global_load_lds((const unsigned*)((const char*)(gbase) + (voff)[_i]), (LAS unsigned*)(lds + (bufoff) + ldsw + _i * 8192), 16, 0, 0); } while (0)
; #define PG8_LDA(dst, b, h) do { _Pragma("unroll") for (int m = 0; m < 4; ++m) _Pragma("unroll") for (int k = 0; k < 2; ++k) dst[m][k] = *(const LAS bf16x8*)(lds + PG8_SA(b, h) + aoff + m * 2048 + k * 1024); } while (0)
; #define PG8_LDB(dst, b, h) do { _Pragma("unroll") for (int n = 0; n < 2; ++n) _Pragma("unroll") for (int k = 0; k < 2; ++k) dst[n][k] = *(const LAS bf16x8*)(lds + PG8_SB(b, h) + boff + n * 2048 + k * 1024); } while (0)
; #define PG8_MMA(ai, bj, At, Bt) do { __builtin_amdgcn_s_setprio(1); _Pragma("unroll") for (int m = 0; m < 4; ++m) _Pragma("unroll") for (int n = 0; n < 2; ++n) _Pragma("unroll") for (int k = 0; k < 2; ++k) \
;         acc[ai][bj][m][n] = __builtin_amdgcn_mfma_f32_16x16x32_bf16(Bt[n][k], At[m][k], acc[ai][bj][m][n], 0, 0, 0); __builtin_amdgcn_s_setprio(0); } while (0)
; #define PG8_WAIT_V(n) asm volatile("s_waitcnt vmcnt(" #n ")" ::: "memory")
; #define PG8_WAIT_L(n) asm volatile("s_waitcnt lgkmcnt(" #n ")" ::: "memory")
; #define PG8_BAR __builtin_amdgcn_s_barrier()
; #define PG8_SCHED __builtin_amdgcn_sched_barrier(0)
; template <class Epi>
; __device__ __forceinline__ void gemm_phase(LAS unsigned char* lds, const Gemm g, const StaticOrder& S, const Epi& E) {
;     ...
;             PG8_WAIT_V(8); PG8_WAIT_L(0); PG8_BAR; PG8_MMA(1, 0, At, B0); PG8_MMA(1, 1, At, B1); PG8_BAR; PG8_SCHED;
;             PG8_LDB(B0, 1, 0); PG8_LDB(B1, 1, 1); PG8_SCHED; PG8_LDA(At, 1, 0); PG8_STAGE(PG8_SA(0, 1), a2 + hstepA, voffA);
;             PG8_WAIT_V(8); PG8_WAIT_L(0); PG8_BAR; PG8_MMA(0, 0, At, B0); PG8_MMA(0, 1, At, B1); PG8_BAR; PG8_SCHED;
	s_setprio 1
	s_waitcnt lgkmcnt(0)
	v_mfma_f32_16x16x32_bf16 v[60:63], v[88:91], v[206:209], v[60:63]
	v_mfma_f32_16x16x32_bf16 v[56:59], v[104:107], v[206:209], v[56:59]
	v_mfma_f32_16x16x32_bf16 v[44:47], v[88:91], v[214:217], v[44:47]
	v_mfma_f32_16x16x32_bf16 v[40:43], v[104:107], v[214:217], v[40:43]
	v_mfma_f32_16x16x32_bf16 v[28:31], v[88:91], v[222:225], v[28:31]
	v_mfma_f32_16x16x32_bf16 v[24:27], v[104:107], v[222:225], v[24:27]
	v_mfma_f32_16x16x32_bf16 v[12:15], v[88:91], v[230:233], v[12:15]
	v_mfma_f32_16x16x32_bf16 v[8:11], v[104:107], v[230:233], v[8:11]
	v_mfma_f32_16x16x32_bf16 v[60:63], v[92:95], v[210:213], v[60:63]
	v_mfma_f32_16x16x32_bf16 v[56:59], v[108:111], v[210:213], v[56:59]
	v_mfma_f32_16x16x32_bf16 v[44:47], v[92:95], v[218:221], v[44:47]
	v_mfma_f32_16x16x32_bf16 v[40:43], v[108:111], v[218:221], v[40:43]
	v_mfma_f32_16x16x32_bf16 v[28:31], v[92:95], v[226:229], v[28:31]
	v_mfma_f32_16x16x32_bf16 v[24:27], v[108:111], v[226:229], v[24:27]
	v_mfma_f32_16x16x32_bf16 v[12:15], v[92:95], v[234:237], v[12:15]
	v_mfma_f32_16x16x32_bf16 v[8:11], v[108:111], v[234:237], v[8:11]
	v_mfma_f32_16x16x32_bf16 v[52:55], v[162:165], v[206:209], v[52:55]
	v_mfma_f32_16x16x32_bf16 v[48:51], v[170:173], v[206:209], v[48:51]
	v_mfma_f32_16x16x32_bf16 v[36:39], v[162:165], v[214:217], v[36:39]
	v_mfma_f32_16x16x32_bf16 v[32:35], v[170:173], v[214:217], v[32:35]
	v_mfma_f32_16x16x32_bf16 v[20:23], v[162:165], v[222:225], v[20:23]
	v_mfma_f32_16x16x32_bf16 v[16:19], v[170:173], v[222:225], v[16:19]
	v_mfma_f32_16x16x32_bf16 v[4:7], v[162:165], v[230:233], v[4:7]
	v_mfma_f32_16x16x32_bf16 v[0:3], v[170:173], v[230:233], v[0:3]
	v_mfma_f32_16x16x32_bf16 v[52:55], v[166:169], v[210:213], v[52:55]
	v_mfma_f32_16x16x32_bf16 v[48:51], v[194:197], v[210:213], v[48:51]
	v_mfma_f32_16x16x32_bf16 v[36:39], v[166:169], v[218:221], v[36:39]
	v_mfma_f32_16x16x32_bf16 v[32:35], v[194:197], v[218:221], v[32:35]
	v_mfma_f32_16x16x32_bf16 v[20:23], v[166:169], v[226:229], v[20:23]
	v_mfma_f32_16x16x32_bf16 v[16:19], v[194:197], v[226:229], v[16:19]
	v_mfma_f32_16x16x32_bf16 v[4:7], v[166:169], v[234:237], v[4:7]
	v_mfma_f32_16x16x32_bf16 v[0:3], v[194:197], v[234:237], v[0:3]
	s_setprio 0
	s_barrier
	s_add_i32 s74, 0, 0x18000
	s_add_i32 s75, 0, 0x1c000
	v_add_u32_e32 v108, s74, v193
	v_add_u32_e32 v152, s75, v193
	ds_read_b128 v[88:91], v108
	ds_read_b128 v[92:95], v108 offset:1024
	ds_read_b128 v[104:107], v108 offset:2048
	ds_read_b128 v[108:111], v108 offset:3072
	ds_read_b128 v[162:165], v152
	ds_read_b128 v[166:169], v152 offset:1024
	ds_read_b128 v[170:173], v152 offset:2048
	ds_read_b128 v[194:197], v152 offset:3072
	s_add_u32 s56, s56, 0x40000
	s_addc_u32 s57, s57, 0
	s_mov_b32 m0, s58
	v_lshl_add_u64 v[250:251], s[56:57], 0, v[144:145]
	ds_read_b128 v[206:209], v201 offset:32768
	ds_read_b128 v[210:213], v201 offset:33792
	ds_read_b128 v[214:217], v201 offset:34816
	ds_read_b128 v[218:221], v201 offset:35840
	ds_read_b128 v[222:225], v201 offset:36864
	ds_read_b128 v[226:229], v201 offset:37888
	ds_read_b128 v[230:233], v201 offset:38912
	ds_read_b128 v[234:237], v201 offset:39936
	global_load_lds_dwordx4 v[250:251], off
	v_lshl_add_u64 v[250:251], s[56:57], 0, v[148:149]
	s_mov_b32 m0, s59
	s_nop 0
	global_load_lds_dwordx4 v[250:251], off
	s_waitcnt vmcnt(8)
	s_waitcnt lgkmcnt(0)
	s_barrier
	s_setprio 1
	s_waitcnt lgkmcnt(0)
	v_mfma_f32_16x16x32_bf16 v[140:143], v[88:91], v[206:209], v[140:143]
	v_mfma_f32_16x16x32_bf16 v[136:139], v[104:107], v[206:209], v[136:139]
	v_mfma_f32_16x16x32_bf16 v[124:127], v[88:91], v[214:217], v[124:127]
	v_mfma_f32_16x16x32_bf16 v[120:123], v[104:107], v[214:217], v[120:123]
	v_mfma_f32_16x16x32_bf16 v[100:103], v[88:91], v[222:225], v[100:103]
	v_mfma_f32_16x16x32_bf16 v[96:99], v[104:107], v[222:225], v[96:99]
	v_mfma_f32_16x16x32_bf16 v[76:79], v[88:91], v[230:233], v[76:79]
	v_mfma_f32_16x16x32_bf16 v[72:75], v[104:107], v[230:233], v[72:75]
	v_mfma_f32_16x16x32_bf16 v[140:143], v[92:95], v[210:213], v[140:143]
	v_mfma_f32_16x16x32_bf16 v[136:139], v[108:111], v[210:213], v[136:139]
	v_mfma_f32_16x16x32_bf16 v[124:127], v[92:95], v[218:221], v[124:127]
	v_mfma_f32_16x16x32_bf16 v[120:123], v[108:111], v[218:221], v[120:123]
	v_mfma_f32_16x16x32_bf16 v[100:103], v[92:95], v[226:229], v[100:103]
	v_mfma_f32_16x16x32_bf16 v[96:99], v[108:111], v[226:229], v[96:99]
	v_mfma_f32_16x16x32_bf16 v[76:79], v[92:95], v[234:237], v[76:79]
	v_mfma_f32_16x16x32_bf16 v[72:75], v[108:111], v[234:237], v[72:75]
	v_mfma_f32_16x16x32_bf16 v[132:135], v[162:165], v[206:209], v[132:135]
	v_mfma_f32_16x16x32_bf16 v[128:131], v[170:173], v[206:209], v[128:131]
	v_mfma_f32_16x16x32_bf16 v[116:119], v[162:165], v[214:217], v[116:119]
	v_mfma_f32_16x16x32_bf16 v[112:115], v[170:173], v[214:217], v[112:115]
	v_mfma_f32_16x16x32_bf16 v[84:87], v[162:165], v[222:225], v[84:87]
	v_mfma_f32_16x16x32_bf16 v[80:83], v[170:173], v[222:225], v[80:83]
	v_mfma_f32_16x16x32_bf16 v[68:71], v[162:165], v[230:233], v[68:71]
	v_mfma_f32_16x16x32_bf16 v[64:67], v[170:173], v[230:233], v[64:67]
	v_mfma_f32_16x16x32_bf16 v[132:135], v[166:169], v[210:213], v[132:135]
	v_mfma_f32_16x16x32_bf16 v[128:131], v[194:197], v[210:213], v[128:131]
	v_mfma_f32_16x16x32_bf16 v[116:119], v[166:169], v[218:221], v[116:119]
	v_mfma_f32_16x16x32_bf16 v[112:115], v[194:197], v[218:221], v[112:115]
	v_mfma_f32_16x16x32_bf16 v[84:87], v[166:169], v[226:229], v[84:87]
	v_mfma_f32_16x16x32_bf16 v[80:83], v[194:197], v[226:229], v[80:83]
	v_mfma_f32_16x16x32_bf16 v[68:71], v[166:169], v[234:237], v[68:71]
	v_mfma_f32_16x16x32_bf16 v[64:67], v[194:197], v[234:237], v[64:67]
	s_setprio 0
	s_barrier
; #define PG8_STAGE(bufoff, gbase, voff) do { _Pragma("unroll") for (int _i = 0; _i < 2; ++_i) \
;         __builtin_amdgcn_global_load_lds((const unsigned*)((const char*)(gbase) + (voff)[_i]), (LAS unsigned*)(lds + (bufoff) + ldsw + _i * 8192), 16, 0, 0); } while (0)
; #define PG8_LDA(dst, b, h) do { _Pragma("unroll") for (int m = 0; m < 4; ++m) _Pragma("unroll") for (int k = 0; k < 2; ++k) dst[m][k] = *(const LAS bf16x8*)(lds + PG8_SA(b, h) + aoff + m * 2048 + k * 1024); } while (0)
; #define PG8_MMA(ai, bj, At, Bt) do { __builtin_amdgcn_s_setprio(1); _Pragma("unroll") for (int m = 0; m < 4; ++m) _Pragma("unroll") for (int n = 0; n < 2; ++n) _Pragma("unroll") for (int k = 0; k < 2; ++k) \
;         acc[ai][bj][m][n] = __builtin_amdgcn_mfma_f32_16x16x32_bf16(Bt[n][k], At[m][k], acc[ai][bj][m][n], 0, 0, 0); __builtin_amdgcn_s_setprio(0); } while (0)
; #define PG8_WAIT_V(n) asm volatile("s_waitcnt vmcnt(" #n ")" ::: "memory")
; #define PG8_WAIT_L(n) asm volatile("s_waitcnt lgkmcnt(" #n ")" ::: "memory")
; #define PG8_BAR __builtin_amdgcn_s_barrier()
; #define PG8_SCHED __builtin_amdgcn_sched_barrier(0)
; template <class Epi>
; __device__ __forceinline__ void gemm_phase(LAS unsigned char* lds, const Gemm g, const StaticOrder& S, const Epi& E) {
;     ...
;             PG8_LDA(At, 1, 1); PG8_STAGE(PG8_SB(1, 0), b3, voffB); PG8_STAGE(PG8_SB(1, 1), b3 + hstepB, voffB); PG8_STAGE(PG8_SA(1, 0), a3, voffA);
;             PG8_WAIT_V(8); PG8_WAIT_L(0); PG8_BAR; PG8_MMA(1, 0, At, B0); PG8_MMA(1, 1, At, B1); PG8_BAR; PG8_SCHED;
;         }
;         if (wr == 0) PG8_BAR;
	s_add_i32 s56, s74, s3
	v_lshl_add_u64 v[174:175], v[174:175], 0, s[16:17]
	s_mov_b32 m0, s56
	ds_read_b128 v[206:209], v201 offset:49152
	ds_read_b128 v[210:213], v201 offset:50176
	ds_read_b128 v[214:217], v201 offset:51200
	ds_read_b128 v[218:221], v201 offset:52224
	ds_read_b128 v[222:225], v201 offset:53248
	ds_read_b128 v[226:229], v201 offset:54272
	ds_read_b128 v[230:233], v201 offset:55296
	ds_read_b128 v[234:237], v201 offset:56320
	global_load_lds_dwordx4 v[174:175], off
	s_add_i32 m0, s56, 0x2000
	s_add_u32 s52, s52, 0x40080
	v_lshl_add_u64 v[174:175], v[240:241], 0, s[16:17]
	s_addc_u32 s53, s53, 0
	s_add_i32 s56, s75, s3
	global_load_lds_dwordx4 v[174:175], off
	v_lshl_add_u64 v[174:175], s[52:53], 0, v[146:147]
	s_mov_b32 m0, s56
	s_nop 0
	global_load_lds_dwordx4 v[174:175], off
	v_lshl_add_u64 v[174:175], s[52:53], 0, v[150:151]
	s_add_i32 m0, s56, 0x2000
	s_nop 0
	global_load_lds_dwordx4 v[174:175], off
	v_lshl_add_u64 v[174:175], v[242:243], 0, s[16:17]
	s_mov_b32 m0, s62
	s_nop 0
	global_load_lds_dwordx4 v[174:175], off
	v_lshl_add_u64 v[174:175], v[248:249], 0, s[16:17]
	s_mov_b32 m0, s63
	s_nop 0
	global_load_lds_dwordx4 v[174:175], off
	s_waitcnt vmcnt(8)
	s_waitcnt lgkmcnt(0)
	s_barrier
	s_setprio 1
	s_waitcnt lgkmcnt(0)
	v_mfma_f32_16x16x32_bf16 v[60:63], v[88:91], v[206:209], v[60:63]
	v_mfma_f32_16x16x32_bf16 v[56:59], v[104:107], v[206:209], v[56:59]
	v_mfma_f32_16x16x32_bf16 v[44:47], v[88:91], v[214:217], v[44:47]
	v_mfma_f32_16x16x32_bf16 v[40:43], v[104:107], v[214:217], v[40:43]
	v_mfma_f32_16x16x32_bf16 v[28:31], v[88:91], v[222:225], v[28:31]
	v_mfma_f32_16x16x32_bf16 v[24:27], v[104:107], v[222:225], v[24:27]
	v_mfma_f32_16x16x32_bf16 v[12:15], v[88:91], v[230:233], v[12:15]
	v_mfma_f32_16x16x32_bf16 v[8:11], v[104:107], v[230:233], v[8:11]
	v_mfma_f32_16x16x32_bf16 v[60:63], v[92:95], v[210:213], v[60:63]
	v_mfma_f32_16x16x32_bf16 v[56:59], v[108:111], v[210:213], v[56:59]
	v_mfma_f32_16x16x32_bf16 v[44:47], v[92:95], v[218:221], v[44:47]
	v_mfma_f32_16x16x32_bf16 v[40:43], v[108:111], v[218:221], v[40:43]
	v_mfma_f32_16x16x32_bf16 v[28:31], v[92:95], v[226:229], v[28:31]
	v_mfma_f32_16x16x32_bf16 v[24:27], v[108:111], v[226:229], v[24:27]
	v_mfma_f32_16x16x32_bf16 v[12:15], v[92:95], v[234:237], v[12:15]
	v_mfma_f32_16x16x32_bf16 v[8:11], v[108:111], v[234:237], v[8:11]
	v_mfma_f32_16x16x32_bf16 v[52:55], v[162:165], v[206:209], v[52:55]
	v_mfma_f32_16x16x32_bf16 v[48:51], v[170:173], v[206:209], v[48:51]
	v_mfma_f32_16x16x32_bf16 v[36:39], v[162:165], v[214:217], v[36:39]
	v_mfma_f32_16x16x32_bf16 v[32:35], v[170:173], v[214:217], v[32:35]
	v_mfma_f32_16x16x32_bf16 v[20:23], v[162:165], v[222:225], v[20:23]
	v_mfma_f32_16x16x32_bf16 v[16:19], v[170:173], v[222:225], v[16:19]
	v_mfma_f32_16x16x32_bf16 v[4:7], v[162:165], v[230:233], v[4:7]
	v_mfma_f32_16x16x32_bf16 v[0:3], v[170:173], v[230:233], v[0:3]
	v_mfma_f32_16x16x32_bf16 v[52:55], v[166:169], v[210:213], v[52:55]
	v_mfma_f32_16x16x32_bf16 v[48:51], v[194:197], v[210:213], v[48:51]
	v_mfma_f32_16x16x32_bf16 v[36:39], v[166:169], v[218:221], v[36:39]
	v_mfma_f32_16x16x32_bf16 v[32:35], v[194:197], v[218:221], v[32:35]
	v_mfma_f32_16x16x32_bf16 v[20:23], v[166:169], v[226:229], v[20:23]
	v_mfma_f32_16x16x32_bf16 v[16:19], v[194:197], v[226:229], v[16:19]
	v_mfma_f32_16x16x32_bf16 v[4:7], v[166:169], v[234:237], v[4:7]
	v_mfma_f32_16x16x32_bf16 v[0:3], v[194:197], v[234:237], v[0:3]
	s_setprio 0
	s_barrier
	s_add_i32 s73, s73, 2
	s_add_u32 s40, s40, 0x100
	s_addc_u32 s41, s41, 0
	s_add_u32 s46, s46, 0x100
	s_addc_u32 s47, s47, 0
	s_cmp_gt_u32 s73, 13
	s_cbranch_scc0 .LBB0_1369
	s_and_b64 vcc, exec, s[18:19]
	s_cbranch_vccz .LBB0_1372
	s_barrier

; #define PG8_STAGE(bufoff, gbase, voff) do { _Pragma("unroll") for (int _i = 0; _i < 2; ++_i) \
;         __builtin_amdgcn_global_load_lds((const unsigned*)((const char*)(gbase) + (voff)[_i]), (LAS unsigned*)(lds + (bufoff) + ldsw + _i * 8192), 16, 0, 0); } while (0)
; #define PG8_LDA(dst, b, h) do { _Pragma("unroll") for (int m = 0; m < 4; ++m) _Pragma("unroll") for (int k = 0; k < 2; ++k) dst[m][k] = *(const LAS bf16x8*)(lds + PG8_SA(b, h) + aoff + m * 2048 + k * 1024); } while (0)
; #define PG8_LDB(dst, b, h) do { _Pragma("unroll") for (int n = 0; n < 2; ++n) _Pragma("unroll") for (int k = 0; k < 2; ++k) dst[n][k] = *(const LAS bf16x8*)(lds + PG8_SB(b, h) + boff + n * 2048 + k * 1024); } while (0)
; #define PG8_MMA(ai, bj, At, Bt) do { __builtin_amdgcn_s_setprio(1); _Pragma("unroll") for (int m = 0; m < 4; ++m) _Pragma("unroll") for (int n = 0; n < 2; ++n) _Pragma("unroll") for (int k = 0; k < 2; ++k) \
;         acc[ai][bj][m][n] = __builtin_amdgcn_mfma_f32_16x16x32_bf16(Bt[n][k], At[m][k], acc[ai][bj][m][n], 0, 0, 0); __builtin_amdgcn_s_setprio(0); } while (0)
; #define PG8_WAIT_V(n) asm volatile("s_waitcnt vmcnt(" #n ")" ::: "memory")
; #define PG8_WAIT_L(n) asm volatile("s_waitcnt lgkmcnt(" #n ")" ::: "memory")
; #define PG8_BAR __builtin_amdgcn_s_barrier()
; #define PG8_SCHED __builtin_amdgcn_sched_barrier(0)
; template <class Epi>
; __device__ __forceinline__ void gemm_phase(LAS unsigned char* lds, const Gemm g, const StaticOrder& S, const Epi& E) {
;     ...
;         for (int t = 0; t < nt; t += 2) {
;             const bool last = (t == nt - 2);
;             const char* a1 = cA + (size_t)(t + 1) * kstep;
;             const char* a2 = last ? nA : cA + (size_t)(t + 2) * kstep; const char* b2 = last ? nB : cB + (size_t)(t + 2) * kstep;
;             const char* a3 = a2 + kstep; const char* b3 = b2 + kstep;
;             PG8_LDB(B0, 0, 0); PG8_LDB(B1, 0, 1); PG8_SCHED; PG8_LDA(At, 0, 0); PG8_STAGE(PG8_SA(1, 1), a1 + hstepA, voffA);
;             PG8_WAIT_V(8); PG8_WAIT_L(0); PG8_BAR; PG8_MMA(0, 0, At, B0); PG8_MMA(0, 1, At, B1); PG8_BAR; PG8_SCHED;
;             PG8_LDA(At, 0, 1); PG8_STAGE(PG8_SB(0, 0), b2, voffB); PG8_STAGE(PG8_SB(0, 1), b2 + hstepB, voffB); PG8_STAGE(PG8_SA(0, 0), a2, voffA);
;             PG8_WAIT_V(8); PG8_WAIT_L(0); PG8_BAR; PG8_MMA(1, 0, At, B0); PG8_MMA(1, 1, At, B1); PG8_BAR; PG8_SCHED;
.LBB0_1630:
	ds_read_b128 v[64:67], v232
	ds_read_b128 v[68:71], v232 offset:1024
	ds_read_b128 v[72:75], v232 offset:2048
	ds_read_b128 v[76:79], v232 offset:3072
	ds_read_b128 v[80:83], v233
	ds_read_b128 v[84:87], v233 offset:1024
	ds_read_b128 v[88:91], v233 offset:2048
	ds_read_b128 v[92:95], v233 offset:3072
	s_add_u32 s64, s62, 0xfffc0080
	s_addc_u32 s65, s63, -1
	s_cmp_eq_u32 s79, 12
	s_cselect_b32 s69, s41, s65
	s_cselect_b32 s68, s46, s64
	s_cselect_b32 s65, s39, s61
	s_cselect_b32 s64, s47, s59
	v_lshl_add_u64 v[212:213], s[62:63], 0, v[188:189]
	s_add_i32 m0, s25, 0xc000
	ds_read_b128 v[96:99], v234
	ds_read_b128 v[100:103], v234 offset:1024
	ds_read_b128 v[104:107], v234 offset:2048
	ds_read_b128 v[108:111], v234 offset:3072
	ds_read_b128 v[196:199], v234 offset:4096
	ds_read_b128 v[200:203], v234 offset:5120
	ds_read_b128 v[204:207], v234 offset:6144
	ds_read_b128 v[208:211], v234 offset:7168
	global_load_lds_dwordx4 v[212:213], off
	v_lshl_add_u64 v[212:213], s[62:63], 0, v[190:191]
	s_add_i32 m0, s25, 0xe000
	s_nop 0
	global_load_lds_dwordx4 v[212:213], off
	s_waitcnt vmcnt(8)
	s_waitcnt lgkmcnt(0)
	s_barrier
	s_setprio 1
	s_waitcnt lgkmcnt(0)
	v_mfma_f32_16x16x32_bf16 v[172:175], v[64:67], v[96:99], v[172:175]
	v_mfma_f32_16x16x32_bf16 v[168:171], v[72:75], v[96:99], v[168:171]
	v_mfma_f32_16x16x32_bf16 v[156:159], v[64:67], v[104:107], v[156:159]
	v_mfma_f32_16x16x32_bf16 v[152:155], v[72:75], v[104:107], v[152:155]
	v_mfma_f32_16x16x32_bf16 v[140:143], v[64:67], v[196:199], v[140:143]
	v_mfma_f32_16x16x32_bf16 v[136:139], v[72:75], v[196:199], v[136:139]
	v_mfma_f32_16x16x32_bf16 v[124:127], v[64:67], v[204:207], v[124:127]
	v_mfma_f32_16x16x32_bf16 v[120:123], v[72:75], v[204:207], v[120:123]
	v_mfma_f32_16x16x32_bf16 v[172:175], v[68:71], v[100:103], v[172:175]
	v_mfma_f32_16x16x32_bf16 v[168:171], v[76:79], v[100:103], v[168:171]
	v_mfma_f32_16x16x32_bf16 v[156:159], v[68:71], v[108:111], v[156:159]
	v_mfma_f32_16x16x32_bf16 v[152:155], v[76:79], v[108:111], v[152:155]
	v_mfma_f32_16x16x32_bf16 v[140:143], v[68:71], v[200:203], v[140:143]
	v_mfma_f32_16x16x32_bf16 v[136:139], v[76:79], v[200:203], v[136:139]
	v_mfma_f32_16x16x32_bf16 v[124:127], v[68:71], v[208:211], v[124:127]
	v_mfma_f32_16x16x32_bf16 v[120:123], v[76:79], v[208:211], v[120:123]
	v_mfma_f32_16x16x32_bf16 v[164:167], v[80:83], v[96:99], v[164:167]
	v_mfma_f32_16x16x32_bf16 v[96:99], v[88:91], v[96:99], v[160:163]
	v_mfma_f32_16x16x32_bf16 v[164:167], v[84:87], v[100:103], v[164:167]
	v_mfma_f32_16x16x32_bf16 v[96:99], v[92:95], v[100:103], v[96:99]
	v_mfma_f32_16x16x32_bf16 v[100:103], v[80:83], v[104:107], v[148:151]
	v_mfma_f32_16x16x32_bf16 v[104:107], v[88:91], v[104:107], v[144:147]
	v_mfma_f32_16x16x32_bf16 v[128:131], v[88:91], v[196:199], v[128:131]
	v_mfma_f32_16x16x32_bf16 v[116:119], v[80:83], v[204:207], v[116:119]
	v_mfma_f32_16x16x32_bf16 v[112:115], v[88:91], v[204:207], v[112:115]
	v_mfma_f32_16x16x32_bf16 v[100:103], v[84:87], v[108:111], v[100:103]
	v_mfma_f32_16x16x32_bf16 v[104:107], v[92:95], v[108:111], v[104:107]
	v_mfma_f32_16x16x32_bf16 v[108:111], v[80:83], v[196:199], v[132:135]
	v_mfma_f32_16x16x32_bf16 v[128:131], v[92:95], v[200:203], v[128:131]
	v_mfma_f32_16x16x32_bf16 v[116:119], v[84:87], v[208:211], v[116:119]
	v_mfma_f32_16x16x32_bf16 v[112:115], v[92:95], v[208:211], v[112:115]
	v_mfma_f32_16x16x32_bf16 v[108:111], v[84:87], v[200:203], v[108:111]
	s_setprio 0
	s_barrier
	s_add_i32 s80, s77, s3
	v_lshl_add_u64 v[220:221], s[64:65], 0, v[182:183]
	s_mov_b32 m0, s80
	ds_read_b128 v[132:135], v234 offset:16384
	ds_read_b128 v[144:147], v234 offset:17408
	ds_read_b128 v[148:151], v234 offset:18432
	ds_read_b128 v[160:163], v234 offset:19456
	ds_read_b128 v[196:199], v234 offset:20480
	ds_read_b128 v[200:203], v234 offset:21504
	ds_read_b128 v[204:207], v234 offset:22528
	ds_read_b128 v[208:211], v234 offset:23552
	global_load_lds_dwordx4 v[220:221], off
	s_add_i32 m0, s80, 0x2000
	s_add_u32 s80, s64, 0x40000
	v_lshl_add_u64 v[222:223], s[64:65], 0, v[184:185]
	s_addc_u32 s81, s65, 0
	s_add_i32 s82, s78, s3
	global_load_lds_dwordx4 v[222:223], off
	v_lshl_add_u64 v[212:213], s[80:81], 0, v[182:183]
	s_mov_b32 m0, s82
	v_lshl_add_u64 v[224:225], s[68:69], 0, v[182:183]
	global_load_lds_dwordx4 v[212:213], off
	v_lshl_add_u64 v[212:213], s[80:81], 0, v[184:185]
	s_add_i32 m0, s82, 0x2000
	v_lshl_add_u64 v[226:227], s[68:69], 0, v[184:185]
	global_load_lds_dwordx4 v[212:213], off
	s_mov_b32 m0, s25
	s_nop 0
	global_load_lds_dwordx4 v[224:225], off
	s_mov_b32 m0, s33
	s_nop 0
	global_load_lds_dwordx4 v[226:227], off
	s_waitcnt vmcnt(8)
	s_waitcnt lgkmcnt(0)
	s_barrier
; #define PG8_STAGE(bufoff, gbase, voff) do { _Pragma("unroll") for (int _i = 0; _i < 2; ++_i) \
;         __builtin_amdgcn_global_load_lds((const unsigned*)((const char*)(gbase) + (voff)[_i]), (LAS unsigned*)(lds + (bufoff) + ldsw + _i * 8192), 16, 0, 0); } while (0)
; #define PG8_LDA(dst, b, h) do { _Pragma("unroll") for (int m = 0; m < 4; ++m) _Pragma("unroll") for (int k = 0; k < 2; ++k) dst[m][k] = *(const LAS bf16x8*)(lds + PG8_SA(b, h) + aoff + m * 2048 + k * 1024); } while (0)
; #define PG8_LDB(dst, b, h) do { _Pragma("unroll") for (int n = 0; n < 2; ++n) _Pragma("unroll") for (int k = 0; k < 2; ++k) dst[n][k] = *(const LAS bf16x8*)(lds + PG8_SB(b, h) + boff + n * 2048 + k * 1024); } while (0)
; #define PG8_MMA(ai, bj, At, Bt) do { __builtin_amdgcn_s_setprio(1); _Pragma("unroll") for (int m = 0; m < 4; ++m) _Pragma("unroll") for (int n = 0; n < 2; ++n) _Pragma("unroll") for (int k = 0; k < 2; ++k) \
;         acc[ai][bj][m][n] = __builtin_amdgcn_mfma_f32_16x16x32_bf16(Bt[n][k], At[m][k], acc[ai][bj][m][n], 0, 0, 0); __builtin_amdgcn_s_setprio(0); } while (0)
; #define PG8_WAIT_V(n) asm volatile("s_waitcnt vmcnt(" #n ")" ::: "memory")
; #define PG8_WAIT_L(n) asm volatile("s_waitcnt lgkmcnt(" #n ")" ::: "memory")
; #define PG8_BAR __builtin_amdgcn_s_barrier()
; #define PG8_SCHED __builtin_amdgcn_sched_barrier(0)
; template <class Epi>
; __device__ __forceinline__ void gemm_phase(LAS unsigned char* lds, const Gemm g, const StaticOrder& S, const Epi& E) {
;     ...
;             PG8_WAIT_V(8); PG8_WAIT_L(0); PG8_BAR; PG8_MMA(1, 0, At, B0); PG8_MMA(1, 1, At, B1); PG8_BAR; PG8_SCHED;
;             PG8_LDB(B0, 1, 0); PG8_LDB(B1, 1, 1); PG8_SCHED; PG8_LDA(At, 1, 0); PG8_STAGE(PG8_SA(0, 1), a2 + hstepA, voffA);
;             PG8_WAIT_V(8); PG8_WAIT_L(0); PG8_BAR; PG8_MMA(0, 0, At, B0); PG8_MMA(0, 1, At, B1); PG8_BAR; PG8_SCHED;
	s_setprio 1
	s_waitcnt lgkmcnt(0)
	v_mfma_f32_16x16x32_bf16 v[60:63], v[64:67], v[132:135], v[60:63]
	v_mfma_f32_16x16x32_bf16 v[56:59], v[72:75], v[132:135], v[56:59]
	v_mfma_f32_16x16x32_bf16 v[44:47], v[64:67], v[148:151], v[44:47]
	v_mfma_f32_16x16x32_bf16 v[40:43], v[72:75], v[148:151], v[40:43]
	v_mfma_f32_16x16x32_bf16 v[28:31], v[64:67], v[196:199], v[28:31]
	v_mfma_f32_16x16x32_bf16 v[24:27], v[72:75], v[196:199], v[24:27]
	v_mfma_f32_16x16x32_bf16 v[12:15], v[64:67], v[204:207], v[12:15]
	v_mfma_f32_16x16x32_bf16 v[8:11], v[72:75], v[204:207], v[8:11]
	v_mfma_f32_16x16x32_bf16 v[60:63], v[68:71], v[144:147], v[60:63]
	v_mfma_f32_16x16x32_bf16 v[56:59], v[76:79], v[144:147], v[56:59]
	v_mfma_f32_16x16x32_bf16 v[44:47], v[68:71], v[160:163], v[44:47]
	v_mfma_f32_16x16x32_bf16 v[40:43], v[76:79], v[160:163], v[40:43]
	v_mfma_f32_16x16x32_bf16 v[28:31], v[68:71], v[200:203], v[28:31]
	v_mfma_f32_16x16x32_bf16 v[24:27], v[76:79], v[200:203], v[24:27]
	v_mfma_f32_16x16x32_bf16 v[12:15], v[68:71], v[208:211], v[12:15]
	v_mfma_f32_16x16x32_bf16 v[8:11], v[76:79], v[208:211], v[8:11]
	v_mfma_f32_16x16x32_bf16 v[52:55], v[80:83], v[132:135], v[52:55]
	v_mfma_f32_16x16x32_bf16 v[48:51], v[88:91], v[132:135], v[48:51]
	v_mfma_f32_16x16x32_bf16 v[36:39], v[80:83], v[148:151], v[36:39]
	v_mfma_f32_16x16x32_bf16 v[32:35], v[88:91], v[148:151], v[32:35]
	v_mfma_f32_16x16x32_bf16 v[20:23], v[80:83], v[196:199], v[20:23]
	v_mfma_f32_16x16x32_bf16 v[16:19], v[88:91], v[196:199], v[16:19]
	v_mfma_f32_16x16x32_bf16 v[4:7], v[80:83], v[204:207], v[4:7]
	v_mfma_f32_16x16x32_bf16 v[0:3], v[88:91], v[204:207], v[0:3]
	v_mfma_f32_16x16x32_bf16 v[52:55], v[84:87], v[144:147], v[52:55]
	v_mfma_f32_16x16x32_bf16 v[48:51], v[92:95], v[144:147], v[48:51]
	v_mfma_f32_16x16x32_bf16 v[36:39], v[84:87], v[160:163], v[36:39]
	v_mfma_f32_16x16x32_bf16 v[32:35], v[92:95], v[160:163], v[32:35]
	v_mfma_f32_16x16x32_bf16 v[20:23], v[84:87], v[200:203], v[20:23]
	v_mfma_f32_16x16x32_bf16 v[16:19], v[92:95], v[200:203], v[16:19]
	v_mfma_f32_16x16x32_bf16 v[4:7], v[84:87], v[208:211], v[4:7]
	v_mfma_f32_16x16x32_bf16 v[0:3], v[92:95], v[208:211], v[0:3]
	s_setprio 0
	s_barrier
	s_add_i32 s80, 0, 0x18000
	s_add_i32 s81, 0, 0x1c000
	v_add_u32_e32 v76, s80, v230
	v_add_u32_e32 v92, s81, v230
	ds_read_b128 v[64:67], v76
	ds_read_b128 v[68:71], v76 offset:1024
	ds_read_b128 v[72:75], v76 offset:2048
	ds_read_b128 v[76:79], v76 offset:3072
	ds_read_b128 v[80:83], v92
	ds_read_b128 v[84:87], v92 offset:1024
	ds_read_b128 v[88:91], v92 offset:2048
	ds_read_b128 v[92:95], v92 offset:3072
	s_add_u32 s68, s68, 0x40000
	s_addc_u32 s69, s69, 0
	s_mov_b32 m0, s67
	v_lshl_add_u64 v[148:149], s[68:69], 0, v[182:183]
	ds_read_b128 v[132:135], v234 offset:32768
	ds_read_b128 v[144:147], v234 offset:33792
	ds_read_b128 v[196:199], v234 offset:34816
	ds_read_b128 v[200:203], v234 offset:35840
	ds_read_b128 v[204:207], v234 offset:36864
	ds_read_b128 v[208:211], v234 offset:37888
	ds_read_b128 v[212:215], v234 offset:38912
	ds_read_b128 v[216:219], v234 offset:39936
	global_load_lds_dwordx4 v[148:149], off
	v_lshl_add_u64 v[148:149], s[68:69], 0, v[184:185]
	s_mov_b32 m0, s70
	s_nop 0
	global_load_lds_dwordx4 v[148:149], off
	s_waitcnt vmcnt(8)
	s_waitcnt lgkmcnt(0)
	s_barrier
	s_setprio 1
	s_waitcnt lgkmcnt(0)
	v_mfma_f32_16x16x32_bf16 v[148:151], v[64:67], v[132:135], v[172:175]
	v_mfma_f32_16x16x32_bf16 v[172:175], v[68:71], v[144:147], v[148:151]
	v_mfma_f32_16x16x32_bf16 v[148:151], v[72:75], v[132:135], v[168:171]
	v_mfma_f32_16x16x32_bf16 v[168:171], v[76:79], v[144:147], v[148:151]
	v_mfma_f32_16x16x32_bf16 v[148:151], v[64:67], v[196:199], v[156:159]
	v_mfma_f32_16x16x32_bf16 v[156:159], v[68:71], v[200:203], v[148:151]
	v_mfma_f32_16x16x32_bf16 v[148:151], v[72:75], v[196:199], v[152:155]
	v_mfma_f32_16x16x32_bf16 v[140:143], v[64:67], v[204:207], v[140:143]
	v_mfma_f32_16x16x32_bf16 v[136:139], v[72:75], v[204:207], v[136:139]
	v_mfma_f32_16x16x32_bf16 v[124:127], v[64:67], v[212:215], v[124:127]
	v_mfma_f32_16x16x32_bf16 v[120:123], v[72:75], v[212:215], v[120:123]
	v_mfma_f32_16x16x32_bf16 v[152:155], v[76:79], v[200:203], v[148:151]
	v_mfma_f32_16x16x32_bf16 v[140:143], v[68:71], v[208:211], v[140:143]
	v_mfma_f32_16x16x32_bf16 v[136:139], v[76:79], v[208:211], v[136:139]
	v_mfma_f32_16x16x32_bf16 v[124:127], v[68:71], v[216:219], v[124:127]
	v_mfma_f32_16x16x32_bf16 v[120:123], v[76:79], v[216:219], v[120:123]
	v_mfma_f32_16x16x32_bf16 v[96:99], v[88:91], v[132:135], v[96:99]
	v_mfma_f32_16x16x32_bf16 v[148:151], v[80:83], v[132:135], v[164:167]
	v_mfma_f32_16x16x32_bf16 v[160:163], v[92:95], v[144:147], v[96:99]
	v_mfma_f32_16x16x32_bf16 v[96:99], v[80:83], v[196:199], v[100:103]
	v_mfma_f32_16x16x32_bf16 v[164:167], v[84:87], v[144:147], v[148:151]
	v_mfma_f32_16x16x32_bf16 v[148:151], v[84:87], v[200:203], v[96:99]
	v_mfma_f32_16x16x32_bf16 v[96:99], v[88:91], v[196:199], v[104:107]
	v_mfma_f32_16x16x32_bf16 v[144:147], v[92:95], v[200:203], v[96:99]
	v_mfma_f32_16x16x32_bf16 v[96:99], v[80:83], v[204:207], v[108:111]
	v_mfma_f32_16x16x32_bf16 v[132:135], v[84:87], v[208:211], v[96:99]
	v_mfma_f32_16x16x32_bf16 v[96:99], v[88:91], v[204:207], v[128:131]
	v_mfma_f32_16x16x32_bf16 v[128:131], v[92:95], v[208:211], v[96:99]
	v_mfma_f32_16x16x32_bf16 v[96:99], v[80:83], v[212:215], v[116:119]
	v_mfma_f32_16x16x32_bf16 v[116:119], v[84:87], v[216:219], v[96:99]
	v_mfma_f32_16x16x32_bf16 v[96:99], v[88:91], v[212:215], v[112:115]
	v_mfma_f32_16x16x32_bf16 v[112:115], v[92:95], v[216:219], v[96:99]
	s_setprio 0
	s_barrier
; #define PG8_STAGE(bufoff, gbase, voff) do { _Pragma("unroll") for (int _i = 0; _i < 2; ++_i) \
;         __builtin_amdgcn_global_load_lds((const unsigned*)((const char*)(gbase) + (voff)[_i]), (LAS unsigned*)(lds + (bufoff) + ldsw + _i * 8192), 16, 0, 0); } while (0)
; #define PG8_LDA(dst, b, h) do { _Pragma("unroll") for (int m = 0; m < 4; ++m) _Pragma("unroll") for (int k = 0; k < 2; ++k) dst[m][k] = *(const LAS bf16x8*)(lds + PG8_SA(b, h) + aoff + m * 2048 + k * 1024); } while (0)
; #define PG8_MMA(ai, bj, At, Bt) do { __builtin_amdgcn_s_setprio(1); _Pragma("unroll") for (int m = 0; m < 4; ++m) _Pragma("unroll") for (int n = 0; n < 2; ++n) _Pragma("unroll") for (int k = 0; k < 2; ++k) \
;         acc[ai][bj][m][n] = __builtin_amdgcn_mfma_f32_16x16x32_bf16(Bt[n][k], At[m][k], acc[ai][bj][m][n], 0, 0, 0); __builtin_amdgcn_s_setprio(0); } while (0)
; #define PG8_WAIT_V(n) asm volatile("s_waitcnt vmcnt(" #n ")" ::: "memory")
; #define PG8_WAIT_L(n) asm volatile("s_waitcnt lgkmcnt(" #n ")" ::: "memory")
; #define PG8_BAR __builtin_amdgcn_s_barrier()
; #define PG8_SCHED __builtin_amdgcn_sched_barrier(0)
; template <class Epi>
; __device__ __forceinline__ void gemm_phase(LAS unsigned char* lds, const Gemm g, const StaticOrder& S, const Epi& E) {
;     ...
;             PG8_LDA(At, 1, 1); PG8_STAGE(PG8_SB(1, 0), b3, voffB); PG8_STAGE(PG8_SB(1, 1), b3 + hstepB, voffB); PG8_STAGE(PG8_SA(1, 0), a3, voffA);
;             PG8_WAIT_V(8); PG8_WAIT_L(0); PG8_BAR; PG8_MMA(1, 0, At, B0); PG8_MMA(1, 1, At, B1); PG8_BAR; PG8_SCHED;
;         }
;         if (wr == 0) PG8_BAR;
	s_add_i32 s68, s80, s3
	v_lshl_add_u64 v[212:213], v[220:221], 0, s[34:35]
	s_mov_b32 m0, s68
	s_nop 1
	ds_read_b128 v[96:99], v234 offset:49152
	ds_read_b128 v[100:103], v234 offset:50176
	ds_read_b128 v[104:107], v234 offset:51200
	ds_read_b128 v[108:111], v234 offset:52224
	ds_read_b128 v[196:199], v234 offset:53248
	ds_read_b128 v[200:203], v234 offset:54272
	ds_read_b128 v[204:207], v234 offset:55296
	ds_read_b128 v[208:211], v234 offset:56320
	global_load_lds_dwordx4 v[212:213], off
	s_add_i32 m0, s68, 0x2000
	s_add_u32 s64, s64, 0x40080
	v_lshl_add_u64 v[212:213], v[222:223], 0, s[34:35]
	s_addc_u32 s65, s65, 0
	s_add_i32 s68, s81, s3
	global_load_lds_dwordx4 v[212:213], off
	v_lshl_add_u64 v[212:213], s[64:65], 0, v[182:183]
	s_mov_b32 m0, s68
	s_nop 0
	global_load_lds_dwordx4 v[212:213], off
	v_lshl_add_u64 v[212:213], s[64:65], 0, v[184:185]
	s_add_i32 m0, s68, 0x2000
	s_nop 0
	global_load_lds_dwordx4 v[212:213], off
	v_lshl_add_u64 v[212:213], v[224:225], 0, s[34:35]
	s_mov_b32 m0, s72
	s_nop 0
	global_load_lds_dwordx4 v[212:213], off
	v_lshl_add_u64 v[212:213], v[226:227], 0, s[34:35]
	s_mov_b32 m0, s73
	s_nop 0
	global_load_lds_dwordx4 v[212:213], off
	s_waitcnt vmcnt(8)
	s_waitcnt lgkmcnt(0)
	s_barrier
	s_setprio 1
	s_waitcnt lgkmcnt(0)
	v_mfma_f32_16x16x32_bf16 v[60:63], v[64:67], v[96:99], v[60:63]
	v_mfma_f32_16x16x32_bf16 v[56:59], v[72:75], v[96:99], v[56:59]
	v_mfma_f32_16x16x32_bf16 v[44:47], v[64:67], v[104:107], v[44:47]
	v_mfma_f32_16x16x32_bf16 v[40:43], v[72:75], v[104:107], v[40:43]
	v_mfma_f32_16x16x32_bf16 v[28:31], v[64:67], v[196:199], v[28:31]
	v_mfma_f32_16x16x32_bf16 v[24:27], v[72:75], v[196:199], v[24:27]
	v_mfma_f32_16x16x32_bf16 v[12:15], v[64:67], v[204:207], v[12:15]
	v_mfma_f32_16x16x32_bf16 v[8:11], v[72:75], v[204:207], v[8:11]
	v_mfma_f32_16x16x32_bf16 v[60:63], v[68:71], v[100:103], v[60:63]
	v_mfma_f32_16x16x32_bf16 v[56:59], v[76:79], v[100:103], v[56:59]
	v_mfma_f32_16x16x32_bf16 v[44:47], v[68:71], v[108:111], v[44:47]
	v_mfma_f32_16x16x32_bf16 v[40:43], v[76:79], v[108:111], v[40:43]
	v_mfma_f32_16x16x32_bf16 v[28:31], v[68:71], v[200:203], v[28:31]
	v_mfma_f32_16x16x32_bf16 v[24:27], v[76:79], v[200:203], v[24:27]
	v_mfma_f32_16x16x32_bf16 v[12:15], v[68:71], v[208:211], v[12:15]
	v_mfma_f32_16x16x32_bf16 v[8:11], v[76:79], v[208:211], v[8:11]
	v_mfma_f32_16x16x32_bf16 v[52:55], v[80:83], v[96:99], v[52:55]
	v_mfma_f32_16x16x32_bf16 v[48:51], v[88:91], v[96:99], v[48:51]
	v_mfma_f32_16x16x32_bf16 v[36:39], v[80:83], v[104:107], v[36:39]
	v_mfma_f32_16x16x32_bf16 v[32:35], v[88:91], v[104:107], v[32:35]
	v_mfma_f32_16x16x32_bf16 v[20:23], v[80:83], v[196:199], v[20:23]
	v_mfma_f32_16x16x32_bf16 v[16:19], v[88:91], v[196:199], v[16:19]
	v_mfma_f32_16x16x32_bf16 v[4:7], v[80:83], v[204:207], v[4:7]
	v_mfma_f32_16x16x32_bf16 v[0:3], v[88:91], v[204:207], v[0:3]
	v_mfma_f32_16x16x32_bf16 v[52:55], v[84:87], v[100:103], v[52:55]
	v_mfma_f32_16x16x32_bf16 v[48:51], v[92:95], v[100:103], v[48:51]
	v_mfma_f32_16x16x32_bf16 v[36:39], v[84:87], v[108:111], v[36:39]
	v_mfma_f32_16x16x32_bf16 v[32:35], v[92:95], v[108:111], v[32:35]
	v_mfma_f32_16x16x32_bf16 v[20:23], v[84:87], v[200:203], v[20:23]
	v_mfma_f32_16x16x32_bf16 v[16:19], v[92:95], v[200:203], v[16:19]
	v_mfma_f32_16x16x32_bf16 v[4:7], v[84:87], v[208:211], v[4:7]
	v_mfma_f32_16x16x32_bf16 v[0:3], v[92:95], v[208:211], v[0:3]
	s_setprio 0
	s_barrier
	s_add_i32 s79, s79, 2
	s_add_u32 s62, s62, 0x100
	s_addc_u32 s63, s63, 0
	s_add_u32 s59, s59, 0x100
	s_addc_u32 s61, s61, 0
	s_cmp_gt_u32 s79, 13
	s_cbranch_scc0 .LBB0_1630
	s_and_b64 vcc, exec, s[36:37]
	s_cbranch_vccz .LBB0_1633
	s_barrier

; #define PG8_STAGE(bufoff, gbase, voff) do { _Pragma("unroll") for (int _i = 0; _i < 2; ++_i) \
;         __builtin_amdgcn_global_load_lds((const unsigned*)((const char*)(gbase) + (voff)[_i]), (LAS unsigned*)(lds + (bufoff) + ldsw + _i * 8192), 16, 0, 0); } while (0)
; #define PG8_LDA(dst, b, h) do { _Pragma("unroll") for (int m = 0; m < 4; ++m) _Pragma("unroll") for (int k = 0; k < 2; ++k) dst[m][k] = *(const LAS bf16x8*)(lds + PG8_SA(b, h) + aoff + m * 2048 + k * 1024); } while (0)
; #define PG8_LDB(dst, b, h) do { _Pragma("unroll") for (int n = 0; n < 2; ++n) _Pragma("unroll") for (int k = 0; k < 2; ++k) dst[n][k] = *(const LAS bf16x8*)(lds + PG8_SB(b, h) + boff + n * 2048 + k * 1024); } while (0)
; #define PG8_MMA(ai, bj, At, Bt) do { __builtin_amdgcn_s_setprio(1); _Pragma("unroll") for (int m = 0; m < 4; ++m) _Pragma("unroll") for (int n = 0; n < 2; ++n) _Pragma("unroll") for (int k = 0; k < 2; ++k) \
;         acc[ai][bj][m][n] = __builtin_amdgcn_mfma_f32_16x16x32_bf16(Bt[n][k], At[m][k], acc[ai][bj][m][n], 0, 0, 0); __builtin_amdgcn_s_setprio(0); } while (0)
; #define PG8_WAIT_V(n) asm volatile("s_waitcnt vmcnt(" #n ")" ::: "memory")
; #define PG8_WAIT_L(n) asm volatile("s_waitcnt lgkmcnt(" #n ")" ::: "memory")
; #define PG8_BAR __builtin_amdgcn_s_barrier()
; #define PG8_SCHED __builtin_amdgcn_sched_barrier(0)
; template <class Epi>
; __device__ __forceinline__ void gemm_phase(LAS unsigned char* lds, const Gemm g, const StaticOrder& S, const Epi& E) {
;     ...
;         for (int t = 0; t < nt; t += 2) {
;             const bool last = (t == nt - 2);
;             const char* a1 = cA + (size_t)(t + 1) * kstep;
;             const char* a2 = last ? nA : cA + (size_t)(t + 2) * kstep; const char* b2 = last ? nB : cB + (size_t)(t + 2) * kstep;
;             const char* a3 = a2 + kstep; const char* b3 = b2 + kstep;
;             PG8_LDB(B0, 0, 0); PG8_LDB(B1, 0, 1); PG8_SCHED; PG8_LDA(At, 0, 0); PG8_STAGE(PG8_SA(1, 1), a1 + hstepA, voffA);
;             PG8_WAIT_V(8); PG8_WAIT_L(0); PG8_BAR; PG8_MMA(0, 0, At, B0); PG8_MMA(0, 1, At, B1); PG8_BAR; PG8_SCHED;
;             PG8_LDA(At, 0, 1); PG8_STAGE(PG8_SB(0, 0), b2, voffB); PG8_STAGE(PG8_SB(0, 1), b2 + hstepB, voffB); PG8_STAGE(PG8_SA(0, 0), a2, voffA);
;             PG8_WAIT_V(8); PG8_WAIT_L(0); PG8_BAR; PG8_MMA(1, 0, At, B0); PG8_MMA(1, 1, At, B1); PG8_BAR; PG8_SCHED;
.LBB0_1722:
	ds_read_b128 v[128:131], v183
	ds_read_b128 v[132:135], v183 offset:1024
	ds_read_b128 v[136:139], v183 offset:2048
	ds_read_b128 v[140:143], v183 offset:3072
	ds_read_b128 v[164:167], v184
	ds_read_b128 v[168:171], v184 offset:1024
	ds_read_b128 v[172:175], v184 offset:2048
	ds_read_b128 v[188:191], v184 offset:3072
	s_add_u32 s30, s28, 0xfffc0080
	s_addc_u32 s31, s29, -1
	s_cmp_eq_u32 s64, 12
	s_cselect_b32 s35, s21, s31
	s_cselect_b32 s34, s60, s30
	s_cselect_b32 s31, s19, s63
	s_cselect_b32 s30, s61, s62
	v_lshl_add_u64 v[224:225], s[28:29], 0, v[156:157]
	s_add_i32 m0, s38, 0xc000
	ds_read_b128 v[192:195], v185
	ds_read_b128 v[196:199], v185 offset:1024
	ds_read_b128 v[200:203], v185 offset:2048
	ds_read_b128 v[204:207], v185 offset:3072
	ds_read_b128 v[208:211], v185 offset:4096
	ds_read_b128 v[212:215], v185 offset:5120
	ds_read_b128 v[216:219], v185 offset:6144
	ds_read_b128 v[220:223], v185 offset:7168
	global_load_lds_dwordx4 v[224:225], off
	v_lshl_add_u64 v[224:225], s[28:29], 0, v[158:159]
	s_add_i32 m0, s38, 0xe000
	s_nop 0
	global_load_lds_dwordx4 v[224:225], off
	s_waitcnt vmcnt(8)
	s_waitcnt lgkmcnt(0)
	s_barrier
	s_setprio 1
	s_waitcnt lgkmcnt(0)
	v_mfma_f32_16x16x32_bf16 v[124:127], v[128:131], v[192:195], v[124:127]
	v_mfma_f32_16x16x32_bf16 v[120:123], v[136:139], v[192:195], v[120:123]
	v_mfma_f32_16x16x32_bf16 v[108:111], v[128:131], v[200:203], v[108:111]
	v_mfma_f32_16x16x32_bf16 v[104:107], v[136:139], v[200:203], v[104:107]
	v_mfma_f32_16x16x32_bf16 v[92:95], v[128:131], v[208:211], v[92:95]
	v_mfma_f32_16x16x32_bf16 v[88:91], v[136:139], v[208:211], v[88:91]
	v_mfma_f32_16x16x32_bf16 v[76:79], v[128:131], v[216:219], v[76:79]
	v_mfma_f32_16x16x32_bf16 v[72:75], v[136:139], v[216:219], v[72:75]
	v_mfma_f32_16x16x32_bf16 v[124:127], v[132:135], v[196:199], v[124:127]
	v_mfma_f32_16x16x32_bf16 v[120:123], v[140:143], v[196:199], v[120:123]
	v_mfma_f32_16x16x32_bf16 v[108:111], v[132:135], v[204:207], v[108:111]
	v_mfma_f32_16x16x32_bf16 v[104:107], v[140:143], v[204:207], v[104:107]
	v_mfma_f32_16x16x32_bf16 v[92:95], v[132:135], v[212:215], v[92:95]
	v_mfma_f32_16x16x32_bf16 v[88:91], v[140:143], v[212:215], v[88:91]
	v_mfma_f32_16x16x32_bf16 v[76:79], v[132:135], v[220:223], v[76:79]
	v_mfma_f32_16x16x32_bf16 v[72:75], v[140:143], v[220:223], v[72:75]
	v_mfma_f32_16x16x32_bf16 v[116:119], v[164:167], v[192:195], v[116:119]
	v_mfma_f32_16x16x32_bf16 v[112:115], v[172:175], v[192:195], v[112:115]
	v_mfma_f32_16x16x32_bf16 v[100:103], v[164:167], v[200:203], v[100:103]
	v_mfma_f32_16x16x32_bf16 v[96:99], v[172:175], v[200:203], v[96:99]
	v_mfma_f32_16x16x32_bf16 v[84:87], v[164:167], v[208:211], v[84:87]
	v_mfma_f32_16x16x32_bf16 v[80:83], v[172:175], v[208:211], v[80:83]
	v_mfma_f32_16x16x32_bf16 v[68:71], v[164:167], v[216:219], v[68:71]
	v_mfma_f32_16x16x32_bf16 v[64:67], v[172:175], v[216:219], v[64:67]
	v_mfma_f32_16x16x32_bf16 v[116:119], v[168:171], v[196:199], v[116:119]
	v_mfma_f32_16x16x32_bf16 v[112:115], v[188:191], v[196:199], v[112:115]
	v_mfma_f32_16x16x32_bf16 v[100:103], v[168:171], v[204:207], v[100:103]
	v_mfma_f32_16x16x32_bf16 v[96:99], v[188:191], v[204:207], v[96:99]
	v_mfma_f32_16x16x32_bf16 v[84:87], v[168:171], v[212:215], v[84:87]
	v_mfma_f32_16x16x32_bf16 v[80:83], v[188:191], v[212:215], v[80:83]
	v_mfma_f32_16x16x32_bf16 v[68:71], v[168:171], v[220:223], v[68:71]
	v_mfma_f32_16x16x32_bf16 v[64:67], v[188:191], v[220:223], v[64:67]
	s_setprio 0
	s_barrier
	s_add_i32 s65, s55, s33
	v_lshl_add_u64 v[224:225], s[30:31], 0, v[148:149]
	s_mov_b32 m0, s65
	ds_read_b128 v[192:195], v185 offset:16384
	ds_read_b128 v[196:199], v185 offset:17408
	ds_read_b128 v[200:203], v185 offset:18432
	ds_read_b128 v[204:207], v185 offset:19456
	ds_read_b128 v[208:211], v185 offset:20480
	ds_read_b128 v[212:215], v185 offset:21504
	ds_read_b128 v[216:219], v185 offset:22528
	ds_read_b128 v[220:223], v185 offset:23552
	global_load_lds_dwordx4 v[224:225], off
	s_add_i32 m0, s65, 0x2000
	s_add_u32 s68, s30, 0x40000
	v_lshl_add_u64 v[226:227], s[30:31], 0, v[144:145]
	s_addc_u32 s69, s31, 0
	s_add_i32 s65, s56, s33
	global_load_lds_dwordx4 v[226:227], off
	v_lshl_add_u64 v[230:231], s[68:69], 0, v[148:149]
	s_mov_b32 m0, s65
	v_lshl_add_u64 v[232:233], s[34:35], 0, v[146:147]
	global_load_lds_dwordx4 v[230:231], off
	v_lshl_add_u64 v[230:231], s[68:69], 0, v[144:145]
	s_add_i32 m0, s65, 0x2000
	s_nop 0
	global_load_lds_dwordx4 v[230:231], off
	v_lshl_add_u64 v[230:231], s[34:35], 0, v[150:151]
	s_mov_b32 m0, s38
	s_nop 0
	global_load_lds_dwordx4 v[230:231], off
	s_mov_b32 m0, s39
	s_nop 0
	global_load_lds_dwordx4 v[232:233], off
	s_waitcnt vmcnt(8)
	s_waitcnt lgkmcnt(0)
	s_barrier
; #define PG8_STAGE(bufoff, gbase, voff) do { _Pragma("unroll") for (int _i = 0; _i < 2; ++_i) \
;         __builtin_amdgcn_global_load_lds((const unsigned*)((const char*)(gbase) + (voff)[_i]), (LAS unsigned*)(lds + (bufoff) + ldsw + _i * 8192), 16, 0, 0); } while (0)
; #define PG8_LDA(dst, b, h) do { _Pragma("unroll") for (int m = 0; m < 4; ++m) _Pragma("unroll") for (int k = 0; k < 2; ++k) dst[m][k] = *(const LAS bf16x8*)(lds + PG8_SA(b, h) + aoff + m * 2048 + k * 1024); } while (0)
; #define PG8_LDB(dst, b, h) do { _Pragma("unroll") for (int n = 0; n < 2; ++n) _Pragma("unroll") for (int k = 0; k < 2; ++k) dst[n][k] = *(const LAS bf16x8*)(lds + PG8_SB(b, h) + boff + n * 2048 + k * 1024); } while (0)
; #define PG8_MMA(ai, bj, At, Bt) do { __builtin_amdgcn_s_setprio(1); _Pragma("unroll") for (int m = 0; m < 4; ++m) _Pragma("unroll") for (int n = 0; n < 2; ++n) _Pragma("unroll") for (int k = 0; k < 2; ++k) \
;         acc[ai][bj][m][n] = __builtin_amdgcn_mfma_f32_16x16x32_bf16(Bt[n][k], At[m][k], acc[ai][bj][m][n], 0, 0, 0); __builtin_amdgcn_s_setprio(0); } while (0)
; #define PG8_WAIT_V(n) asm volatile("s_waitcnt vmcnt(" #n ")" ::: "memory")
; #define PG8_WAIT_L(n) asm volatile("s_waitcnt lgkmcnt(" #n ")" ::: "memory")
; #define PG8_BAR __builtin_amdgcn_s_barrier()
; #define PG8_SCHED __builtin_amdgcn_sched_barrier(0)
; template <class Epi>
; __device__ __forceinline__ void gemm_phase(LAS unsigned char* lds, const Gemm g, const StaticOrder& S, const Epi& E) {
;     ...
;             PG8_WAIT_V(8); PG8_WAIT_L(0); PG8_BAR; PG8_MMA(1, 0, At, B0); PG8_MMA(1, 1, At, B1); PG8_BAR; PG8_SCHED;
;             PG8_LDB(B0, 1, 0); PG8_LDB(B1, 1, 1); PG8_SCHED; PG8_LDA(At, 1, 0); PG8_STAGE(PG8_SA(0, 1), a2 + hstepA, voffA);
;             PG8_WAIT_V(8); PG8_WAIT_L(0); PG8_BAR; PG8_MMA(0, 0, At, B0); PG8_MMA(0, 1, At, B1); PG8_BAR; PG8_SCHED;
	s_setprio 1
	s_waitcnt lgkmcnt(0)
	v_mfma_f32_16x16x32_bf16 v[60:63], v[128:131], v[192:195], v[60:63]
	v_mfma_f32_16x16x32_bf16 v[56:59], v[136:139], v[192:195], v[56:59]
	v_mfma_f32_16x16x32_bf16 v[44:47], v[128:131], v[200:203], v[44:47]
	v_mfma_f32_16x16x32_bf16 v[40:43], v[136:139], v[200:203], v[40:43]
	v_mfma_f32_16x16x32_bf16 v[28:31], v[128:131], v[208:211], v[28:31]
	v_mfma_f32_16x16x32_bf16 v[24:27], v[136:139], v[208:211], v[24:27]
	v_mfma_f32_16x16x32_bf16 v[12:15], v[128:131], v[216:219], v[12:15]
	v_mfma_f32_16x16x32_bf16 v[8:11], v[136:139], v[216:219], v[8:11]
	v_mfma_f32_16x16x32_bf16 v[60:63], v[132:135], v[196:199], v[60:63]
	v_mfma_f32_16x16x32_bf16 v[56:59], v[140:143], v[196:199], v[56:59]
	v_mfma_f32_16x16x32_bf16 v[44:47], v[132:135], v[204:207], v[44:47]
	v_mfma_f32_16x16x32_bf16 v[40:43], v[140:143], v[204:207], v[40:43]
	v_mfma_f32_16x16x32_bf16 v[28:31], v[132:135], v[212:215], v[28:31]
	v_mfma_f32_16x16x32_bf16 v[24:27], v[140:143], v[212:215], v[24:27]
	v_mfma_f32_16x16x32_bf16 v[12:15], v[132:135], v[220:223], v[12:15]
	v_mfma_f32_16x16x32_bf16 v[8:11], v[140:143], v[220:223], v[8:11]
	v_mfma_f32_16x16x32_bf16 v[52:55], v[164:167], v[192:195], v[52:55]
	v_mfma_f32_16x16x32_bf16 v[48:51], v[172:175], v[192:195], v[48:51]
	v_mfma_f32_16x16x32_bf16 v[36:39], v[164:167], v[200:203], v[36:39]
	v_mfma_f32_16x16x32_bf16 v[32:35], v[172:175], v[200:203], v[32:35]
	v_mfma_f32_16x16x32_bf16 v[20:23], v[164:167], v[208:211], v[20:23]
	v_mfma_f32_16x16x32_bf16 v[16:19], v[172:175], v[208:211], v[16:19]
	v_mfma_f32_16x16x32_bf16 v[4:7], v[164:167], v[216:219], v[4:7]
	v_mfma_f32_16x16x32_bf16 v[0:3], v[172:175], v[216:219], v[0:3]
	v_mfma_f32_16x16x32_bf16 v[52:55], v[168:171], v[196:199], v[52:55]
	v_mfma_f32_16x16x32_bf16 v[48:51], v[188:191], v[196:199], v[48:51]
	v_mfma_f32_16x16x32_bf16 v[36:39], v[168:171], v[204:207], v[36:39]
	v_mfma_f32_16x16x32_bf16 v[32:35], v[188:191], v[204:207], v[32:35]
	v_mfma_f32_16x16x32_bf16 v[20:23], v[168:171], v[212:215], v[20:23]
	v_mfma_f32_16x16x32_bf16 v[16:19], v[188:191], v[212:215], v[16:19]
	v_mfma_f32_16x16x32_bf16 v[4:7], v[168:171], v[220:223], v[4:7]
	v_mfma_f32_16x16x32_bf16 v[0:3], v[188:191], v[220:223], v[0:3]
	s_setprio 0
	s_barrier
	s_add_i32 s65, 0, 0x18000
	s_add_i32 s67, 0, 0x1c000
	v_add_u32_e32 v140, s65, v182
	v_add_u32_e32 v152, s67, v182
	ds_read_b128 v[128:131], v140
	ds_read_b128 v[132:135], v140 offset:1024
	ds_read_b128 v[136:139], v140 offset:2048
	ds_read_b128 v[140:143], v140 offset:3072
	ds_read_b128 v[164:167], v152
	ds_read_b128 v[168:171], v152 offset:1024
	ds_read_b128 v[172:175], v152 offset:2048
	ds_read_b128 v[188:191], v152 offset:3072
	s_add_u32 s34, s34, 0x40000
	s_addc_u32 s35, s35, 0
	s_mov_b32 m0, s40
	v_lshl_add_u64 v[234:235], s[34:35], 0, v[150:151]
	ds_read_b128 v[192:195], v185 offset:32768
	ds_read_b128 v[196:199], v185 offset:33792
	ds_read_b128 v[200:203], v185 offset:34816
	ds_read_b128 v[204:207], v185 offset:35840
	ds_read_b128 v[208:211], v185 offset:36864
	ds_read_b128 v[212:215], v185 offset:37888
	ds_read_b128 v[216:219], v185 offset:38912
	ds_read_b128 v[220:223], v185 offset:39936
	global_load_lds_dwordx4 v[234:235], off
	v_lshl_add_u64 v[234:235], s[34:35], 0, v[146:147]
	s_mov_b32 m0, s41
	s_nop 0
	global_load_lds_dwordx4 v[234:235], off
	s_waitcnt vmcnt(8)
	s_waitcnt lgkmcnt(0)
	s_barrier
	s_setprio 1
	s_waitcnt lgkmcnt(0)
	v_mfma_f32_16x16x32_bf16 v[124:127], v[128:131], v[192:195], v[124:127]
	v_mfma_f32_16x16x32_bf16 v[120:123], v[136:139], v[192:195], v[120:123]
	v_mfma_f32_16x16x32_bf16 v[108:111], v[128:131], v[200:203], v[108:111]
	v_mfma_f32_16x16x32_bf16 v[104:107], v[136:139], v[200:203], v[104:107]
	v_mfma_f32_16x16x32_bf16 v[92:95], v[128:131], v[208:211], v[92:95]
	v_mfma_f32_16x16x32_bf16 v[88:91], v[136:139], v[208:211], v[88:91]
	v_mfma_f32_16x16x32_bf16 v[76:79], v[128:131], v[216:219], v[76:79]
	v_mfma_f32_16x16x32_bf16 v[72:75], v[136:139], v[216:219], v[72:75]
	v_mfma_f32_16x16x32_bf16 v[124:127], v[132:135], v[196:199], v[124:127]
	v_mfma_f32_16x16x32_bf16 v[120:123], v[140:143], v[196:199], v[120:123]
	v_mfma_f32_16x16x32_bf16 v[108:111], v[132:135], v[204:207], v[108:111]
	v_mfma_f32_16x16x32_bf16 v[104:107], v[140:143], v[204:207], v[104:107]
	v_mfma_f32_16x16x32_bf16 v[92:95], v[132:135], v[212:215], v[92:95]
	v_mfma_f32_16x16x32_bf16 v[88:91], v[140:143], v[212:215], v[88:91]
	v_mfma_f32_16x16x32_bf16 v[76:79], v[132:135], v[220:223], v[76:79]
	v_mfma_f32_16x16x32_bf16 v[72:75], v[140:143], v[220:223], v[72:75]
	v_mfma_f32_16x16x32_bf16 v[116:119], v[164:167], v[192:195], v[116:119]
	v_mfma_f32_16x16x32_bf16 v[112:115], v[172:175], v[192:195], v[112:115]
	v_mfma_f32_16x16x32_bf16 v[100:103], v[164:167], v[200:203], v[100:103]
	v_mfma_f32_16x16x32_bf16 v[96:99], v[172:175], v[200:203], v[96:99]
	v_mfma_f32_16x16x32_bf16 v[84:87], v[164:167], v[208:211], v[84:87]
	v_mfma_f32_16x16x32_bf16 v[80:83], v[172:175], v[208:211], v[80:83]
	v_mfma_f32_16x16x32_bf16 v[68:71], v[164:167], v[216:219], v[68:71]
	v_mfma_f32_16x16x32_bf16 v[64:67], v[172:175], v[216:219], v[64:67]
	v_mfma_f32_16x16x32_bf16 v[116:119], v[168:171], v[196:199], v[116:119]
	v_mfma_f32_16x16x32_bf16 v[112:115], v[188:191], v[196:199], v[112:115]
	v_mfma_f32_16x16x32_bf16 v[100:103], v[168:171], v[204:207], v[100:103]
	v_mfma_f32_16x16x32_bf16 v[96:99], v[188:191], v[204:207], v[96:99]
	v_mfma_f32_16x16x32_bf16 v[84:87], v[168:171], v[212:215], v[84:87]
	v_mfma_f32_16x16x32_bf16 v[80:83], v[188:191], v[212:215], v[80:83]
	v_mfma_f32_16x16x32_bf16 v[68:71], v[168:171], v[220:223], v[68:71]
	v_mfma_f32_16x16x32_bf16 v[64:67], v[188:191], v[220:223], v[64:67]
	s_setprio 0
	s_barrier
; #define PG8_STAGE(bufoff, gbase, voff) do { _Pragma("unroll") for (int _i = 0; _i < 2; ++_i) \
;         __builtin_amdgcn_global_load_lds((const unsigned*)((const char*)(gbase) + (voff)[_i]), (LAS unsigned*)(lds + (bufoff) + ldsw + _i * 8192), 16, 0, 0); } while (0)
; #define PG8_LDA(dst, b, h) do { _Pragma("unroll") for (int m = 0; m < 4; ++m) _Pragma("unroll") for (int k = 0; k < 2; ++k) dst[m][k] = *(const LAS bf16x8*)(lds + PG8_SA(b, h) + aoff + m * 2048 + k * 1024); } while (0)
; #define PG8_MMA(ai, bj, At, Bt) do { __builtin_amdgcn_s_setprio(1); _Pragma("unroll") for (int m = 0; m < 4; ++m) _Pragma("unroll") for (int n = 0; n < 2; ++n) _Pragma("unroll") for (int k = 0; k < 2; ++k) \
;         acc[ai][bj][m][n] = __builtin_amdgcn_mfma_f32_16x16x32_bf16(Bt[n][k], At[m][k], acc[ai][bj][m][n], 0, 0, 0); __builtin_amdgcn_s_setprio(0); } while (0)
; #define PG8_WAIT_V(n) asm volatile("s_waitcnt vmcnt(" #n ")" ::: "memory")
; #define PG8_WAIT_L(n) asm volatile("s_waitcnt lgkmcnt(" #n ")" ::: "memory")
; #define PG8_BAR __builtin_amdgcn_s_barrier()
; #define PG8_SCHED __builtin_amdgcn_sched_barrier(0)
; template <class Epi>
; __device__ __forceinline__ void gemm_phase(LAS unsigned char* lds, const Gemm g, const StaticOrder& S, const Epi& E) {
;     ...
;             PG8_LDA(At, 1, 1); PG8_STAGE(PG8_SB(1, 0), b3, voffB); PG8_STAGE(PG8_SB(1, 1), b3 + hstepB, voffB); PG8_STAGE(PG8_SA(1, 0), a3, voffA);
;             PG8_WAIT_V(8); PG8_WAIT_L(0); PG8_BAR; PG8_MMA(1, 0, At, B0); PG8_MMA(1, 1, At, B1); PG8_BAR; PG8_SCHED;
;         }
;         if (wr == 0) PG8_BAR;
	s_add_i32 s34, s65, s33
	v_lshl_add_u64 v[224:225], v[224:225], 0, s[14:15]
	s_mov_b32 m0, s34
	ds_read_b128 v[192:195], v185 offset:49152
	ds_read_b128 v[196:199], v185 offset:50176
	ds_read_b128 v[200:203], v185 offset:51200
	ds_read_b128 v[204:207], v185 offset:52224
	ds_read_b128 v[208:211], v185 offset:53248
	ds_read_b128 v[212:215], v185 offset:54272
	ds_read_b128 v[216:219], v185 offset:55296
	ds_read_b128 v[220:223], v185 offset:56320
	global_load_lds_dwordx4 v[224:225], off
	s_add_i32 m0, s34, 0x2000
	s_add_u32 s30, s30, 0x40080
	v_lshl_add_u64 v[224:225], v[226:227], 0, s[14:15]
	s_addc_u32 s31, s31, 0
	s_add_i32 s34, s67, s33
	global_load_lds_dwordx4 v[224:225], off
	v_lshl_add_u64 v[224:225], s[30:31], 0, v[148:149]
	s_mov_b32 m0, s34
	s_nop 0
	global_load_lds_dwordx4 v[224:225], off
	v_lshl_add_u64 v[224:225], s[30:31], 0, v[144:145]
	s_add_i32 m0, s34, 0x2000
	s_nop 0
	global_load_lds_dwordx4 v[224:225], off
	v_lshl_add_u64 v[224:225], v[230:231], 0, s[14:15]
	s_mov_b32 m0, s47
	s_nop 0
	global_load_lds_dwordx4 v[224:225], off
	v_lshl_add_u64 v[224:225], v[232:233], 0, s[14:15]
	s_mov_b32 m0, s52
	s_nop 0
	global_load_lds_dwordx4 v[224:225], off
	s_waitcnt vmcnt(8)
	s_waitcnt lgkmcnt(0)
	s_barrier
	s_setprio 1
	s_waitcnt lgkmcnt(0)
	v_mfma_f32_16x16x32_bf16 v[60:63], v[128:131], v[192:195], v[60:63]
	v_mfma_f32_16x16x32_bf16 v[56:59], v[136:139], v[192:195], v[56:59]
	v_mfma_f32_16x16x32_bf16 v[44:47], v[128:131], v[200:203], v[44:47]
	v_mfma_f32_16x16x32_bf16 v[40:43], v[136:139], v[200:203], v[40:43]
	v_mfma_f32_16x16x32_bf16 v[28:31], v[128:131], v[208:211], v[28:31]
	v_mfma_f32_16x16x32_bf16 v[24:27], v[136:139], v[208:211], v[24:27]
	v_mfma_f32_16x16x32_bf16 v[12:15], v[128:131], v[216:219], v[12:15]
	v_mfma_f32_16x16x32_bf16 v[8:11], v[136:139], v[216:219], v[8:11]
	v_mfma_f32_16x16x32_bf16 v[60:63], v[132:135], v[196:199], v[60:63]
	v_mfma_f32_16x16x32_bf16 v[56:59], v[140:143], v[196:199], v[56:59]
	v_mfma_f32_16x16x32_bf16 v[44:47], v[132:135], v[204:207], v[44:47]
	v_mfma_f32_16x16x32_bf16 v[40:43], v[140:143], v[204:207], v[40:43]
	v_mfma_f32_16x16x32_bf16 v[28:31], v[132:135], v[212:215], v[28:31]
	v_mfma_f32_16x16x32_bf16 v[24:27], v[140:143], v[212:215], v[24:27]
	v_mfma_f32_16x16x32_bf16 v[12:15], v[132:135], v[220:223], v[12:15]
	v_mfma_f32_16x16x32_bf16 v[8:11], v[140:143], v[220:223], v[8:11]
	v_mfma_f32_16x16x32_bf16 v[52:55], v[164:167], v[192:195], v[52:55]
	v_mfma_f32_16x16x32_bf16 v[48:51], v[172:175], v[192:195], v[48:51]
	v_mfma_f32_16x16x32_bf16 v[36:39], v[164:167], v[200:203], v[36:39]
	v_mfma_f32_16x16x32_bf16 v[32:35], v[172:175], v[200:203], v[32:35]
	v_mfma_f32_16x16x32_bf16 v[20:23], v[164:167], v[208:211], v[20:23]
	v_mfma_f32_16x16x32_bf16 v[16:19], v[172:175], v[208:211], v[16:19]
	v_mfma_f32_16x16x32_bf16 v[4:7], v[164:167], v[216:219], v[4:7]
	v_mfma_f32_16x16x32_bf16 v[0:3], v[172:175], v[216:219], v[0:3]
	v_mfma_f32_16x16x32_bf16 v[52:55], v[168:171], v[196:199], v[52:55]
	v_mfma_f32_16x16x32_bf16 v[48:51], v[188:191], v[196:199], v[48:51]
	v_mfma_f32_16x16x32_bf16 v[36:39], v[168:171], v[204:207], v[36:39]
	v_mfma_f32_16x16x32_bf16 v[32:35], v[188:191], v[204:207], v[32:35]
	v_mfma_f32_16x16x32_bf16 v[20:23], v[168:171], v[212:215], v[20:23]
	v_mfma_f32_16x16x32_bf16 v[16:19], v[188:191], v[212:215], v[16:19]
	v_mfma_f32_16x16x32_bf16 v[4:7], v[168:171], v[220:223], v[4:7]
	v_mfma_f32_16x16x32_bf16 v[0:3], v[188:191], v[220:223], v[0:3]
	s_setprio 0
	s_barrier
	s_add_i32 s64, s64, 2
	s_add_u32 s28, s28, 0x100
	s_addc_u32 s29, s29, 0
	s_add_u32 s62, s62, 0x100
	s_addc_u32 s63, s63, 0
	s_cmp_gt_u32 s64, 13
	s_cbranch_scc0 .LBB0_1722
	s_and_b64 vcc, exec, s[16:17]
	s_cbranch_vccz .LBB0_1725
	s_barrier

; #define PG8_STAGE(bufoff, gbase, voff) do { _Pragma("unroll") for (int _i = 0; _i < 2; ++_i) \
;         __builtin_amdgcn_global_load_lds((const unsigned*)((const char*)(gbase) + (voff)[_i]), (LAS unsigned*)(lds + (bufoff) + ldsw + _i * 8192), 16, 0, 0); } while (0)
; #define PG8_LDA(dst, b, h) do { _Pragma("unroll") for (int m = 0; m < 4; ++m) _Pragma("unroll") for (int k = 0; k < 2; ++k) dst[m][k] = *(const LAS bf16x8*)(lds + PG8_SA(b, h) + aoff + m * 2048 + k * 1024); } while (0)
; #define PG8_LDB(dst, b, h) do { _Pragma("unroll") for (int n = 0; n < 2; ++n) _Pragma("unroll") for (int k = 0; k < 2; ++k) dst[n][k] = *(const LAS bf16x8*)(lds + PG8_SB(b, h) + boff + n * 2048 + k * 1024); } while (0)
; #define PG8_MMA(ai, bj, At, Bt) do { __builtin_amdgcn_s_setprio(1); _Pragma("unroll") for (int m = 0; m < 4; ++m) _Pragma("unroll") for (int n = 0; n < 2; ++n) _Pragma("unroll") for (int k = 0; k < 2; ++k) \
;         acc[ai][bj][m][n] = __builtin_amdgcn_mfma_f32_16x16x32_bf16(Bt[n][k], At[m][k], acc[ai][bj][m][n], 0, 0, 0); __builtin_amdgcn_s_setprio(0); } while (0)
; #define PG8_WAIT_V(n) asm volatile("s_waitcnt vmcnt(" #n ")" ::: "memory")
; #define PG8_WAIT_L(n) asm volatile("s_waitcnt lgkmcnt(" #n ")" ::: "memory")
; #define PG8_BAR __builtin_amdgcn_s_barrier()
; #define PG8_SCHED __builtin_amdgcn_sched_barrier(0)
; template <class Epi>
; __device__ __forceinline__ void gemm_phase(LAS unsigned char* lds, const Gemm g, const StaticOrder& S, const Epi& E) {
;     ...
;         for (int t = 0; t < nt; t += 2) {
;             const bool last = (t == nt - 2);
;             const char* a1 = cA + (size_t)(t + 1) * kstep;
;             const char* a2 = last ? nA : cA + (size_t)(t + 2) * kstep; const char* b2 = last ? nB : cB + (size_t)(t + 2) * kstep;
;             const char* a3 = a2 + kstep; const char* b3 = b2 + kstep;
;             PG8_LDB(B0, 0, 0); PG8_LDB(B1, 0, 1); PG8_SCHED; PG8_LDA(At, 0, 0); PG8_STAGE(PG8_SA(1, 1), a1 + hstepA, voffA);
;             PG8_WAIT_V(8); PG8_WAIT_L(0); PG8_BAR; PG8_MMA(0, 0, At, B0); PG8_MMA(0, 1, At, B1); PG8_BAR; PG8_SCHED;
;             PG8_LDA(At, 0, 1); PG8_STAGE(PG8_SB(0, 0), b2, voffB); PG8_STAGE(PG8_SB(0, 1), b2 + hstepB, voffB); PG8_STAGE(PG8_SA(0, 0), a2, voffA);
;             PG8_WAIT_V(8); PG8_WAIT_L(0); PG8_BAR; PG8_MMA(1, 0, At, B0); PG8_MMA(1, 1, At, B1); PG8_BAR; PG8_SCHED;
.LBB0_1814:
	ds_read_b128 v[64:67], v228
	ds_read_b128 v[68:71], v228 offset:1024
	ds_read_b128 v[72:75], v228 offset:2048
	ds_read_b128 v[76:79], v228 offset:3072
	ds_read_b128 v[80:83], v229
	ds_read_b128 v[84:87], v229 offset:1024
	ds_read_b128 v[88:91], v229 offset:2048
	ds_read_b128 v[92:95], v229 offset:3072
	s_add_u32 s60, s58, 0x100
	s_addc_u32 s61, s59, 0
	s_cmp_eq_u32 s85, 40
	s_cselect_b32 s65, s1, s61
	s_cselect_b32 s64, s0, s60
	s_cselect_b32 s63, s57, s84
	s_cselect_b32 s62, s56, s83
	v_lshl_add_u64 v[174:175], s[58:59], 0, v[166:167]
	s_add_i32 m0, s67, 0xc000
	ds_read_b128 v[182:185], v230
	ds_read_b128 v[186:189], v230 offset:1024
	ds_read_b128 v[190:193], v230 offset:2048
	ds_read_b128 v[194:197], v230 offset:3072
	ds_read_b128 v[198:201], v230 offset:4096
	ds_read_b128 v[202:205], v230 offset:5120
	ds_read_b128 v[206:209], v230 offset:6144
	ds_read_b128 v[210:213], v230 offset:7168
	global_load_lds_dwordx4 v[174:175], off
	v_lshl_add_u64 v[174:175], s[58:59], 0, v[168:169]
	s_add_i32 m0, s67, 0xe000
	s_nop 0
	global_load_lds_dwordx4 v[174:175], off
	s_waitcnt vmcnt(8)
	s_waitcnt lgkmcnt(0)
	s_barrier
	s_setprio 1
	s_waitcnt lgkmcnt(0)
	v_mfma_f32_16x16x32_bf16 v[156:159], v[64:67], v[182:185], v[156:159]
	v_mfma_f32_16x16x32_bf16 v[152:155], v[72:75], v[182:185], v[152:155]
	v_mfma_f32_16x16x32_bf16 v[140:143], v[64:67], v[190:193], v[140:143]
	v_mfma_f32_16x16x32_bf16 v[136:139], v[72:75], v[190:193], v[136:139]
	v_mfma_f32_16x16x32_bf16 v[124:127], v[64:67], v[198:201], v[124:127]
	v_mfma_f32_16x16x32_bf16 v[120:123], v[72:75], v[198:201], v[120:123]
	v_mfma_f32_16x16x32_bf16 v[108:111], v[64:67], v[206:209], v[108:111]
	v_mfma_f32_16x16x32_bf16 v[104:107], v[72:75], v[206:209], v[104:107]
	v_mfma_f32_16x16x32_bf16 v[156:159], v[68:71], v[186:189], v[156:159]
	v_mfma_f32_16x16x32_bf16 v[152:155], v[76:79], v[186:189], v[152:155]
	v_mfma_f32_16x16x32_bf16 v[140:143], v[68:71], v[194:197], v[140:143]
	v_mfma_f32_16x16x32_bf16 v[136:139], v[76:79], v[194:197], v[136:139]
	v_mfma_f32_16x16x32_bf16 v[124:127], v[68:71], v[202:205], v[124:127]
	v_mfma_f32_16x16x32_bf16 v[120:123], v[76:79], v[202:205], v[120:123]
	v_mfma_f32_16x16x32_bf16 v[108:111], v[68:71], v[210:213], v[108:111]
	v_mfma_f32_16x16x32_bf16 v[104:107], v[76:79], v[210:213], v[104:107]
	v_mfma_f32_16x16x32_bf16 v[148:151], v[80:83], v[182:185], v[148:151]
	v_mfma_f32_16x16x32_bf16 v[144:147], v[88:91], v[182:185], v[144:147]
	v_mfma_f32_16x16x32_bf16 v[132:135], v[80:83], v[190:193], v[132:135]
	v_mfma_f32_16x16x32_bf16 v[128:131], v[88:91], v[190:193], v[128:131]
	v_mfma_f32_16x16x32_bf16 v[116:119], v[80:83], v[198:201], v[116:119]
	v_mfma_f32_16x16x32_bf16 v[112:115], v[88:91], v[198:201], v[112:115]
	v_mfma_f32_16x16x32_bf16 v[100:103], v[80:83], v[206:209], v[100:103]
	v_mfma_f32_16x16x32_bf16 v[96:99], v[88:91], v[206:209], v[96:99]
	v_mfma_f32_16x16x32_bf16 v[148:151], v[84:87], v[186:189], v[148:151]
	v_mfma_f32_16x16x32_bf16 v[144:147], v[92:95], v[186:189], v[144:147]
	v_mfma_f32_16x16x32_bf16 v[132:135], v[84:87], v[194:197], v[132:135]
	v_mfma_f32_16x16x32_bf16 v[128:131], v[92:95], v[194:197], v[128:131]
	v_mfma_f32_16x16x32_bf16 v[116:119], v[84:87], v[202:205], v[116:119]
	v_mfma_f32_16x16x32_bf16 v[112:115], v[92:95], v[202:205], v[112:115]
	v_mfma_f32_16x16x32_bf16 v[100:103], v[84:87], v[210:213], v[100:103]
	v_mfma_f32_16x16x32_bf16 v[96:99], v[92:95], v[210:213], v[96:99]
	s_setprio 0
	s_barrier
	s_add_i32 s58, s77, s33
	v_lshl_add_u64 v[174:175], s[62:63], 0, v[160:161]
	s_mov_b32 m0, s58
	ds_read_b128 v[182:185], v230 offset:16384
	ds_read_b128 v[186:189], v230 offset:17408
	ds_read_b128 v[190:193], v230 offset:18432
	ds_read_b128 v[194:197], v230 offset:19456
	ds_read_b128 v[198:201], v230 offset:20480
	ds_read_b128 v[202:205], v230 offset:21504
	ds_read_b128 v[206:209], v230 offset:22528
	ds_read_b128 v[210:213], v230 offset:23552
	global_load_lds_dwordx4 v[174:175], off
	s_add_i32 m0, s58, 0x2000
	s_add_u32 s58, s62, 0xb0000
	v_lshl_add_u64 v[178:179], s[62:63], 0, v[162:163]
	s_addc_u32 s59, s63, 0
	s_add_i32 s86, s78, s33
	global_load_lds_dwordx4 v[178:179], off
	v_lshl_add_u64 v[214:215], s[58:59], 0, v[160:161]
	s_mov_b32 m0, s86
	v_lshl_add_u64 v[216:217], s[64:65], 0, v[162:163]
	global_load_lds_dwordx4 v[214:215], off
	v_lshl_add_u64 v[214:215], s[58:59], 0, v[162:163]
	s_add_i32 m0, s86, 0x2000
	s_nop 0
	global_load_lds_dwordx4 v[214:215], off
	v_lshl_add_u64 v[214:215], s[64:65], 0, v[160:161]
	s_mov_b32 m0, s67
	s_nop 0
	global_load_lds_dwordx4 v[214:215], off
	s_mov_b32 m0, s68
	s_nop 0
	global_load_lds_dwordx4 v[216:217], off
	s_waitcnt vmcnt(8)
	s_waitcnt lgkmcnt(0)
	s_barrier
; #define PG8_STAGE(bufoff, gbase, voff) do { _Pragma("unroll") for (int _i = 0; _i < 2; ++_i) \
;         __builtin_amdgcn_global_load_lds((const unsigned*)((const char*)(gbase) + (voff)[_i]), (LAS unsigned*)(lds + (bufoff) + ldsw + _i * 8192), 16, 0, 0); } while (0)
; #define PG8_LDA(dst, b, h) do { _Pragma("unroll") for (int m = 0; m < 4; ++m) _Pragma("unroll") for (int k = 0; k < 2; ++k) dst[m][k] = *(const LAS bf16x8*)(lds + PG8_SA(b, h) + aoff + m * 2048 + k * 1024); } while (0)
; #define PG8_LDB(dst, b, h) do { _Pragma("unroll") for (int n = 0; n < 2; ++n) _Pragma("unroll") for (int k = 0; k < 2; ++k) dst[n][k] = *(const LAS bf16x8*)(lds + PG8_SB(b, h) + boff + n * 2048 + k * 1024); } while (0)
; #define PG8_MMA(ai, bj, At, Bt) do { __builtin_amdgcn_s_setprio(1); _Pragma("unroll") for (int m = 0; m < 4; ++m) _Pragma("unroll") for (int n = 0; n < 2; ++n) _Pragma("unroll") for (int k = 0; k < 2; ++k) \
;         acc[ai][bj][m][n] = __builtin_amdgcn_mfma_f32_16x16x32_bf16(Bt[n][k], At[m][k], acc[ai][bj][m][n], 0, 0, 0); __builtin_amdgcn_s_setprio(0); } while (0)
; #define PG8_WAIT_V(n) asm volatile("s_waitcnt vmcnt(" #n ")" ::: "memory")
; #define PG8_WAIT_L(n) asm volatile("s_waitcnt lgkmcnt(" #n ")" ::: "memory")
; #define PG8_BAR __builtin_amdgcn_s_barrier()
; #define PG8_SCHED __builtin_amdgcn_sched_barrier(0)
; template <class Epi>
; __device__ __forceinline__ void gemm_phase(LAS unsigned char* lds, const Gemm g, const StaticOrder& S, const Epi& E) {
;     ...
;             PG8_WAIT_V(8); PG8_WAIT_L(0); PG8_BAR; PG8_MMA(1, 0, At, B0); PG8_MMA(1, 1, At, B1); PG8_BAR; PG8_SCHED;
;             PG8_LDB(B0, 1, 0); PG8_LDB(B1, 1, 1); PG8_SCHED; PG8_LDA(At, 1, 0); PG8_STAGE(PG8_SA(0, 1), a2 + hstepA, voffA);
;             PG8_WAIT_V(8); PG8_WAIT_L(0); PG8_BAR; PG8_MMA(0, 0, At, B0); PG8_MMA(0, 1, At, B1); PG8_BAR; PG8_SCHED;
	s_setprio 1
	s_waitcnt lgkmcnt(0)
	v_mfma_f32_16x16x32_bf16 v[60:63], v[64:67], v[182:185], v[60:63]
	v_mfma_f32_16x16x32_bf16 v[56:59], v[72:75], v[182:185], v[56:59]
	v_mfma_f32_16x16x32_bf16 v[44:47], v[64:67], v[190:193], v[44:47]
	v_mfma_f32_16x16x32_bf16 v[40:43], v[72:75], v[190:193], v[40:43]
	v_mfma_f32_16x16x32_bf16 v[28:31], v[64:67], v[198:201], v[28:31]
	v_mfma_f32_16x16x32_bf16 v[24:27], v[72:75], v[198:201], v[24:27]
	v_mfma_f32_16x16x32_bf16 v[12:15], v[64:67], v[206:209], v[12:15]
	v_mfma_f32_16x16x32_bf16 v[8:11], v[72:75], v[206:209], v[8:11]
	v_mfma_f32_16x16x32_bf16 v[60:63], v[68:71], v[186:189], v[60:63]
	v_mfma_f32_16x16x32_bf16 v[56:59], v[76:79], v[186:189], v[56:59]
	v_mfma_f32_16x16x32_bf16 v[44:47], v[68:71], v[194:197], v[44:47]
	v_mfma_f32_16x16x32_bf16 v[40:43], v[76:79], v[194:197], v[40:43]
	v_mfma_f32_16x16x32_bf16 v[28:31], v[68:71], v[202:205], v[28:31]
	v_mfma_f32_16x16x32_bf16 v[24:27], v[76:79], v[202:205], v[24:27]
	v_mfma_f32_16x16x32_bf16 v[12:15], v[68:71], v[210:213], v[12:15]
	v_mfma_f32_16x16x32_bf16 v[8:11], v[76:79], v[210:213], v[8:11]
	v_mfma_f32_16x16x32_bf16 v[52:55], v[80:83], v[182:185], v[52:55]
	v_mfma_f32_16x16x32_bf16 v[48:51], v[88:91], v[182:185], v[48:51]
	v_mfma_f32_16x16x32_bf16 v[36:39], v[80:83], v[190:193], v[36:39]
	v_mfma_f32_16x16x32_bf16 v[32:35], v[88:91], v[190:193], v[32:35]
	v_mfma_f32_16x16x32_bf16 v[20:23], v[80:83], v[198:201], v[20:23]
	v_mfma_f32_16x16x32_bf16 v[16:19], v[88:91], v[198:201], v[16:19]
	v_mfma_f32_16x16x32_bf16 v[4:7], v[80:83], v[206:209], v[4:7]
	v_mfma_f32_16x16x32_bf16 v[0:3], v[88:91], v[206:209], v[0:3]
	v_mfma_f32_16x16x32_bf16 v[52:55], v[84:87], v[186:189], v[52:55]
	v_mfma_f32_16x16x32_bf16 v[48:51], v[92:95], v[186:189], v[48:51]
	v_mfma_f32_16x16x32_bf16 v[36:39], v[84:87], v[194:197], v[36:39]
	v_mfma_f32_16x16x32_bf16 v[32:35], v[92:95], v[194:197], v[32:35]
	v_mfma_f32_16x16x32_bf16 v[20:23], v[84:87], v[202:205], v[20:23]
	v_mfma_f32_16x16x32_bf16 v[16:19], v[92:95], v[202:205], v[16:19]
	v_mfma_f32_16x16x32_bf16 v[4:7], v[84:87], v[210:213], v[4:7]
	v_mfma_f32_16x16x32_bf16 v[0:3], v[92:95], v[210:213], v[0:3]
	s_setprio 0
	s_barrier
	s_add_i32 s86, 0, 0x18000
	s_add_i32 s87, 0, 0x1c000
	v_add_u32_e32 v76, s86, v226
	v_add_u32_e32 v92, s87, v226
	ds_read_b128 v[64:67], v76
	ds_read_b128 v[68:71], v76 offset:1024
	ds_read_b128 v[72:75], v76 offset:2048
	ds_read_b128 v[76:79], v76 offset:3072
	ds_read_b128 v[80:83], v92
	ds_read_b128 v[84:87], v92 offset:1024
	ds_read_b128 v[88:91], v92 offset:2048
	ds_read_b128 v[92:95], v92 offset:3072
	s_add_u32 s58, s64, 0xb0000
	s_addc_u32 s59, s65, 0
	s_mov_b32 m0, s69
	v_lshl_add_u64 v[218:219], s[58:59], 0, v[160:161]
	ds_read_b128 v[182:185], v230 offset:32768
	ds_read_b128 v[186:189], v230 offset:33792
	ds_read_b128 v[190:193], v230 offset:34816
	ds_read_b128 v[194:197], v230 offset:35840
	ds_read_b128 v[198:201], v230 offset:36864
	ds_read_b128 v[202:205], v230 offset:37888
	ds_read_b128 v[206:209], v230 offset:38912
	ds_read_b128 v[210:213], v230 offset:39936
	global_load_lds_dwordx4 v[218:219], off
	v_lshl_add_u64 v[218:219], s[58:59], 0, v[162:163]
	s_mov_b32 m0, s70
	s_nop 0
	global_load_lds_dwordx4 v[218:219], off
	s_waitcnt vmcnt(8)
	s_waitcnt lgkmcnt(0)
	s_barrier
	s_setprio 1
	s_waitcnt lgkmcnt(0)
	v_mfma_f32_16x16x32_bf16 v[156:159], v[64:67], v[182:185], v[156:159]
	v_mfma_f32_16x16x32_bf16 v[152:155], v[72:75], v[182:185], v[152:155]
	v_mfma_f32_16x16x32_bf16 v[140:143], v[64:67], v[190:193], v[140:143]
	v_mfma_f32_16x16x32_bf16 v[136:139], v[72:75], v[190:193], v[136:139]
	v_mfma_f32_16x16x32_bf16 v[124:127], v[64:67], v[198:201], v[124:127]
	v_mfma_f32_16x16x32_bf16 v[120:123], v[72:75], v[198:201], v[120:123]
	v_mfma_f32_16x16x32_bf16 v[108:111], v[64:67], v[206:209], v[108:111]
	v_mfma_f32_16x16x32_bf16 v[104:107], v[72:75], v[206:209], v[104:107]
	v_mfma_f32_16x16x32_bf16 v[156:159], v[68:71], v[186:189], v[156:159]
	v_mfma_f32_16x16x32_bf16 v[152:155], v[76:79], v[186:189], v[152:155]
	v_mfma_f32_16x16x32_bf16 v[140:143], v[68:71], v[194:197], v[140:143]
	v_mfma_f32_16x16x32_bf16 v[136:139], v[76:79], v[194:197], v[136:139]
	v_mfma_f32_16x16x32_bf16 v[124:127], v[68:71], v[202:205], v[124:127]
	v_mfma_f32_16x16x32_bf16 v[120:123], v[76:79], v[202:205], v[120:123]
	v_mfma_f32_16x16x32_bf16 v[108:111], v[68:71], v[210:213], v[108:111]
	v_mfma_f32_16x16x32_bf16 v[104:107], v[76:79], v[210:213], v[104:107]
	v_mfma_f32_16x16x32_bf16 v[148:151], v[80:83], v[182:185], v[148:151]
	v_mfma_f32_16x16x32_bf16 v[144:147], v[88:91], v[182:185], v[144:147]
	v_mfma_f32_16x16x32_bf16 v[132:135], v[80:83], v[190:193], v[132:135]
	v_mfma_f32_16x16x32_bf16 v[128:131], v[88:91], v[190:193], v[128:131]
	v_mfma_f32_16x16x32_bf16 v[116:119], v[80:83], v[198:201], v[116:119]
	v_mfma_f32_16x16x32_bf16 v[112:115], v[88:91], v[198:201], v[112:115]
	v_mfma_f32_16x16x32_bf16 v[100:103], v[80:83], v[206:209], v[100:103]
	v_mfma_f32_16x16x32_bf16 v[96:99], v[88:91], v[206:209], v[96:99]
	v_mfma_f32_16x16x32_bf16 v[148:151], v[84:87], v[186:189], v[148:151]
	v_mfma_f32_16x16x32_bf16 v[144:147], v[92:95], v[186:189], v[144:147]
	v_mfma_f32_16x16x32_bf16 v[132:135], v[84:87], v[194:197], v[132:135]
	v_mfma_f32_16x16x32_bf16 v[128:131], v[92:95], v[194:197], v[128:131]
	v_mfma_f32_16x16x32_bf16 v[116:119], v[84:87], v[202:205], v[116:119]
	v_mfma_f32_16x16x32_bf16 v[112:115], v[92:95], v[202:205], v[112:115]
	v_mfma_f32_16x16x32_bf16 v[100:103], v[84:87], v[210:213], v[100:103]
	v_mfma_f32_16x16x32_bf16 v[96:99], v[92:95], v[210:213], v[96:99]
	s_setprio 0
	s_barrier
; #define PG8_STAGE(bufoff, gbase, voff) do { _Pragma("unroll") for (int _i = 0; _i < 2; ++_i) \
;         __builtin_amdgcn_global_load_lds((const unsigned*)((const char*)(gbase) + (voff)[_i]), (LAS unsigned*)(lds + (bufoff) + ldsw + _i * 8192), 16, 0, 0); } while (0)
; #define PG8_LDA(dst, b, h) do { _Pragma("unroll") for (int m = 0; m < 4; ++m) _Pragma("unroll") for (int k = 0; k < 2; ++k) dst[m][k] = *(const LAS bf16x8*)(lds + PG8_SA(b, h) + aoff + m * 2048 + k * 1024); } while (0)
; #define PG8_MMA(ai, bj, At, Bt) do { __builtin_amdgcn_s_setprio(1); _Pragma("unroll") for (int m = 0; m < 4; ++m) _Pragma("unroll") for (int n = 0; n < 2; ++n) _Pragma("unroll") for (int k = 0; k < 2; ++k) \
;         acc[ai][bj][m][n] = __builtin_amdgcn_mfma_f32_16x16x32_bf16(Bt[n][k], At[m][k], acc[ai][bj][m][n], 0, 0, 0); __builtin_amdgcn_s_setprio(0); } while (0)
; #define PG8_WAIT_V(n) asm volatile("s_waitcnt vmcnt(" #n ")" ::: "memory")
; #define PG8_WAIT_L(n) asm volatile("s_waitcnt lgkmcnt(" #n ")" ::: "memory")
; #define PG8_BAR __builtin_amdgcn_s_barrier()
; #define PG8_SCHED __builtin_amdgcn_sched_barrier(0)
; template <class Epi>
; __device__ __forceinline__ void gemm_phase(LAS unsigned char* lds, const Gemm g, const StaticOrder& S, const Epi& E) {
;     ...
;             PG8_LDA(At, 1, 1); PG8_STAGE(PG8_SB(1, 0), b3, voffB); PG8_STAGE(PG8_SB(1, 1), b3 + hstepB, voffB); PG8_STAGE(PG8_SA(1, 0), a3, voffA);
;             PG8_WAIT_V(8); PG8_WAIT_L(0); PG8_BAR; PG8_MMA(1, 0, At, B0); PG8_MMA(1, 1, At, B1); PG8_BAR; PG8_SCHED;
;         }
;         if (wr == 0) PG8_BAR;
	s_add_i32 s58, s86, s33
	v_lshl_add_u64 v[174:175], v[174:175], 0, s[22:23]
	s_mov_b32 m0, s58
	ds_read_b128 v[182:185], v230 offset:49152
	ds_read_b128 v[186:189], v230 offset:50176
	ds_read_b128 v[190:193], v230 offset:51200
	ds_read_b128 v[194:197], v230 offset:52224
	ds_read_b128 v[198:201], v230 offset:53248
	ds_read_b128 v[202:205], v230 offset:54272
	ds_read_b128 v[206:209], v230 offset:55296
	ds_read_b128 v[210:213], v230 offset:56320
	global_load_lds_dwordx4 v[174:175], off
	s_add_i32 m0, s58, 0x2000
	s_add_u32 s58, s62, 0xb0080
	v_lshl_add_u64 v[174:175], v[178:179], 0, s[22:23]
	s_addc_u32 s59, s63, 0
	s_add_i32 s62, s87, s33
	global_load_lds_dwordx4 v[174:175], off
	v_lshl_add_u64 v[174:175], s[58:59], 0, v[160:161]
	s_mov_b32 m0, s62
	s_nop 0
	global_load_lds_dwordx4 v[174:175], off
	v_lshl_add_u64 v[174:175], s[58:59], 0, v[162:163]
	s_add_i32 m0, s62, 0x2000
	s_nop 0
	global_load_lds_dwordx4 v[174:175], off
	v_lshl_add_u64 v[174:175], v[214:215], 0, s[22:23]
	s_mov_b32 m0, s72
	s_nop 0
	global_load_lds_dwordx4 v[174:175], off
	v_lshl_add_u64 v[174:175], v[216:217], 0, s[22:23]
	s_mov_b32 m0, s73
	s_nop 0
	global_load_lds_dwordx4 v[174:175], off
	s_waitcnt vmcnt(8)
	s_waitcnt lgkmcnt(0)
	s_barrier
	s_setprio 1
	s_waitcnt lgkmcnt(0)
	v_mfma_f32_16x16x32_bf16 v[60:63], v[64:67], v[182:185], v[60:63]
	v_mfma_f32_16x16x32_bf16 v[56:59], v[72:75], v[182:185], v[56:59]
	v_mfma_f32_16x16x32_bf16 v[44:47], v[64:67], v[190:193], v[44:47]
	v_mfma_f32_16x16x32_bf16 v[40:43], v[72:75], v[190:193], v[40:43]
	v_mfma_f32_16x16x32_bf16 v[28:31], v[64:67], v[198:201], v[28:31]
	v_mfma_f32_16x16x32_bf16 v[24:27], v[72:75], v[198:201], v[24:27]
	v_mfma_f32_16x16x32_bf16 v[12:15], v[64:67], v[206:209], v[12:15]
	v_mfma_f32_16x16x32_bf16 v[8:11], v[72:75], v[206:209], v[8:11]
	v_mfma_f32_16x16x32_bf16 v[60:63], v[68:71], v[186:189], v[60:63]
	v_mfma_f32_16x16x32_bf16 v[56:59], v[76:79], v[186:189], v[56:59]
	v_mfma_f32_16x16x32_bf16 v[44:47], v[68:71], v[194:197], v[44:47]
	v_mfma_f32_16x16x32_bf16 v[40:43], v[76:79], v[194:197], v[40:43]
	v_mfma_f32_16x16x32_bf16 v[28:31], v[68:71], v[202:205], v[28:31]
	v_mfma_f32_16x16x32_bf16 v[24:27], v[76:79], v[202:205], v[24:27]
	v_mfma_f32_16x16x32_bf16 v[12:15], v[68:71], v[210:213], v[12:15]
	v_mfma_f32_16x16x32_bf16 v[8:11], v[76:79], v[210:213], v[8:11]
	v_mfma_f32_16x16x32_bf16 v[52:55], v[80:83], v[182:185], v[52:55]
	v_mfma_f32_16x16x32_bf16 v[48:51], v[88:91], v[182:185], v[48:51]
	v_mfma_f32_16x16x32_bf16 v[36:39], v[80:83], v[190:193], v[36:39]
	v_mfma_f32_16x16x32_bf16 v[32:35], v[88:91], v[190:193], v[32:35]
	v_mfma_f32_16x16x32_bf16 v[20:23], v[80:83], v[198:201], v[20:23]
	v_mfma_f32_16x16x32_bf16 v[16:19], v[88:91], v[198:201], v[16:19]
	v_mfma_f32_16x16x32_bf16 v[4:7], v[80:83], v[206:209], v[4:7]
	v_mfma_f32_16x16x32_bf16 v[0:3], v[88:91], v[206:209], v[0:3]
	v_mfma_f32_16x16x32_bf16 v[52:55], v[84:87], v[186:189], v[52:55]
	v_mfma_f32_16x16x32_bf16 v[48:51], v[92:95], v[186:189], v[48:51]
	v_mfma_f32_16x16x32_bf16 v[36:39], v[84:87], v[194:197], v[36:39]
	v_mfma_f32_16x16x32_bf16 v[32:35], v[92:95], v[194:197], v[32:35]
	v_mfma_f32_16x16x32_bf16 v[20:23], v[84:87], v[202:205], v[20:23]
	v_mfma_f32_16x16x32_bf16 v[16:19], v[92:95], v[202:205], v[16:19]
	v_mfma_f32_16x16x32_bf16 v[4:7], v[84:87], v[210:213], v[4:7]
	v_mfma_f32_16x16x32_bf16 v[0:3], v[92:95], v[210:213], v[0:3]
	s_setprio 0
	s_barrier
	s_add_i32 s85, s85, 2
	s_add_u32 s83, s83, 0x100
	s_addc_u32 s84, s84, 0
	s_cmp_gt_u32 s85, 41
	s_mov_b64 s[58:59], s[60:61]
	s_cbranch_scc0 .LBB0_1814
	s_and_b64 vcc, exec, s[26:27]
	s_cbranch_vccz .LBB0_1817
	s_barrier
